# K-loop hand-offs: s_setprio moved off the last-MFMA->barrier and barrier->first-MFMA paths, duplicate lgkmcnt wait dropped
# speedup vs baseline: 1.0086x; 1.0027x over previous
.Lpk607_j1:
	s_waitcnt lgkmcnt(0)
	s_setprio 1
	s_barrier
	v_mfma_f32_16x16x32_bf16 v[124:127], v[154:157], v[186:189], 0
	v_mfma_f32_16x16x32_bf16 v[116:119], v[162:165], v[186:189], 0
	v_mfma_f32_16x16x32_bf16 v[108:111], v[154:157], v[194:197], 0
	v_mfma_f32_16x16x32_bf16 v[100:103], v[162:165], v[194:197], 0
	v_mfma_f32_16x16x32_bf16 v[92:95], v[154:157], v[202:205], 0
	v_mfma_f32_16x16x32_bf16 v[84:87], v[162:165], v[202:205], 0
	v_mfma_f32_16x16x32_bf16 v[76:79], v[154:157], v[210:213], 0
	v_mfma_f32_16x16x32_bf16 v[68:71], v[162:165], v[210:213], 0
	v_mfma_f32_16x16x32_bf16 v[124:127], v[158:161], v[190:193], v[124:127]
	v_mfma_f32_16x16x32_bf16 v[116:119], v[166:169], v[190:193], v[116:119]
	v_mfma_f32_16x16x32_bf16 v[108:111], v[158:161], v[198:201], v[108:111]
	v_mfma_f32_16x16x32_bf16 v[100:103], v[166:169], v[198:201], v[100:103]
	v_mfma_f32_16x16x32_bf16 v[92:95], v[158:161], v[206:209], v[92:95]
	v_mfma_f32_16x16x32_bf16 v[84:87], v[166:169], v[206:209], v[84:87]
	v_mfma_f32_16x16x32_bf16 v[76:79], v[158:161], v[214:217], v[76:79]
	v_mfma_f32_16x16x32_bf16 v[68:71], v[166:169], v[214:217], v[68:71]
	s_setprio 0
	s_setprio 1
	v_mfma_f32_16x16x32_bf16 v[120:123], v[170:173], v[186:189], 0
	v_mfma_f32_16x16x32_bf16 v[112:115], v[178:181], v[186:189], 0
	v_mfma_f32_16x16x32_bf16 v[104:107], v[170:173], v[194:197], 0
	v_mfma_f32_16x16x32_bf16 v[96:99], v[178:181], v[194:197], 0
	v_mfma_f32_16x16x32_bf16 v[88:91], v[170:173], v[202:205], 0
	v_mfma_f32_16x16x32_bf16 v[80:83], v[178:181], v[202:205], 0
	v_mfma_f32_16x16x32_bf16 v[72:75], v[170:173], v[210:213], 0
	v_mfma_f32_16x16x32_bf16 v[64:67], v[178:181], v[210:213], 0
	v_mfma_f32_16x16x32_bf16 v[120:123], v[174:177], v[190:193], v[120:123]
	v_mfma_f32_16x16x32_bf16 v[112:115], v[182:185], v[190:193], v[112:115]
	v_mfma_f32_16x16x32_bf16 v[104:107], v[174:177], v[198:201], v[104:107]
	v_mfma_f32_16x16x32_bf16 v[96:99], v[182:185], v[198:201], v[96:99]
	v_mfma_f32_16x16x32_bf16 v[88:91], v[174:177], v[206:209], v[88:91]
	v_mfma_f32_16x16x32_bf16 v[80:83], v[182:185], v[206:209], v[80:83]
	v_mfma_f32_16x16x32_bf16 v[72:75], v[174:177], v[214:217], v[72:75]
	v_mfma_f32_16x16x32_bf16 v[64:67], v[182:185], v[214:217], v[64:67]
	s_barrier
	s_setprio 0
	s_add_i32 s53, s40, s28
	v_lshl_add_u64 v[218:219], s[24:25], 0, v[132:133]
	s_mov_b32 m0, s53
	ds_read_b128 v[186:189], v150 offset:16384
	ds_read_b128 v[190:193], v150 offset:17408
	global_load_lds_dwordx4 v[218:219], off
	s_add_i32 m0, s53, 0x2000
	s_add_u32 s66, s24, 0x40000
	v_lshl_add_u64 v[220:221], s[24:25], 0, v[128:129]
	s_addc_u32 s67, s25, 0
	s_add_i32 s53, s41, s28
	ds_read_b128 v[194:197], v150 offset:18432
	ds_read_b128 v[198:201], v150 offset:19456
	global_load_lds_dwordx4 v[220:221], off
	v_lshl_add_u64 v[222:223], s[66:67], 0, v[132:133]
	s_mov_b32 m0, s53
	v_lshl_add_u64 v[224:225], s[26:27], 0, v[130:131]
	ds_read_b128 v[202:205], v150 offset:20480
	global_load_lds_dwordx4 v[222:223], off
	v_lshl_add_u64 v[222:223], s[66:67], 0, v[128:129]
	s_add_i32 m0, s53, 0x2000
	ds_read_b128 v[206:209], v150 offset:21504
	global_load_lds_dwordx4 v[222:223], off
	v_lshl_add_u64 v[222:223], s[26:27], 0, v[134:135]
	s_mov_b32 m0, s21
	ds_read_b128 v[210:213], v150 offset:22528
	global_load_lds_dwordx4 v[222:223], off
	s_mov_b32 m0, s35
	ds_read_b128 v[214:217], v150 offset:23552
	global_load_lds_dwordx4 v[224:225], off
	s_cmp_eq_u32 s101, 1
	s_cbranch_scc1 .Lpk607_r2
	s_waitcnt vmcnt(8)
	s_branch .Lpk607_j2

.Lpk607_j2:
	s_mov_b32 s101, 0
	s_waitcnt lgkmcnt(0)
	s_setprio 1
	s_barrier
	v_mfma_f32_16x16x32_bf16 v[60:63], v[154:157], v[186:189], 0
	v_mfma_f32_16x16x32_bf16 v[52:55], v[162:165], v[186:189], 0
	v_mfma_f32_16x16x32_bf16 v[44:47], v[154:157], v[194:197], 0
	v_mfma_f32_16x16x32_bf16 v[36:39], v[162:165], v[194:197], 0
	v_mfma_f32_16x16x32_bf16 v[28:31], v[154:157], v[202:205], 0
	v_mfma_f32_16x16x32_bf16 v[20:23], v[162:165], v[202:205], 0
	v_mfma_f32_16x16x32_bf16 v[12:15], v[154:157], v[210:213], 0
	v_mfma_f32_16x16x32_bf16 v[4:7], v[162:165], v[210:213], 0
	v_mfma_f32_16x16x32_bf16 v[60:63], v[158:161], v[190:193], v[60:63]
	v_mfma_f32_16x16x32_bf16 v[52:55], v[166:169], v[190:193], v[52:55]
	v_mfma_f32_16x16x32_bf16 v[44:47], v[158:161], v[198:201], v[44:47]
	v_mfma_f32_16x16x32_bf16 v[36:39], v[166:169], v[198:201], v[36:39]
	v_mfma_f32_16x16x32_bf16 v[28:31], v[158:161], v[206:209], v[28:31]
	v_mfma_f32_16x16x32_bf16 v[20:23], v[166:169], v[206:209], v[20:23]
	v_mfma_f32_16x16x32_bf16 v[12:15], v[158:161], v[214:217], v[12:15]
	v_mfma_f32_16x16x32_bf16 v[4:7], v[166:169], v[214:217], v[4:7]
	s_setprio 0
	s_setprio 1
	v_mfma_f32_16x16x32_bf16 v[56:59], v[170:173], v[186:189], 0
	v_mfma_f32_16x16x32_bf16 v[48:51], v[178:181], v[186:189], 0
	v_mfma_f32_16x16x32_bf16 v[40:43], v[170:173], v[194:197], 0
	v_mfma_f32_16x16x32_bf16 v[32:35], v[178:181], v[194:197], 0
	v_mfma_f32_16x16x32_bf16 v[24:27], v[170:173], v[202:205], 0
	v_mfma_f32_16x16x32_bf16 v[16:19], v[178:181], v[202:205], 0
	v_mfma_f32_16x16x32_bf16 v[8:11], v[170:173], v[210:213], 0
	v_mfma_f32_16x16x32_bf16 v[0:3], v[178:181], v[210:213], 0
	v_mfma_f32_16x16x32_bf16 v[56:59], v[174:177], v[190:193], v[56:59]
	v_mfma_f32_16x16x32_bf16 v[48:51], v[182:185], v[190:193], v[48:51]
	v_mfma_f32_16x16x32_bf16 v[40:43], v[174:177], v[198:201], v[40:43]
	v_mfma_f32_16x16x32_bf16 v[32:35], v[182:185], v[198:201], v[32:35]
	v_mfma_f32_16x16x32_bf16 v[24:27], v[174:177], v[206:209], v[24:27]
	v_mfma_f32_16x16x32_bf16 v[16:19], v[182:185], v[206:209], v[16:19]
	v_mfma_f32_16x16x32_bf16 v[8:11], v[174:177], v[214:217], v[8:11]
	v_mfma_f32_16x16x32_bf16 v[0:3], v[182:185], v[214:217], v[0:3]
	s_barrier
	s_setprio 0
	s_branch .Lpk607_seg3
.LBB0_607:
	ds_read_b128 v[154:157], v148
	ds_read_b128 v[158:161], v148 offset:1024
	ds_read_b128 v[162:165], v148 offset:2048
	ds_read_b128 v[166:169], v148 offset:3072
	ds_read_b128 v[170:173], v149
	ds_read_b128 v[174:177], v149 offset:1024
	ds_read_b128 v[178:181], v149 offset:2048
	ds_read_b128 v[182:185], v149 offset:3072
	s_add_u32 s24, s22, 0xfffc0080
	s_addc_u32 s25, s23, -1
	s_cmp_eq_u32 s52, 12
	s_cselect_b32 s27, s15, s25
	s_cselect_b32 s26, s48, s24
	s_cselect_b32 s25, s13, s51
	s_cselect_b32 s24, s49, s50
	v_lshl_add_u64 v[218:219], s[22:23], 0, v[136:137]
	s_add_i32 m0, s21, 0xc000
	ds_read_b128 v[186:189], v150
	ds_read_b128 v[190:193], v150 offset:1024
	ds_read_b128 v[194:197], v150 offset:2048
	ds_read_b128 v[198:201], v150 offset:3072
	ds_read_b128 v[202:205], v150 offset:4096
	ds_read_b128 v[206:209], v150 offset:5120
	ds_read_b128 v[210:213], v150 offset:6144
	ds_read_b128 v[214:217], v150 offset:7168
	global_load_lds_dwordx4 v[218:219], off
	v_lshl_add_u64 v[218:219], s[22:23], 0, v[138:139]
	s_add_i32 m0, s21, 0xe000
	s_nop 0
	global_load_lds_dwordx4 v[218:219], off
	s_waitcnt vmcnt(8)
	s_waitcnt lgkmcnt(0)
	s_setprio 1
	s_barrier
	v_mfma_f32_16x16x32_bf16 v[124:127], v[154:157], v[186:189], v[124:127]
	v_mfma_f32_16x16x32_bf16 v[116:119], v[162:165], v[186:189], v[116:119]
	v_mfma_f32_16x16x32_bf16 v[108:111], v[154:157], v[194:197], v[108:111]
	v_mfma_f32_16x16x32_bf16 v[100:103], v[162:165], v[194:197], v[100:103]
	v_mfma_f32_16x16x32_bf16 v[92:95], v[154:157], v[202:205], v[92:95]
	v_mfma_f32_16x16x32_bf16 v[84:87], v[162:165], v[202:205], v[84:87]
	v_mfma_f32_16x16x32_bf16 v[76:79], v[154:157], v[210:213], v[76:79]
	v_mfma_f32_16x16x32_bf16 v[68:71], v[162:165], v[210:213], v[68:71]
	v_mfma_f32_16x16x32_bf16 v[124:127], v[158:161], v[190:193], v[124:127]
	v_mfma_f32_16x16x32_bf16 v[116:119], v[166:169], v[190:193], v[116:119]
	v_mfma_f32_16x16x32_bf16 v[108:111], v[158:161], v[198:201], v[108:111]
	v_mfma_f32_16x16x32_bf16 v[100:103], v[166:169], v[198:201], v[100:103]
	v_mfma_f32_16x16x32_bf16 v[92:95], v[158:161], v[206:209], v[92:95]
	v_mfma_f32_16x16x32_bf16 v[84:87], v[166:169], v[206:209], v[84:87]
	v_mfma_f32_16x16x32_bf16 v[76:79], v[158:161], v[214:217], v[76:79]
	v_mfma_f32_16x16x32_bf16 v[68:71], v[166:169], v[214:217], v[68:71]
	s_setprio 0
	s_setprio 1
	v_mfma_f32_16x16x32_bf16 v[120:123], v[170:173], v[186:189], v[120:123]
	v_mfma_f32_16x16x32_bf16 v[112:115], v[178:181], v[186:189], v[112:115]
	v_mfma_f32_16x16x32_bf16 v[104:107], v[170:173], v[194:197], v[104:107]
	v_mfma_f32_16x16x32_bf16 v[96:99], v[178:181], v[194:197], v[96:99]
	v_mfma_f32_16x16x32_bf16 v[88:91], v[170:173], v[202:205], v[88:91]
	v_mfma_f32_16x16x32_bf16 v[80:83], v[178:181], v[202:205], v[80:83]
	v_mfma_f32_16x16x32_bf16 v[72:75], v[170:173], v[210:213], v[72:75]
	v_mfma_f32_16x16x32_bf16 v[64:67], v[178:181], v[210:213], v[64:67]
	v_mfma_f32_16x16x32_bf16 v[120:123], v[174:177], v[190:193], v[120:123]
	v_mfma_f32_16x16x32_bf16 v[112:115], v[182:185], v[190:193], v[112:115]
	v_mfma_f32_16x16x32_bf16 v[104:107], v[174:177], v[198:201], v[104:107]
	v_mfma_f32_16x16x32_bf16 v[96:99], v[182:185], v[198:201], v[96:99]
	v_mfma_f32_16x16x32_bf16 v[88:91], v[174:177], v[206:209], v[88:91]
	v_mfma_f32_16x16x32_bf16 v[80:83], v[182:185], v[206:209], v[80:83]
	v_mfma_f32_16x16x32_bf16 v[72:75], v[174:177], v[214:217], v[72:75]
	v_mfma_f32_16x16x32_bf16 v[64:67], v[182:185], v[214:217], v[64:67]
	s_barrier
	s_setprio 0
	s_add_i32 s53, s40, s28
	v_lshl_add_u64 v[218:219], s[24:25], 0, v[132:133]
	s_mov_b32 m0, s53
	ds_read_b128 v[186:189], v150 offset:16384
	ds_read_b128 v[190:193], v150 offset:17408
	global_load_lds_dwordx4 v[218:219], off
	s_add_i32 m0, s53, 0x2000
	s_add_u32 s66, s24, 0x40000
	v_lshl_add_u64 v[220:221], s[24:25], 0, v[128:129]
	s_addc_u32 s67, s25, 0
	s_add_i32 s53, s41, s28
	ds_read_b128 v[194:197], v150 offset:18432
	ds_read_b128 v[198:201], v150 offset:19456
	global_load_lds_dwordx4 v[220:221], off
	v_lshl_add_u64 v[222:223], s[66:67], 0, v[132:133]
	s_mov_b32 m0, s53
	v_lshl_add_u64 v[224:225], s[26:27], 0, v[130:131]
	ds_read_b128 v[202:205], v150 offset:20480
	global_load_lds_dwordx4 v[222:223], off
	v_lshl_add_u64 v[222:223], s[66:67], 0, v[128:129]
	s_add_i32 m0, s53, 0x2000
	ds_read_b128 v[206:209], v150 offset:21504
	global_load_lds_dwordx4 v[222:223], off
	v_lshl_add_u64 v[222:223], s[26:27], 0, v[134:135]
	s_mov_b32 m0, s21
	ds_read_b128 v[210:213], v150 offset:22528
	global_load_lds_dwordx4 v[222:223], off
	s_mov_b32 m0, s35
	ds_read_b128 v[214:217], v150 offset:23552
	global_load_lds_dwordx4 v[224:225], off
	s_waitcnt vmcnt(8)
	s_waitcnt lgkmcnt(0)
	s_setprio 1
	s_barrier
	v_mfma_f32_16x16x32_bf16 v[60:63], v[154:157], v[186:189], v[60:63]
	v_mfma_f32_16x16x32_bf16 v[52:55], v[162:165], v[186:189], v[52:55]
	v_mfma_f32_16x16x32_bf16 v[44:47], v[154:157], v[194:197], v[44:47]
	v_mfma_f32_16x16x32_bf16 v[36:39], v[162:165], v[194:197], v[36:39]
	v_mfma_f32_16x16x32_bf16 v[28:31], v[154:157], v[202:205], v[28:31]
	v_mfma_f32_16x16x32_bf16 v[20:23], v[162:165], v[202:205], v[20:23]
	v_mfma_f32_16x16x32_bf16 v[12:15], v[154:157], v[210:213], v[12:15]
	v_mfma_f32_16x16x32_bf16 v[4:7], v[162:165], v[210:213], v[4:7]
	v_mfma_f32_16x16x32_bf16 v[60:63], v[158:161], v[190:193], v[60:63]
	v_mfma_f32_16x16x32_bf16 v[52:55], v[166:169], v[190:193], v[52:55]
	v_mfma_f32_16x16x32_bf16 v[44:47], v[158:161], v[198:201], v[44:47]
	v_mfma_f32_16x16x32_bf16 v[36:39], v[166:169], v[198:201], v[36:39]
	v_mfma_f32_16x16x32_bf16 v[28:31], v[158:161], v[206:209], v[28:31]
	v_mfma_f32_16x16x32_bf16 v[20:23], v[166:169], v[206:209], v[20:23]
	v_mfma_f32_16x16x32_bf16 v[12:15], v[158:161], v[214:217], v[12:15]
	v_mfma_f32_16x16x32_bf16 v[4:7], v[166:169], v[214:217], v[4:7]
	s_setprio 0
	s_setprio 1
	v_mfma_f32_16x16x32_bf16 v[56:59], v[170:173], v[186:189], v[56:59]
	v_mfma_f32_16x16x32_bf16 v[48:51], v[178:181], v[186:189], v[48:51]
	v_mfma_f32_16x16x32_bf16 v[40:43], v[170:173], v[194:197], v[40:43]
	v_mfma_f32_16x16x32_bf16 v[32:35], v[178:181], v[194:197], v[32:35]
	v_mfma_f32_16x16x32_bf16 v[24:27], v[170:173], v[202:205], v[24:27]
	v_mfma_f32_16x16x32_bf16 v[16:19], v[178:181], v[202:205], v[16:19]
	v_mfma_f32_16x16x32_bf16 v[8:11], v[170:173], v[210:213], v[8:11]
	v_mfma_f32_16x16x32_bf16 v[0:3], v[178:181], v[210:213], v[0:3]
	v_mfma_f32_16x16x32_bf16 v[56:59], v[174:177], v[190:193], v[56:59]
	v_mfma_f32_16x16x32_bf16 v[48:51], v[182:185], v[190:193], v[48:51]
	v_mfma_f32_16x16x32_bf16 v[40:43], v[174:177], v[198:201], v[40:43]
	v_mfma_f32_16x16x32_bf16 v[32:35], v[182:185], v[198:201], v[32:35]
	v_mfma_f32_16x16x32_bf16 v[24:27], v[174:177], v[206:209], v[24:27]
	v_mfma_f32_16x16x32_bf16 v[16:19], v[182:185], v[206:209], v[16:19]
	v_mfma_f32_16x16x32_bf16 v[8:11], v[174:177], v[214:217], v[8:11]
	v_mfma_f32_16x16x32_bf16 v[0:3], v[182:185], v[214:217], v[0:3]
	s_barrier
	s_setprio 0
.Lpk607_seg3:
	s_add_i32 s53, 0, 0x18000
	v_add_u32_e32 v151, s53, v145
	s_add_i32 s54, 0, 0x1c000
	ds_read_b128 v[154:157], v151
	ds_read_b128 v[158:161], v151 offset:1024
	ds_read_b128 v[162:165], v151 offset:2048
	ds_read_b128 v[166:169], v151 offset:3072
	v_add_u32_e32 v151, s54, v145
	ds_read_b128 v[170:173], v151
	ds_read_b128 v[174:177], v151 offset:1024
	ds_read_b128 v[178:181], v151 offset:2048
	ds_read_b128 v[182:185], v151 offset:3072
	s_add_u32 s26, s26, 0x40000
	s_addc_u32 s27, s27, 0
	s_mov_b32 m0, s36
	v_lshl_add_u64 v[226:227], s[26:27], 0, v[134:135]
	ds_read_b128 v[186:189], v150 offset:32768
	ds_read_b128 v[190:193], v150 offset:33792
	ds_read_b128 v[194:197], v150 offset:34816
	ds_read_b128 v[198:201], v150 offset:35840
	ds_read_b128 v[202:205], v150 offset:36864
	ds_read_b128 v[206:209], v150 offset:37888
	ds_read_b128 v[210:213], v150 offset:38912
	ds_read_b128 v[214:217], v150 offset:39936
	global_load_lds_dwordx4 v[226:227], off
	v_lshl_add_u64 v[226:227], s[26:27], 0, v[130:131]
	s_mov_b32 m0, s37
	s_nop 0
	global_load_lds_dwordx4 v[226:227], off
	s_waitcnt vmcnt(8)
	s_waitcnt lgkmcnt(0)
	s_setprio 1
	s_barrier
	v_mfma_f32_16x16x32_bf16 v[124:127], v[154:157], v[186:189], v[124:127]
	v_mfma_f32_16x16x32_bf16 v[116:119], v[162:165], v[186:189], v[116:119]
	v_mfma_f32_16x16x32_bf16 v[108:111], v[154:157], v[194:197], v[108:111]
	v_mfma_f32_16x16x32_bf16 v[100:103], v[162:165], v[194:197], v[100:103]
	v_mfma_f32_16x16x32_bf16 v[92:95], v[154:157], v[202:205], v[92:95]
	v_mfma_f32_16x16x32_bf16 v[84:87], v[162:165], v[202:205], v[84:87]
	v_mfma_f32_16x16x32_bf16 v[76:79], v[154:157], v[210:213], v[76:79]
	v_mfma_f32_16x16x32_bf16 v[68:71], v[162:165], v[210:213], v[68:71]
	v_mfma_f32_16x16x32_bf16 v[124:127], v[158:161], v[190:193], v[124:127]
	v_mfma_f32_16x16x32_bf16 v[116:119], v[166:169], v[190:193], v[116:119]
	v_mfma_f32_16x16x32_bf16 v[108:111], v[158:161], v[198:201], v[108:111]
	v_mfma_f32_16x16x32_bf16 v[100:103], v[166:169], v[198:201], v[100:103]
	v_mfma_f32_16x16x32_bf16 v[92:95], v[158:161], v[206:209], v[92:95]
	v_mfma_f32_16x16x32_bf16 v[84:87], v[166:169], v[206:209], v[84:87]
	v_mfma_f32_16x16x32_bf16 v[76:79], v[158:161], v[214:217], v[76:79]
	v_mfma_f32_16x16x32_bf16 v[68:71], v[166:169], v[214:217], v[68:71]
	s_setprio 0
	s_setprio 1
	v_mfma_f32_16x16x32_bf16 v[120:123], v[170:173], v[186:189], v[120:123]
	v_mfma_f32_16x16x32_bf16 v[112:115], v[178:181], v[186:189], v[112:115]
	v_mfma_f32_16x16x32_bf16 v[104:107], v[170:173], v[194:197], v[104:107]
	v_mfma_f32_16x16x32_bf16 v[96:99], v[178:181], v[194:197], v[96:99]
	v_mfma_f32_16x16x32_bf16 v[88:91], v[170:173], v[202:205], v[88:91]
	v_mfma_f32_16x16x32_bf16 v[80:83], v[178:181], v[202:205], v[80:83]
	v_mfma_f32_16x16x32_bf16 v[72:75], v[170:173], v[210:213], v[72:75]
	v_mfma_f32_16x16x32_bf16 v[64:67], v[178:181], v[210:213], v[64:67]
	v_mfma_f32_16x16x32_bf16 v[120:123], v[174:177], v[190:193], v[120:123]
	v_mfma_f32_16x16x32_bf16 v[112:115], v[182:185], v[190:193], v[112:115]
	v_mfma_f32_16x16x32_bf16 v[104:107], v[174:177], v[198:201], v[104:107]
	v_mfma_f32_16x16x32_bf16 v[96:99], v[182:185], v[198:201], v[96:99]
	v_mfma_f32_16x16x32_bf16 v[88:91], v[174:177], v[206:209], v[88:91]
	v_mfma_f32_16x16x32_bf16 v[80:83], v[182:185], v[206:209], v[80:83]
	v_mfma_f32_16x16x32_bf16 v[72:75], v[174:177], v[214:217], v[72:75]
	v_mfma_f32_16x16x32_bf16 v[64:67], v[182:185], v[214:217], v[64:67]
	s_barrier
	s_setprio 0
	s_add_i32 s26, s53, s28
	v_lshl_add_u64 v[218:219], v[218:219], 0, s[8:9]
	s_mov_b32 m0, s26
	ds_read_b128 v[186:189], v150 offset:49152
	ds_read_b128 v[190:193], v150 offset:50176
	global_load_lds_dwordx4 v[218:219], off
	s_add_i32 m0, s26, 0x2000
	s_add_u32 s24, s24, 0x40080
	v_lshl_add_u64 v[218:219], v[220:221], 0, s[8:9]
	s_addc_u32 s25, s25, 0
	s_add_i32 s26, s54, s28
	ds_read_b128 v[194:197], v150 offset:51200
	ds_read_b128 v[198:201], v150 offset:52224
	global_load_lds_dwordx4 v[218:219], off
	v_lshl_add_u64 v[218:219], s[24:25], 0, v[132:133]
	s_mov_b32 m0, s26
	ds_read_b128 v[202:205], v150 offset:53248
	global_load_lds_dwordx4 v[218:219], off
	v_lshl_add_u64 v[218:219], s[24:25], 0, v[128:129]
	s_add_i32 m0, s26, 0x2000
	ds_read_b128 v[206:209], v150 offset:54272
	global_load_lds_dwordx4 v[218:219], off
	v_lshl_add_u64 v[218:219], v[222:223], 0, s[8:9]
	s_mov_b32 m0, s38
	ds_read_b128 v[210:213], v150 offset:55296
	global_load_lds_dwordx4 v[218:219], off
	v_lshl_add_u64 v[218:219], v[224:225], 0, s[8:9]
	s_mov_b32 m0, s39
	ds_read_b128 v[214:217], v150 offset:56320
	global_load_lds_dwordx4 v[218:219], off
	s_waitcnt vmcnt(8)
	s_waitcnt lgkmcnt(0)
	s_setprio 1
	s_barrier
	v_mfma_f32_16x16x32_bf16 v[60:63], v[154:157], v[186:189], v[60:63]
	v_mfma_f32_16x16x32_bf16 v[52:55], v[162:165], v[186:189], v[52:55]
	v_mfma_f32_16x16x32_bf16 v[44:47], v[154:157], v[194:197], v[44:47]
	v_mfma_f32_16x16x32_bf16 v[36:39], v[162:165], v[194:197], v[36:39]
	v_mfma_f32_16x16x32_bf16 v[28:31], v[154:157], v[202:205], v[28:31]
	v_mfma_f32_16x16x32_bf16 v[20:23], v[162:165], v[202:205], v[20:23]
	v_mfma_f32_16x16x32_bf16 v[12:15], v[154:157], v[210:213], v[12:15]
	v_mfma_f32_16x16x32_bf16 v[4:7], v[162:165], v[210:213], v[4:7]
	v_mfma_f32_16x16x32_bf16 v[60:63], v[158:161], v[190:193], v[60:63]
	v_mfma_f32_16x16x32_bf16 v[52:55], v[166:169], v[190:193], v[52:55]
	v_mfma_f32_16x16x32_bf16 v[44:47], v[158:161], v[198:201], v[44:47]
	v_mfma_f32_16x16x32_bf16 v[36:39], v[166:169], v[198:201], v[36:39]
	v_mfma_f32_16x16x32_bf16 v[28:31], v[158:161], v[206:209], v[28:31]
	v_mfma_f32_16x16x32_bf16 v[20:23], v[166:169], v[206:209], v[20:23]
	v_mfma_f32_16x16x32_bf16 v[12:15], v[158:161], v[214:217], v[12:15]
	v_mfma_f32_16x16x32_bf16 v[4:7], v[166:169], v[214:217], v[4:7]
	s_setprio 0
	s_setprio 1
	v_mfma_f32_16x16x32_bf16 v[56:59], v[170:173], v[186:189], v[56:59]
	v_mfma_f32_16x16x32_bf16 v[48:51], v[178:181], v[186:189], v[48:51]
	v_mfma_f32_16x16x32_bf16 v[40:43], v[170:173], v[194:197], v[40:43]
	v_mfma_f32_16x16x32_bf16 v[32:35], v[178:181], v[194:197], v[32:35]
	v_mfma_f32_16x16x32_bf16 v[24:27], v[170:173], v[202:205], v[24:27]
	v_mfma_f32_16x16x32_bf16 v[16:19], v[178:181], v[202:205], v[16:19]
	v_mfma_f32_16x16x32_bf16 v[8:11], v[170:173], v[210:213], v[8:11]
	v_mfma_f32_16x16x32_bf16 v[0:3], v[178:181], v[210:213], v[0:3]
	v_mfma_f32_16x16x32_bf16 v[56:59], v[174:177], v[190:193], v[56:59]
	v_mfma_f32_16x16x32_bf16 v[48:51], v[182:185], v[190:193], v[48:51]
	v_mfma_f32_16x16x32_bf16 v[40:43], v[174:177], v[198:201], v[40:43]
	v_mfma_f32_16x16x32_bf16 v[32:35], v[182:185], v[198:201], v[32:35]
	v_mfma_f32_16x16x32_bf16 v[24:27], v[174:177], v[206:209], v[24:27]
	v_mfma_f32_16x16x32_bf16 v[16:19], v[182:185], v[206:209], v[16:19]
	v_mfma_f32_16x16x32_bf16 v[8:11], v[174:177], v[214:217], v[8:11]
	v_mfma_f32_16x16x32_bf16 v[0:3], v[182:185], v[214:217], v[0:3]
	s_barrier
	s_setprio 0
	s_add_i32 s52, s52, 2
	s_add_u32 s22, s22, 0x100
	s_addc_u32 s23, s23, 0
	s_add_u32 s50, s50, 0x100
	s_addc_u32 s51, s51, 0
	s_cmp_gt_u32 s52, 13
	s_cbranch_scc0 .LBB0_607
	s_and_b64 vcc, exec, s[10:11]
	s_cbranch_vccz .LBB0_610
	s_barrier

.Lpk716_j1:
	s_waitcnt lgkmcnt(0)
	s_setprio 1
	s_barrier
	v_mfma_f32_16x16x32_bf16 v[124:127], v[128:131], v[178:181], 0
	v_mfma_f32_16x16x32_bf16 v[120:123], v[136:139], v[178:181], 0
	v_mfma_f32_16x16x32_bf16 v[108:111], v[128:131], v[196:199], 0
	v_mfma_f32_16x16x32_bf16 v[104:107], v[136:139], v[196:199], 0
	v_mfma_f32_16x16x32_bf16 v[92:95], v[128:131], v[204:207], 0
	v_mfma_f32_16x16x32_bf16 v[88:91], v[136:139], v[204:207], 0
	v_mfma_f32_16x16x32_bf16 v[76:79], v[128:131], v[212:215], 0
	v_mfma_f32_16x16x32_bf16 v[72:75], v[136:139], v[212:215], 0
	v_mfma_f32_16x16x32_bf16 v[124:127], v[132:135], v[182:185], v[124:127]
	v_mfma_f32_16x16x32_bf16 v[120:123], v[140:143], v[182:185], v[120:123]
	v_mfma_f32_16x16x32_bf16 v[108:111], v[132:135], v[200:203], v[108:111]
	v_mfma_f32_16x16x32_bf16 v[104:107], v[140:143], v[200:203], v[104:107]
	v_mfma_f32_16x16x32_bf16 v[92:95], v[132:135], v[208:211], v[92:95]
	v_mfma_f32_16x16x32_bf16 v[88:91], v[140:143], v[208:211], v[88:91]
	v_mfma_f32_16x16x32_bf16 v[76:79], v[132:135], v[216:219], v[76:79]
	v_mfma_f32_16x16x32_bf16 v[72:75], v[140:143], v[216:219], v[72:75]
	s_setprio 0
	s_setprio 1
	v_mfma_f32_16x16x32_bf16 v[116:119], v[144:147], v[178:181], 0
	v_mfma_f32_16x16x32_bf16 v[112:115], v[170:173], v[178:181], 0
	v_mfma_f32_16x16x32_bf16 v[100:103], v[144:147], v[196:199], 0
	v_mfma_f32_16x16x32_bf16 v[96:99], v[170:173], v[196:199], 0
	v_mfma_f32_16x16x32_bf16 v[84:87], v[144:147], v[204:207], 0
	v_mfma_f32_16x16x32_bf16 v[80:83], v[170:173], v[204:207], 0
	v_mfma_f32_16x16x32_bf16 v[68:71], v[144:147], v[212:215], 0
	v_mfma_f32_16x16x32_bf16 v[64:67], v[170:173], v[212:215], 0
	v_mfma_f32_16x16x32_bf16 v[116:119], v[148:151], v[182:185], v[116:119]
	v_mfma_f32_16x16x32_bf16 v[112:115], v[174:177], v[182:185], v[112:115]
	v_mfma_f32_16x16x32_bf16 v[100:103], v[148:151], v[200:203], v[100:103]
	v_mfma_f32_16x16x32_bf16 v[96:99], v[174:177], v[200:203], v[96:99]
	v_mfma_f32_16x16x32_bf16 v[84:87], v[148:151], v[208:211], v[84:87]
	v_mfma_f32_16x16x32_bf16 v[80:83], v[174:177], v[208:211], v[80:83]
	v_mfma_f32_16x16x32_bf16 v[68:71], v[148:151], v[216:219], v[68:71]
	v_mfma_f32_16x16x32_bf16 v[64:67], v[174:177], v[216:219], v[64:67]
	s_barrier
	s_setprio 0
	s_add_i32 s48, s38, s26
	v_lshl_add_u64 v[186:187], s[22:23], 0, v[156:157]
	s_mov_b32 m0, s48
	ds_read_b128 v[178:181], v193 offset:16384
	ds_read_b128 v[182:185], v193 offset:17408
	global_load_lds_dwordx4 v[186:187], off
	s_add_i32 m0, s48, 0x2000
	s_add_u32 s48, s22, 0xb0000
	v_lshl_add_u64 v[220:221], s[22:23], 0, v[160:161]
	s_addc_u32 s49, s23, 0
	s_add_i32 s50, s39, s26
	ds_read_b128 v[196:199], v193 offset:18432
	ds_read_b128 v[200:203], v193 offset:19456
	global_load_lds_dwordx4 v[220:221], off
	v_lshl_add_u64 v[222:223], s[48:49], 0, v[156:157]
	s_mov_b32 m0, s50
	v_lshl_add_u64 v[224:225], s[24:25], 0, v[158:159]
	ds_read_b128 v[204:207], v193 offset:20480
	global_load_lds_dwordx4 v[222:223], off
	v_lshl_add_u64 v[222:223], s[48:49], 0, v[160:161]
	s_add_i32 m0, s50, 0x2000
	ds_read_b128 v[208:211], v193 offset:21504
	global_load_lds_dwordx4 v[222:223], off
	v_lshl_add_u64 v[222:223], s[24:25], 0, v[154:155]
	s_mov_b32 m0, s27
	ds_read_b128 v[212:215], v193 offset:22528
	global_load_lds_dwordx4 v[222:223], off
	s_mov_b32 m0, s28
	ds_read_b128 v[216:219], v193 offset:23552
	global_load_lds_dwordx4 v[224:225], off
	s_cmp_eq_u32 s101, 1
	s_cbranch_scc1 .Lpk716_r2
	s_waitcnt vmcnt(8)
	s_branch .Lpk716_j2

.Lpk716_j2:
	s_mov_b32 s101, 0
	s_waitcnt lgkmcnt(0)
	s_setprio 1
	s_barrier
	v_mfma_f32_16x16x32_bf16 v[60:63], v[128:131], v[178:181], 0
	v_mfma_f32_16x16x32_bf16 v[56:59], v[136:139], v[178:181], 0
	v_mfma_f32_16x16x32_bf16 v[44:47], v[128:131], v[196:199], 0
	v_mfma_f32_16x16x32_bf16 v[40:43], v[136:139], v[196:199], 0
	v_mfma_f32_16x16x32_bf16 v[28:31], v[128:131], v[204:207], 0
	v_mfma_f32_16x16x32_bf16 v[24:27], v[136:139], v[204:207], 0
	v_mfma_f32_16x16x32_bf16 v[12:15], v[128:131], v[212:215], 0
	v_mfma_f32_16x16x32_bf16 v[8:11], v[136:139], v[212:215], 0
	v_mfma_f32_16x16x32_bf16 v[60:63], v[132:135], v[182:185], v[60:63]
	v_mfma_f32_16x16x32_bf16 v[56:59], v[140:143], v[182:185], v[56:59]
	v_mfma_f32_16x16x32_bf16 v[44:47], v[132:135], v[200:203], v[44:47]
	v_mfma_f32_16x16x32_bf16 v[40:43], v[140:143], v[200:203], v[40:43]
	v_mfma_f32_16x16x32_bf16 v[28:31], v[132:135], v[208:211], v[28:31]
	v_mfma_f32_16x16x32_bf16 v[24:27], v[140:143], v[208:211], v[24:27]
	v_mfma_f32_16x16x32_bf16 v[12:15], v[132:135], v[216:219], v[12:15]
	v_mfma_f32_16x16x32_bf16 v[8:11], v[140:143], v[216:219], v[8:11]
	s_setprio 0
	s_setprio 1
	v_mfma_f32_16x16x32_bf16 v[52:55], v[144:147], v[178:181], 0
	v_mfma_f32_16x16x32_bf16 v[48:51], v[170:173], v[178:181], 0
	v_mfma_f32_16x16x32_bf16 v[36:39], v[144:147], v[196:199], 0
	v_mfma_f32_16x16x32_bf16 v[32:35], v[170:173], v[196:199], 0
	v_mfma_f32_16x16x32_bf16 v[20:23], v[144:147], v[204:207], 0
	v_mfma_f32_16x16x32_bf16 v[16:19], v[170:173], v[204:207], 0
	v_mfma_f32_16x16x32_bf16 v[4:7], v[144:147], v[212:215], 0
	v_mfma_f32_16x16x32_bf16 v[0:3], v[170:173], v[212:215], 0
	v_mfma_f32_16x16x32_bf16 v[52:55], v[148:151], v[182:185], v[52:55]
	v_mfma_f32_16x16x32_bf16 v[48:51], v[174:177], v[182:185], v[48:51]
	v_mfma_f32_16x16x32_bf16 v[36:39], v[148:151], v[200:203], v[36:39]
	v_mfma_f32_16x16x32_bf16 v[32:35], v[174:177], v[200:203], v[32:35]
	v_mfma_f32_16x16x32_bf16 v[20:23], v[148:151], v[208:211], v[20:23]
	v_mfma_f32_16x16x32_bf16 v[16:19], v[174:177], v[208:211], v[16:19]
	v_mfma_f32_16x16x32_bf16 v[4:7], v[148:151], v[216:219], v[4:7]
	v_mfma_f32_16x16x32_bf16 v[0:3], v[174:177], v[216:219], v[0:3]
	s_barrier
	s_setprio 0
	s_branch .Lpk716_seg3
.LBB0_716:
	ds_read_b128 v[128:131], v191
	ds_read_b128 v[132:135], v191 offset:1024
	ds_read_b128 v[136:139], v191 offset:2048
	ds_read_b128 v[140:143], v191 offset:3072
	ds_read_b128 v[144:147], v192
	ds_read_b128 v[148:151], v192 offset:1024
	ds_read_b128 v[170:173], v192 offset:2048
	ds_read_b128 v[174:177], v192 offset:3072
	s_add_u32 s22, s20, 0xfff50080
	s_addc_u32 s23, s21, -1
	s_cmp_eq_u32 s47, 40
	s_cselect_b32 s25, s7, s23
	s_cselect_b32 s24, s6, s22
	s_cselect_b32 s23, s19, s45
	s_cselect_b32 s22, s18, s44
	v_lshl_add_u64 v[186:187], s[20:21], 0, v[162:163]
	s_add_i32 m0, s27, 0xc000
	ds_read_b128 v[178:181], v193
	ds_read_b128 v[182:185], v193 offset:1024
	ds_read_b128 v[196:199], v193 offset:2048
	ds_read_b128 v[200:203], v193 offset:3072
	ds_read_b128 v[204:207], v193 offset:4096
	ds_read_b128 v[208:211], v193 offset:5120
	ds_read_b128 v[212:215], v193 offset:6144
	ds_read_b128 v[216:219], v193 offset:7168
	global_load_lds_dwordx4 v[186:187], off
	v_lshl_add_u64 v[186:187], s[20:21], 0, v[164:165]
	s_add_i32 m0, s27, 0xe000
	s_nop 0
	global_load_lds_dwordx4 v[186:187], off
	s_waitcnt vmcnt(8)
	s_waitcnt lgkmcnt(0)
	s_setprio 1
	s_barrier
	v_mfma_f32_16x16x32_bf16 v[124:127], v[128:131], v[178:181], v[124:127]
	v_mfma_f32_16x16x32_bf16 v[120:123], v[136:139], v[178:181], v[120:123]
	v_mfma_f32_16x16x32_bf16 v[108:111], v[128:131], v[196:199], v[108:111]
	v_mfma_f32_16x16x32_bf16 v[104:107], v[136:139], v[196:199], v[104:107]
	v_mfma_f32_16x16x32_bf16 v[92:95], v[128:131], v[204:207], v[92:95]
	v_mfma_f32_16x16x32_bf16 v[88:91], v[136:139], v[204:207], v[88:91]
	v_mfma_f32_16x16x32_bf16 v[76:79], v[128:131], v[212:215], v[76:79]
	v_mfma_f32_16x16x32_bf16 v[72:75], v[136:139], v[212:215], v[72:75]
	v_mfma_f32_16x16x32_bf16 v[124:127], v[132:135], v[182:185], v[124:127]
	v_mfma_f32_16x16x32_bf16 v[120:123], v[140:143], v[182:185], v[120:123]
	v_mfma_f32_16x16x32_bf16 v[108:111], v[132:135], v[200:203], v[108:111]
	v_mfma_f32_16x16x32_bf16 v[104:107], v[140:143], v[200:203], v[104:107]
	v_mfma_f32_16x16x32_bf16 v[92:95], v[132:135], v[208:211], v[92:95]
	v_mfma_f32_16x16x32_bf16 v[88:91], v[140:143], v[208:211], v[88:91]
	v_mfma_f32_16x16x32_bf16 v[76:79], v[132:135], v[216:219], v[76:79]
	v_mfma_f32_16x16x32_bf16 v[72:75], v[140:143], v[216:219], v[72:75]
	s_setprio 0
	s_setprio 1
	v_mfma_f32_16x16x32_bf16 v[116:119], v[144:147], v[178:181], v[116:119]
	v_mfma_f32_16x16x32_bf16 v[112:115], v[170:173], v[178:181], v[112:115]
	v_mfma_f32_16x16x32_bf16 v[100:103], v[144:147], v[196:199], v[100:103]
	v_mfma_f32_16x16x32_bf16 v[96:99], v[170:173], v[196:199], v[96:99]
	v_mfma_f32_16x16x32_bf16 v[84:87], v[144:147], v[204:207], v[84:87]
	v_mfma_f32_16x16x32_bf16 v[80:83], v[170:173], v[204:207], v[80:83]
	v_mfma_f32_16x16x32_bf16 v[68:71], v[144:147], v[212:215], v[68:71]
	v_mfma_f32_16x16x32_bf16 v[64:67], v[170:173], v[212:215], v[64:67]
	v_mfma_f32_16x16x32_bf16 v[116:119], v[148:151], v[182:185], v[116:119]
	v_mfma_f32_16x16x32_bf16 v[112:115], v[174:177], v[182:185], v[112:115]
	v_mfma_f32_16x16x32_bf16 v[100:103], v[148:151], v[200:203], v[100:103]
	v_mfma_f32_16x16x32_bf16 v[96:99], v[174:177], v[200:203], v[96:99]
	v_mfma_f32_16x16x32_bf16 v[84:87], v[148:151], v[208:211], v[84:87]
	v_mfma_f32_16x16x32_bf16 v[80:83], v[174:177], v[208:211], v[80:83]
	v_mfma_f32_16x16x32_bf16 v[68:71], v[148:151], v[216:219], v[68:71]
	v_mfma_f32_16x16x32_bf16 v[64:67], v[174:177], v[216:219], v[64:67]
	s_barrier
	s_setprio 0
	s_add_i32 s48, s38, s26
	v_lshl_add_u64 v[186:187], s[22:23], 0, v[156:157]
	s_mov_b32 m0, s48
	ds_read_b128 v[178:181], v193 offset:16384
	ds_read_b128 v[182:185], v193 offset:17408
	global_load_lds_dwordx4 v[186:187], off
	s_add_i32 m0, s48, 0x2000
	s_add_u32 s48, s22, 0xb0000
	v_lshl_add_u64 v[220:221], s[22:23], 0, v[160:161]
	s_addc_u32 s49, s23, 0
	s_add_i32 s50, s39, s26
	ds_read_b128 v[196:199], v193 offset:18432
	ds_read_b128 v[200:203], v193 offset:19456
	global_load_lds_dwordx4 v[220:221], off
	v_lshl_add_u64 v[222:223], s[48:49], 0, v[156:157]
	s_mov_b32 m0, s50
	v_lshl_add_u64 v[224:225], s[24:25], 0, v[158:159]
	ds_read_b128 v[204:207], v193 offset:20480
	global_load_lds_dwordx4 v[222:223], off
	v_lshl_add_u64 v[222:223], s[48:49], 0, v[160:161]
	s_add_i32 m0, s50, 0x2000
	ds_read_b128 v[208:211], v193 offset:21504
	global_load_lds_dwordx4 v[222:223], off
	v_lshl_add_u64 v[222:223], s[24:25], 0, v[154:155]
	s_mov_b32 m0, s27
	ds_read_b128 v[212:215], v193 offset:22528
	global_load_lds_dwordx4 v[222:223], off
	s_mov_b32 m0, s28
	ds_read_b128 v[216:219], v193 offset:23552
	global_load_lds_dwordx4 v[224:225], off
	s_waitcnt vmcnt(8)
	s_waitcnt lgkmcnt(0)
	s_setprio 1
	s_barrier
	v_mfma_f32_16x16x32_bf16 v[60:63], v[128:131], v[178:181], v[60:63]
	v_mfma_f32_16x16x32_bf16 v[56:59], v[136:139], v[178:181], v[56:59]
	v_mfma_f32_16x16x32_bf16 v[44:47], v[128:131], v[196:199], v[44:47]
	v_mfma_f32_16x16x32_bf16 v[40:43], v[136:139], v[196:199], v[40:43]
	v_mfma_f32_16x16x32_bf16 v[28:31], v[128:131], v[204:207], v[28:31]
	v_mfma_f32_16x16x32_bf16 v[24:27], v[136:139], v[204:207], v[24:27]
	v_mfma_f32_16x16x32_bf16 v[12:15], v[128:131], v[212:215], v[12:15]
	v_mfma_f32_16x16x32_bf16 v[8:11], v[136:139], v[212:215], v[8:11]
	v_mfma_f32_16x16x32_bf16 v[60:63], v[132:135], v[182:185], v[60:63]
	v_mfma_f32_16x16x32_bf16 v[56:59], v[140:143], v[182:185], v[56:59]
	v_mfma_f32_16x16x32_bf16 v[44:47], v[132:135], v[200:203], v[44:47]
	v_mfma_f32_16x16x32_bf16 v[40:43], v[140:143], v[200:203], v[40:43]
	v_mfma_f32_16x16x32_bf16 v[28:31], v[132:135], v[208:211], v[28:31]
	v_mfma_f32_16x16x32_bf16 v[24:27], v[140:143], v[208:211], v[24:27]
	v_mfma_f32_16x16x32_bf16 v[12:15], v[132:135], v[216:219], v[12:15]
	v_mfma_f32_16x16x32_bf16 v[8:11], v[140:143], v[216:219], v[8:11]
	s_setprio 0
	s_setprio 1
	v_mfma_f32_16x16x32_bf16 v[52:55], v[144:147], v[178:181], v[52:55]
	v_mfma_f32_16x16x32_bf16 v[48:51], v[170:173], v[178:181], v[48:51]
	v_mfma_f32_16x16x32_bf16 v[36:39], v[144:147], v[196:199], v[36:39]
	v_mfma_f32_16x16x32_bf16 v[32:35], v[170:173], v[196:199], v[32:35]
	v_mfma_f32_16x16x32_bf16 v[20:23], v[144:147], v[204:207], v[20:23]
	v_mfma_f32_16x16x32_bf16 v[16:19], v[170:173], v[204:207], v[16:19]
	v_mfma_f32_16x16x32_bf16 v[4:7], v[144:147], v[212:215], v[4:7]
	v_mfma_f32_16x16x32_bf16 v[0:3], v[170:173], v[212:215], v[0:3]
	v_mfma_f32_16x16x32_bf16 v[52:55], v[148:151], v[182:185], v[52:55]
	v_mfma_f32_16x16x32_bf16 v[48:51], v[174:177], v[182:185], v[48:51]
	v_mfma_f32_16x16x32_bf16 v[36:39], v[148:151], v[200:203], v[36:39]
	v_mfma_f32_16x16x32_bf16 v[32:35], v[174:177], v[200:203], v[32:35]
	v_mfma_f32_16x16x32_bf16 v[20:23], v[148:151], v[208:211], v[20:23]
	v_mfma_f32_16x16x32_bf16 v[16:19], v[174:177], v[208:211], v[16:19]
	v_mfma_f32_16x16x32_bf16 v[4:7], v[148:151], v[216:219], v[4:7]
	v_mfma_f32_16x16x32_bf16 v[0:3], v[174:177], v[216:219], v[0:3]
	s_barrier
	s_setprio 0
.Lpk716_seg3:
	s_add_i32 s48, 0, 0x18000
	s_add_i32 s49, 0, 0x1c000
	v_add_u32_e32 v140, s48, v189
	v_add_u32_e32 v174, s49, v189
	ds_read_b128 v[128:131], v140
	ds_read_b128 v[132:135], v140 offset:1024
	ds_read_b128 v[136:139], v140 offset:2048
	ds_read_b128 v[140:143], v140 offset:3072
	ds_read_b128 v[144:147], v174
	ds_read_b128 v[148:151], v174 offset:1024
	ds_read_b128 v[170:173], v174 offset:2048
	ds_read_b128 v[174:177], v174 offset:3072
	s_add_u32 s24, s24, 0xb0000
	s_addc_u32 s25, s25, 0
	s_mov_b32 m0, s29
	v_lshl_add_u64 v[226:227], s[24:25], 0, v[154:155]
	ds_read_b128 v[178:181], v193 offset:32768
	ds_read_b128 v[182:185], v193 offset:33792
	ds_read_b128 v[196:199], v193 offset:34816
	ds_read_b128 v[200:203], v193 offset:35840
	ds_read_b128 v[204:207], v193 offset:36864
	ds_read_b128 v[208:211], v193 offset:37888
	ds_read_b128 v[212:215], v193 offset:38912
	ds_read_b128 v[216:219], v193 offset:39936
	global_load_lds_dwordx4 v[226:227], off
	v_lshl_add_u64 v[226:227], s[24:25], 0, v[158:159]
	s_mov_b32 m0, s30
	s_nop 0
	global_load_lds_dwordx4 v[226:227], off
	s_waitcnt vmcnt(8)
	s_waitcnt lgkmcnt(0)
	s_setprio 1
	s_barrier
	v_mfma_f32_16x16x32_bf16 v[124:127], v[128:131], v[178:181], v[124:127]
	v_mfma_f32_16x16x32_bf16 v[120:123], v[136:139], v[178:181], v[120:123]
	v_mfma_f32_16x16x32_bf16 v[108:111], v[128:131], v[196:199], v[108:111]
	v_mfma_f32_16x16x32_bf16 v[104:107], v[136:139], v[196:199], v[104:107]
	v_mfma_f32_16x16x32_bf16 v[92:95], v[128:131], v[204:207], v[92:95]
	v_mfma_f32_16x16x32_bf16 v[88:91], v[136:139], v[204:207], v[88:91]
	v_mfma_f32_16x16x32_bf16 v[76:79], v[128:131], v[212:215], v[76:79]
	v_mfma_f32_16x16x32_bf16 v[72:75], v[136:139], v[212:215], v[72:75]
	v_mfma_f32_16x16x32_bf16 v[124:127], v[132:135], v[182:185], v[124:127]
	v_mfma_f32_16x16x32_bf16 v[120:123], v[140:143], v[182:185], v[120:123]
	v_mfma_f32_16x16x32_bf16 v[108:111], v[132:135], v[200:203], v[108:111]
	v_mfma_f32_16x16x32_bf16 v[104:107], v[140:143], v[200:203], v[104:107]
	v_mfma_f32_16x16x32_bf16 v[92:95], v[132:135], v[208:211], v[92:95]
	v_mfma_f32_16x16x32_bf16 v[88:91], v[140:143], v[208:211], v[88:91]
	v_mfma_f32_16x16x32_bf16 v[76:79], v[132:135], v[216:219], v[76:79]
	v_mfma_f32_16x16x32_bf16 v[72:75], v[140:143], v[216:219], v[72:75]
	s_setprio 0
	s_setprio 1
	v_mfma_f32_16x16x32_bf16 v[116:119], v[144:147], v[178:181], v[116:119]
	v_mfma_f32_16x16x32_bf16 v[112:115], v[170:173], v[178:181], v[112:115]
	v_mfma_f32_16x16x32_bf16 v[100:103], v[144:147], v[196:199], v[100:103]
	v_mfma_f32_16x16x32_bf16 v[96:99], v[170:173], v[196:199], v[96:99]
	v_mfma_f32_16x16x32_bf16 v[84:87], v[144:147], v[204:207], v[84:87]
	v_mfma_f32_16x16x32_bf16 v[80:83], v[170:173], v[204:207], v[80:83]
	v_mfma_f32_16x16x32_bf16 v[68:71], v[144:147], v[212:215], v[68:71]
	v_mfma_f32_16x16x32_bf16 v[64:67], v[170:173], v[212:215], v[64:67]
	v_mfma_f32_16x16x32_bf16 v[116:119], v[148:151], v[182:185], v[116:119]
	v_mfma_f32_16x16x32_bf16 v[112:115], v[174:177], v[182:185], v[112:115]
	v_mfma_f32_16x16x32_bf16 v[100:103], v[148:151], v[200:203], v[100:103]
	v_mfma_f32_16x16x32_bf16 v[96:99], v[174:177], v[200:203], v[96:99]
	v_mfma_f32_16x16x32_bf16 v[84:87], v[148:151], v[208:211], v[84:87]
	v_mfma_f32_16x16x32_bf16 v[80:83], v[174:177], v[208:211], v[80:83]
	v_mfma_f32_16x16x32_bf16 v[68:71], v[148:151], v[216:219], v[68:71]
	v_mfma_f32_16x16x32_bf16 v[64:67], v[174:177], v[216:219], v[64:67]
	s_barrier
	s_setprio 0
	s_add_i32 s24, s48, s26
	v_lshl_add_u64 v[186:187], v[186:187], 0, s[14:15]
	s_mov_b32 m0, s24
	ds_read_b128 v[178:181], v193 offset:49152
	ds_read_b128 v[182:185], v193 offset:50176
	global_load_lds_dwordx4 v[186:187], off
	s_add_i32 m0, s24, 0x2000
	s_add_u32 s22, s22, 0xb0080
	v_lshl_add_u64 v[186:187], v[220:221], 0, s[14:15]
	s_addc_u32 s23, s23, 0
	s_add_i32 s24, s49, s26
	ds_read_b128 v[196:199], v193 offset:51200
	ds_read_b128 v[200:203], v193 offset:52224
	global_load_lds_dwordx4 v[186:187], off
	v_lshl_add_u64 v[186:187], s[22:23], 0, v[156:157]
	s_mov_b32 m0, s24
	ds_read_b128 v[204:207], v193 offset:53248
	global_load_lds_dwordx4 v[186:187], off
	v_lshl_add_u64 v[186:187], s[22:23], 0, v[160:161]
	s_add_i32 m0, s24, 0x2000
	ds_read_b128 v[208:211], v193 offset:54272
	global_load_lds_dwordx4 v[186:187], off
	v_lshl_add_u64 v[186:187], v[222:223], 0, s[14:15]
	s_mov_b32 m0, s33
	ds_read_b128 v[212:215], v193 offset:55296
	global_load_lds_dwordx4 v[186:187], off
	v_lshl_add_u64 v[186:187], v[224:225], 0, s[14:15]
	s_mov_b32 m0, s34
	ds_read_b128 v[216:219], v193 offset:56320
	global_load_lds_dwordx4 v[186:187], off
	s_waitcnt vmcnt(8)
	s_waitcnt lgkmcnt(0)
	s_setprio 1
	s_barrier
	v_mfma_f32_16x16x32_bf16 v[60:63], v[128:131], v[178:181], v[60:63]
	v_mfma_f32_16x16x32_bf16 v[56:59], v[136:139], v[178:181], v[56:59]
	v_mfma_f32_16x16x32_bf16 v[44:47], v[128:131], v[196:199], v[44:47]
	v_mfma_f32_16x16x32_bf16 v[40:43], v[136:139], v[196:199], v[40:43]
	v_mfma_f32_16x16x32_bf16 v[28:31], v[128:131], v[204:207], v[28:31]
	v_mfma_f32_16x16x32_bf16 v[24:27], v[136:139], v[204:207], v[24:27]
	v_mfma_f32_16x16x32_bf16 v[12:15], v[128:131], v[212:215], v[12:15]
	v_mfma_f32_16x16x32_bf16 v[8:11], v[136:139], v[212:215], v[8:11]
	v_mfma_f32_16x16x32_bf16 v[60:63], v[132:135], v[182:185], v[60:63]
	v_mfma_f32_16x16x32_bf16 v[56:59], v[140:143], v[182:185], v[56:59]
	v_mfma_f32_16x16x32_bf16 v[44:47], v[132:135], v[200:203], v[44:47]
	v_mfma_f32_16x16x32_bf16 v[40:43], v[140:143], v[200:203], v[40:43]
	v_mfma_f32_16x16x32_bf16 v[28:31], v[132:135], v[208:211], v[28:31]
	v_mfma_f32_16x16x32_bf16 v[24:27], v[140:143], v[208:211], v[24:27]
	v_mfma_f32_16x16x32_bf16 v[12:15], v[132:135], v[216:219], v[12:15]
	v_mfma_f32_16x16x32_bf16 v[8:11], v[140:143], v[216:219], v[8:11]
	s_setprio 0
	s_setprio 1
	v_mfma_f32_16x16x32_bf16 v[52:55], v[144:147], v[178:181], v[52:55]
	v_mfma_f32_16x16x32_bf16 v[48:51], v[170:173], v[178:181], v[48:51]
	v_mfma_f32_16x16x32_bf16 v[36:39], v[144:147], v[196:199], v[36:39]
	v_mfma_f32_16x16x32_bf16 v[32:35], v[170:173], v[196:199], v[32:35]
	v_mfma_f32_16x16x32_bf16 v[20:23], v[144:147], v[204:207], v[20:23]
	v_mfma_f32_16x16x32_bf16 v[16:19], v[170:173], v[204:207], v[16:19]
	v_mfma_f32_16x16x32_bf16 v[4:7], v[144:147], v[212:215], v[4:7]
	v_mfma_f32_16x16x32_bf16 v[0:3], v[170:173], v[212:215], v[0:3]
	v_mfma_f32_16x16x32_bf16 v[52:55], v[148:151], v[182:185], v[52:55]
	v_mfma_f32_16x16x32_bf16 v[48:51], v[174:177], v[182:185], v[48:51]
	v_mfma_f32_16x16x32_bf16 v[36:39], v[148:151], v[200:203], v[36:39]
	v_mfma_f32_16x16x32_bf16 v[32:35], v[174:177], v[200:203], v[32:35]
	v_mfma_f32_16x16x32_bf16 v[20:23], v[148:151], v[208:211], v[20:23]
	v_mfma_f32_16x16x32_bf16 v[16:19], v[174:177], v[208:211], v[16:19]
	v_mfma_f32_16x16x32_bf16 v[4:7], v[148:151], v[216:219], v[4:7]
	v_mfma_f32_16x16x32_bf16 v[0:3], v[174:177], v[216:219], v[0:3]
	s_barrier
	s_setprio 0
	s_add_i32 s47, s47, 2
	s_add_u32 s20, s20, 0x100
	s_addc_u32 s21, s21, 0
	s_add_u32 s44, s44, 0x100
	s_addc_u32 s45, s45, 0
	s_cmp_gt_u32 s47, 41
	s_cbranch_scc0 .LBB0_716
	s_and_b64 vcc, exec, s[16:17]
	s_cbranch_vccz .LBB0_719
	s_barrier

.Lpk874_j1:
	s_waitcnt lgkmcnt(0)
	s_setprio 1
	s_barrier
	v_mfma_f32_16x16x32_bf16 v[116:119], v[146:149], v[190:193], 0
	v_mfma_f32_16x16x32_bf16 v[112:115], v[166:169], v[190:193], 0
	v_mfma_f32_16x16x32_bf16 v[100:103], v[146:149], v[198:201], 0
	v_mfma_f32_16x16x32_bf16 v[96:99], v[166:169], v[198:201], 0
	v_mfma_f32_16x16x32_bf16 v[84:87], v[146:149], v[206:209], 0
	v_mfma_f32_16x16x32_bf16 v[80:83], v[166:169], v[206:209], 0
	v_mfma_f32_16x16x32_bf16 v[68:71], v[146:149], v[214:217], 0
	v_mfma_f32_16x16x32_bf16 v[64:67], v[166:169], v[214:217], 0
	v_mfma_f32_16x16x32_bf16 v[116:119], v[162:165], v[194:197], v[116:119]
	v_mfma_f32_16x16x32_bf16 v[112:115], v[170:173], v[194:197], v[112:115]
	v_mfma_f32_16x16x32_bf16 v[100:103], v[162:165], v[202:205], v[100:103]
	v_mfma_f32_16x16x32_bf16 v[96:99], v[170:173], v[202:205], v[96:99]
	v_mfma_f32_16x16x32_bf16 v[84:87], v[162:165], v[210:213], v[84:87]
	v_mfma_f32_16x16x32_bf16 v[80:83], v[170:173], v[210:213], v[80:83]
	v_mfma_f32_16x16x32_bf16 v[68:71], v[162:165], v[218:221], v[68:71]
	v_mfma_f32_16x16x32_bf16 v[64:67], v[170:173], v[218:221], v[64:67]
	s_setprio 0
	s_setprio 1
	v_mfma_f32_16x16x32_bf16 v[124:127], v[174:177], v[190:193], 0
	v_mfma_f32_16x16x32_bf16 v[120:123], v[182:185], v[190:193], 0
	v_mfma_f32_16x16x32_bf16 v[108:111], v[174:177], v[198:201], 0
	v_mfma_f32_16x16x32_bf16 v[104:107], v[182:185], v[198:201], 0
	v_mfma_f32_16x16x32_bf16 v[92:95], v[174:177], v[206:209], 0
	v_mfma_f32_16x16x32_bf16 v[88:91], v[182:185], v[206:209], 0
	v_mfma_f32_16x16x32_bf16 v[76:79], v[174:177], v[214:217], 0
	v_mfma_f32_16x16x32_bf16 v[72:75], v[182:185], v[214:217], 0
	v_mfma_f32_16x16x32_bf16 v[124:127], v[178:181], v[194:197], v[124:127]
	v_mfma_f32_16x16x32_bf16 v[120:123], v[186:189], v[194:197], v[120:123]
	v_mfma_f32_16x16x32_bf16 v[108:111], v[178:181], v[202:205], v[108:111]
	v_mfma_f32_16x16x32_bf16 v[104:107], v[186:189], v[202:205], v[104:107]
	v_mfma_f32_16x16x32_bf16 v[92:95], v[178:181], v[210:213], v[92:95]
	v_mfma_f32_16x16x32_bf16 v[88:91], v[186:189], v[210:213], v[88:91]
	v_mfma_f32_16x16x32_bf16 v[76:79], v[178:181], v[218:221], v[76:79]
	v_mfma_f32_16x16x32_bf16 v[72:75], v[186:189], v[218:221], v[72:75]
	s_barrier
	s_setprio 0
	s_add_i32 s54, s44, s33
	v_lshl_add_u64 v[222:223], s[28:29], 0, v[130:131]
	s_mov_b32 m0, s54
	ds_read_b128 v[190:193], v160 offset:16384
	ds_read_b128 v[194:197], v160 offset:17408
	global_load_lds_dwordx4 v[222:223], off
	s_add_i32 m0, s54, 0x2000
	s_add_u32 s70, s28, 0x40000
	v_lshl_add_u64 v[224:225], s[28:29], 0, v[134:135]
	s_addc_u32 s71, s29, 0
	s_add_i32 s54, s45, s33
	ds_read_b128 v[198:201], v160 offset:18432
	ds_read_b128 v[202:205], v160 offset:19456
	global_load_lds_dwordx4 v[224:225], off
	v_lshl_add_u64 v[226:227], s[70:71], 0, v[130:131]
	s_mov_b32 m0, s54
	v_lshl_add_u64 v[228:229], s[30:31], 0, v[132:133]
	ds_read_b128 v[206:209], v160 offset:20480
	global_load_lds_dwordx4 v[226:227], off
	v_lshl_add_u64 v[226:227], s[70:71], 0, v[134:135]
	s_add_i32 m0, s54, 0x2000
	ds_read_b128 v[210:213], v160 offset:21504
	global_load_lds_dwordx4 v[226:227], off
	v_lshl_add_u64 v[226:227], s[30:31], 0, v[128:129]
	s_mov_b32 m0, s9
	ds_read_b128 v[214:217], v160 offset:22528
	global_load_lds_dwordx4 v[226:227], off
	s_mov_b32 m0, s38
	ds_read_b128 v[218:221], v160 offset:23552
	global_load_lds_dwordx4 v[228:229], off
	s_cmp_eq_u32 s101, 1
	s_cbranch_scc1 .Lpk874_r2
	s_waitcnt vmcnt(8)
	s_branch .Lpk874_j2

.Lpk874_j2:
	s_mov_b32 s101, 0
	s_waitcnt lgkmcnt(0)
	s_setprio 1
	s_barrier
	v_mfma_f32_16x16x32_bf16 v[52:55], v[146:149], v[190:193], 0
	v_mfma_f32_16x16x32_bf16 v[48:51], v[166:169], v[190:193], 0
	v_mfma_f32_16x16x32_bf16 v[36:39], v[146:149], v[198:201], 0
	v_mfma_f32_16x16x32_bf16 v[32:35], v[166:169], v[198:201], 0
	v_mfma_f32_16x16x32_bf16 v[20:23], v[146:149], v[206:209], 0
	v_mfma_f32_16x16x32_bf16 v[16:19], v[166:169], v[206:209], 0
	v_mfma_f32_16x16x32_bf16 v[4:7], v[146:149], v[214:217], 0
	v_mfma_f32_16x16x32_bf16 v[0:3], v[166:169], v[214:217], 0
	v_mfma_f32_16x16x32_bf16 v[52:55], v[162:165], v[194:197], v[52:55]
	v_mfma_f32_16x16x32_bf16 v[48:51], v[170:173], v[194:197], v[48:51]
	v_mfma_f32_16x16x32_bf16 v[36:39], v[162:165], v[202:205], v[36:39]
	v_mfma_f32_16x16x32_bf16 v[32:35], v[170:173], v[202:205], v[32:35]
	v_mfma_f32_16x16x32_bf16 v[20:23], v[162:165], v[210:213], v[20:23]
	v_mfma_f32_16x16x32_bf16 v[16:19], v[170:173], v[210:213], v[16:19]
	v_mfma_f32_16x16x32_bf16 v[4:7], v[162:165], v[218:221], v[4:7]
	v_mfma_f32_16x16x32_bf16 v[0:3], v[170:173], v[218:221], v[0:3]
	s_setprio 0
	s_setprio 1
	v_mfma_f32_16x16x32_bf16 v[60:63], v[174:177], v[190:193], 0
	v_mfma_f32_16x16x32_bf16 v[56:59], v[182:185], v[190:193], 0
	v_mfma_f32_16x16x32_bf16 v[44:47], v[174:177], v[198:201], 0
	v_mfma_f32_16x16x32_bf16 v[40:43], v[182:185], v[198:201], 0
	v_mfma_f32_16x16x32_bf16 v[28:31], v[174:177], v[206:209], 0
	v_mfma_f32_16x16x32_bf16 v[24:27], v[182:185], v[206:209], 0
	v_mfma_f32_16x16x32_bf16 v[12:15], v[174:177], v[214:217], 0
	v_mfma_f32_16x16x32_bf16 v[8:11], v[182:185], v[214:217], 0
	v_mfma_f32_16x16x32_bf16 v[60:63], v[178:181], v[194:197], v[60:63]
	v_mfma_f32_16x16x32_bf16 v[56:59], v[186:189], v[194:197], v[56:59]
	v_mfma_f32_16x16x32_bf16 v[44:47], v[178:181], v[202:205], v[44:47]
	v_mfma_f32_16x16x32_bf16 v[40:43], v[186:189], v[202:205], v[40:43]
	v_mfma_f32_16x16x32_bf16 v[28:31], v[178:181], v[210:213], v[28:31]
	v_mfma_f32_16x16x32_bf16 v[24:27], v[186:189], v[210:213], v[24:27]
	v_mfma_f32_16x16x32_bf16 v[12:15], v[178:181], v[218:221], v[12:15]
	v_mfma_f32_16x16x32_bf16 v[8:11], v[186:189], v[218:221], v[8:11]
	s_barrier
	s_setprio 0
	s_branch .Lpk874_seg3
.LBB0_874:
	ds_read_b128 v[146:149], v158
	ds_read_b128 v[162:165], v158 offset:1024
	ds_read_b128 v[166:169], v158 offset:2048
	ds_read_b128 v[170:173], v158 offset:3072
	ds_read_b128 v[174:177], v159
	ds_read_b128 v[178:181], v159 offset:1024
	ds_read_b128 v[182:185], v159 offset:2048
	ds_read_b128 v[186:189], v159 offset:3072
	s_add_u32 s28, s26, 0xfffc0080
	s_addc_u32 s29, s27, -1
	s_cmp_eq_u32 s66, 12
	s_cselect_b32 s31, s21, s29
	s_cselect_b32 s30, s50, s28
	s_cselect_b32 s29, s19, s53
	s_cselect_b32 s28, s51, s52
	v_lshl_add_u64 v[222:223], s[26:27], 0, v[138:139]
	s_add_i32 m0, s9, 0xc000
	ds_read_b128 v[190:193], v160
	ds_read_b128 v[194:197], v160 offset:1024
	ds_read_b128 v[198:201], v160 offset:2048
	ds_read_b128 v[202:205], v160 offset:3072
	ds_read_b128 v[206:209], v160 offset:4096
	ds_read_b128 v[210:213], v160 offset:5120
	ds_read_b128 v[214:217], v160 offset:6144
	ds_read_b128 v[218:221], v160 offset:7168
	global_load_lds_dwordx4 v[222:223], off
	v_lshl_add_u64 v[222:223], s[26:27], 0, v[140:141]
	s_add_i32 m0, s9, 0xe000
	s_nop 0
	global_load_lds_dwordx4 v[222:223], off
	s_waitcnt vmcnt(8)
	s_waitcnt lgkmcnt(0)
	s_setprio 1
	s_barrier
	v_mfma_f32_16x16x32_bf16 v[116:119], v[146:149], v[190:193], v[116:119]
	v_mfma_f32_16x16x32_bf16 v[112:115], v[166:169], v[190:193], v[112:115]
	v_mfma_f32_16x16x32_bf16 v[100:103], v[146:149], v[198:201], v[100:103]
	v_mfma_f32_16x16x32_bf16 v[96:99], v[166:169], v[198:201], v[96:99]
	v_mfma_f32_16x16x32_bf16 v[84:87], v[146:149], v[206:209], v[84:87]
	v_mfma_f32_16x16x32_bf16 v[80:83], v[166:169], v[206:209], v[80:83]
	v_mfma_f32_16x16x32_bf16 v[68:71], v[146:149], v[214:217], v[68:71]
	v_mfma_f32_16x16x32_bf16 v[64:67], v[166:169], v[214:217], v[64:67]
	v_mfma_f32_16x16x32_bf16 v[116:119], v[162:165], v[194:197], v[116:119]
	v_mfma_f32_16x16x32_bf16 v[112:115], v[170:173], v[194:197], v[112:115]
	v_mfma_f32_16x16x32_bf16 v[100:103], v[162:165], v[202:205], v[100:103]
	v_mfma_f32_16x16x32_bf16 v[96:99], v[170:173], v[202:205], v[96:99]
	v_mfma_f32_16x16x32_bf16 v[84:87], v[162:165], v[210:213], v[84:87]
	v_mfma_f32_16x16x32_bf16 v[80:83], v[170:173], v[210:213], v[80:83]
	v_mfma_f32_16x16x32_bf16 v[68:71], v[162:165], v[218:221], v[68:71]
	v_mfma_f32_16x16x32_bf16 v[64:67], v[170:173], v[218:221], v[64:67]
	s_setprio 0
	s_setprio 1
	v_mfma_f32_16x16x32_bf16 v[124:127], v[174:177], v[190:193], v[124:127]
	v_mfma_f32_16x16x32_bf16 v[120:123], v[182:185], v[190:193], v[120:123]
	v_mfma_f32_16x16x32_bf16 v[108:111], v[174:177], v[198:201], v[108:111]
	v_mfma_f32_16x16x32_bf16 v[104:107], v[182:185], v[198:201], v[104:107]
	v_mfma_f32_16x16x32_bf16 v[92:95], v[174:177], v[206:209], v[92:95]
	v_mfma_f32_16x16x32_bf16 v[88:91], v[182:185], v[206:209], v[88:91]
	v_mfma_f32_16x16x32_bf16 v[76:79], v[174:177], v[214:217], v[76:79]
	v_mfma_f32_16x16x32_bf16 v[72:75], v[182:185], v[214:217], v[72:75]
	v_mfma_f32_16x16x32_bf16 v[124:127], v[178:181], v[194:197], v[124:127]
	v_mfma_f32_16x16x32_bf16 v[120:123], v[186:189], v[194:197], v[120:123]
	v_mfma_f32_16x16x32_bf16 v[108:111], v[178:181], v[202:205], v[108:111]
	v_mfma_f32_16x16x32_bf16 v[104:107], v[186:189], v[202:205], v[104:107]
	v_mfma_f32_16x16x32_bf16 v[92:95], v[178:181], v[210:213], v[92:95]
	v_mfma_f32_16x16x32_bf16 v[88:91], v[186:189], v[210:213], v[88:91]
	v_mfma_f32_16x16x32_bf16 v[76:79], v[178:181], v[218:221], v[76:79]
	v_mfma_f32_16x16x32_bf16 v[72:75], v[186:189], v[218:221], v[72:75]
	s_barrier
	s_setprio 0
	s_add_i32 s54, s44, s33
	v_lshl_add_u64 v[222:223], s[28:29], 0, v[130:131]
	s_mov_b32 m0, s54
	ds_read_b128 v[190:193], v160 offset:16384
	ds_read_b128 v[194:197], v160 offset:17408
	global_load_lds_dwordx4 v[222:223], off
	s_add_i32 m0, s54, 0x2000
	s_add_u32 s70, s28, 0x40000
	v_lshl_add_u64 v[224:225], s[28:29], 0, v[134:135]
	s_addc_u32 s71, s29, 0
	s_add_i32 s54, s45, s33
	ds_read_b128 v[198:201], v160 offset:18432
	ds_read_b128 v[202:205], v160 offset:19456
	global_load_lds_dwordx4 v[224:225], off
	v_lshl_add_u64 v[226:227], s[70:71], 0, v[130:131]
	s_mov_b32 m0, s54
	v_lshl_add_u64 v[228:229], s[30:31], 0, v[132:133]
	ds_read_b128 v[206:209], v160 offset:20480
	global_load_lds_dwordx4 v[226:227], off
	v_lshl_add_u64 v[226:227], s[70:71], 0, v[134:135]
	s_add_i32 m0, s54, 0x2000
	ds_read_b128 v[210:213], v160 offset:21504
	global_load_lds_dwordx4 v[226:227], off
	v_lshl_add_u64 v[226:227], s[30:31], 0, v[128:129]
	s_mov_b32 m0, s9
	ds_read_b128 v[214:217], v160 offset:22528
	global_load_lds_dwordx4 v[226:227], off
	s_mov_b32 m0, s38
	ds_read_b128 v[218:221], v160 offset:23552
	global_load_lds_dwordx4 v[228:229], off
	s_waitcnt vmcnt(8)
	s_waitcnt lgkmcnt(0)
	s_setprio 1
	s_barrier
	v_mfma_f32_16x16x32_bf16 v[52:55], v[146:149], v[190:193], v[52:55]
	v_mfma_f32_16x16x32_bf16 v[48:51], v[166:169], v[190:193], v[48:51]
	v_mfma_f32_16x16x32_bf16 v[36:39], v[146:149], v[198:201], v[36:39]
	v_mfma_f32_16x16x32_bf16 v[32:35], v[166:169], v[198:201], v[32:35]
	v_mfma_f32_16x16x32_bf16 v[20:23], v[146:149], v[206:209], v[20:23]
	v_mfma_f32_16x16x32_bf16 v[16:19], v[166:169], v[206:209], v[16:19]
	v_mfma_f32_16x16x32_bf16 v[4:7], v[146:149], v[214:217], v[4:7]
	v_mfma_f32_16x16x32_bf16 v[0:3], v[166:169], v[214:217], v[0:3]
	v_mfma_f32_16x16x32_bf16 v[52:55], v[162:165], v[194:197], v[52:55]
	v_mfma_f32_16x16x32_bf16 v[48:51], v[170:173], v[194:197], v[48:51]
	v_mfma_f32_16x16x32_bf16 v[36:39], v[162:165], v[202:205], v[36:39]
	v_mfma_f32_16x16x32_bf16 v[32:35], v[170:173], v[202:205], v[32:35]
	v_mfma_f32_16x16x32_bf16 v[20:23], v[162:165], v[210:213], v[20:23]
	v_mfma_f32_16x16x32_bf16 v[16:19], v[170:173], v[210:213], v[16:19]
	v_mfma_f32_16x16x32_bf16 v[4:7], v[162:165], v[218:221], v[4:7]
	v_mfma_f32_16x16x32_bf16 v[0:3], v[170:173], v[218:221], v[0:3]
	s_setprio 0
	s_setprio 1
	v_mfma_f32_16x16x32_bf16 v[60:63], v[174:177], v[190:193], v[60:63]
	v_mfma_f32_16x16x32_bf16 v[56:59], v[182:185], v[190:193], v[56:59]
	v_mfma_f32_16x16x32_bf16 v[44:47], v[174:177], v[198:201], v[44:47]
	v_mfma_f32_16x16x32_bf16 v[40:43], v[182:185], v[198:201], v[40:43]
	v_mfma_f32_16x16x32_bf16 v[28:31], v[174:177], v[206:209], v[28:31]
	v_mfma_f32_16x16x32_bf16 v[24:27], v[182:185], v[206:209], v[24:27]
	v_mfma_f32_16x16x32_bf16 v[12:15], v[174:177], v[214:217], v[12:15]
	v_mfma_f32_16x16x32_bf16 v[8:11], v[182:185], v[214:217], v[8:11]
	v_mfma_f32_16x16x32_bf16 v[60:63], v[178:181], v[194:197], v[60:63]
	v_mfma_f32_16x16x32_bf16 v[56:59], v[186:189], v[194:197], v[56:59]
	v_mfma_f32_16x16x32_bf16 v[44:47], v[178:181], v[202:205], v[44:47]
	v_mfma_f32_16x16x32_bf16 v[40:43], v[186:189], v[202:205], v[40:43]
	v_mfma_f32_16x16x32_bf16 v[28:31], v[178:181], v[210:213], v[28:31]
	v_mfma_f32_16x16x32_bf16 v[24:27], v[186:189], v[210:213], v[24:27]
	v_mfma_f32_16x16x32_bf16 v[12:15], v[178:181], v[218:221], v[12:15]
	v_mfma_f32_16x16x32_bf16 v[8:11], v[186:189], v[218:221], v[8:11]
	s_barrier
	s_setprio 0
.Lpk874_seg3:
	s_add_i32 s54, 0, 0x18000
	v_add_u32_e32 v136, s54, v154
	s_add_i32 s55, 0, 0x1c000
	ds_read_b128 v[146:149], v136
	ds_read_b128 v[162:165], v136 offset:1024
	ds_read_b128 v[166:169], v136 offset:2048
	ds_read_b128 v[170:173], v136 offset:3072
	v_add_u32_e32 v136, s55, v154
	ds_read_b128 v[174:177], v136
	ds_read_b128 v[178:181], v136 offset:1024
	ds_read_b128 v[182:185], v136 offset:2048
	ds_read_b128 v[186:189], v136 offset:3072
	s_add_u32 s30, s30, 0x40000
	s_addc_u32 s31, s31, 0
	s_mov_b32 m0, s39
	v_lshl_add_u64 v[230:231], s[30:31], 0, v[128:129]
	ds_read_b128 v[190:193], v160 offset:32768
	ds_read_b128 v[194:197], v160 offset:33792
	ds_read_b128 v[198:201], v160 offset:34816
	ds_read_b128 v[202:205], v160 offset:35840
	ds_read_b128 v[206:209], v160 offset:36864
	ds_read_b128 v[210:213], v160 offset:37888
	ds_read_b128 v[214:217], v160 offset:38912
	ds_read_b128 v[218:221], v160 offset:39936
	global_load_lds_dwordx4 v[230:231], off
	v_lshl_add_u64 v[230:231], s[30:31], 0, v[132:133]
	s_mov_b32 m0, s40
	s_nop 0
	global_load_lds_dwordx4 v[230:231], off
	s_waitcnt vmcnt(8)
	s_waitcnt lgkmcnt(0)
	s_setprio 1
	s_barrier
	v_mfma_f32_16x16x32_bf16 v[116:119], v[146:149], v[190:193], v[116:119]
	v_mfma_f32_16x16x32_bf16 v[112:115], v[166:169], v[190:193], v[112:115]
	v_mfma_f32_16x16x32_bf16 v[100:103], v[146:149], v[198:201], v[100:103]
	v_mfma_f32_16x16x32_bf16 v[96:99], v[166:169], v[198:201], v[96:99]
	v_mfma_f32_16x16x32_bf16 v[84:87], v[146:149], v[206:209], v[84:87]
	v_mfma_f32_16x16x32_bf16 v[80:83], v[166:169], v[206:209], v[80:83]
	v_mfma_f32_16x16x32_bf16 v[68:71], v[146:149], v[214:217], v[68:71]
	v_mfma_f32_16x16x32_bf16 v[64:67], v[166:169], v[214:217], v[64:67]
	v_mfma_f32_16x16x32_bf16 v[116:119], v[162:165], v[194:197], v[116:119]
	v_mfma_f32_16x16x32_bf16 v[112:115], v[170:173], v[194:197], v[112:115]
	v_mfma_f32_16x16x32_bf16 v[100:103], v[162:165], v[202:205], v[100:103]
	v_mfma_f32_16x16x32_bf16 v[96:99], v[170:173], v[202:205], v[96:99]
	v_mfma_f32_16x16x32_bf16 v[84:87], v[162:165], v[210:213], v[84:87]
	v_mfma_f32_16x16x32_bf16 v[80:83], v[170:173], v[210:213], v[80:83]
	v_mfma_f32_16x16x32_bf16 v[68:71], v[162:165], v[218:221], v[68:71]
	v_mfma_f32_16x16x32_bf16 v[64:67], v[170:173], v[218:221], v[64:67]
	s_setprio 0
	s_setprio 1
	v_mfma_f32_16x16x32_bf16 v[124:127], v[174:177], v[190:193], v[124:127]
	v_mfma_f32_16x16x32_bf16 v[120:123], v[182:185], v[190:193], v[120:123]
	v_mfma_f32_16x16x32_bf16 v[108:111], v[174:177], v[198:201], v[108:111]
	v_mfma_f32_16x16x32_bf16 v[104:107], v[182:185], v[198:201], v[104:107]
	v_mfma_f32_16x16x32_bf16 v[92:95], v[174:177], v[206:209], v[92:95]
	v_mfma_f32_16x16x32_bf16 v[88:91], v[182:185], v[206:209], v[88:91]
	v_mfma_f32_16x16x32_bf16 v[76:79], v[174:177], v[214:217], v[76:79]
	v_mfma_f32_16x16x32_bf16 v[72:75], v[182:185], v[214:217], v[72:75]
	v_mfma_f32_16x16x32_bf16 v[124:127], v[178:181], v[194:197], v[124:127]
	v_mfma_f32_16x16x32_bf16 v[120:123], v[186:189], v[194:197], v[120:123]
	v_mfma_f32_16x16x32_bf16 v[108:111], v[178:181], v[202:205], v[108:111]
	v_mfma_f32_16x16x32_bf16 v[104:107], v[186:189], v[202:205], v[104:107]
	v_mfma_f32_16x16x32_bf16 v[92:95], v[178:181], v[210:213], v[92:95]
	v_mfma_f32_16x16x32_bf16 v[88:91], v[186:189], v[210:213], v[88:91]
	v_mfma_f32_16x16x32_bf16 v[76:79], v[178:181], v[218:221], v[76:79]
	v_mfma_f32_16x16x32_bf16 v[72:75], v[186:189], v[218:221], v[72:75]
	s_barrier
	s_setprio 0
	s_add_i32 s30, s54, s33
	v_lshl_add_u64 v[222:223], v[222:223], 0, s[14:15]
	s_mov_b32 m0, s30
	ds_read_b128 v[190:193], v160 offset:49152
	ds_read_b128 v[194:197], v160 offset:50176
	global_load_lds_dwordx4 v[222:223], off
	s_add_i32 m0, s30, 0x2000
	s_add_u32 s28, s28, 0x40080
	v_lshl_add_u64 v[222:223], v[224:225], 0, s[14:15]
	s_addc_u32 s29, s29, 0
	s_add_i32 s30, s55, s33
	ds_read_b128 v[198:201], v160 offset:51200
	ds_read_b128 v[202:205], v160 offset:52224
	global_load_lds_dwordx4 v[222:223], off
	v_lshl_add_u64 v[222:223], s[28:29], 0, v[130:131]
	s_mov_b32 m0, s30
	ds_read_b128 v[206:209], v160 offset:53248
	global_load_lds_dwordx4 v[222:223], off
	v_lshl_add_u64 v[222:223], s[28:29], 0, v[134:135]
	s_add_i32 m0, s30, 0x2000
	ds_read_b128 v[210:213], v160 offset:54272
	global_load_lds_dwordx4 v[222:223], off
	v_lshl_add_u64 v[222:223], v[226:227], 0, s[14:15]
	s_mov_b32 m0, s41
	ds_read_b128 v[214:217], v160 offset:55296
	global_load_lds_dwordx4 v[222:223], off
	v_lshl_add_u64 v[222:223], v[228:229], 0, s[14:15]
	s_mov_b32 m0, s42
	ds_read_b128 v[218:221], v160 offset:56320
	global_load_lds_dwordx4 v[222:223], off
	s_waitcnt vmcnt(8)
	s_waitcnt lgkmcnt(0)
	s_setprio 1
	s_barrier
	v_mfma_f32_16x16x32_bf16 v[52:55], v[146:149], v[190:193], v[52:55]
	v_mfma_f32_16x16x32_bf16 v[48:51], v[166:169], v[190:193], v[48:51]
	v_mfma_f32_16x16x32_bf16 v[36:39], v[146:149], v[198:201], v[36:39]
	v_mfma_f32_16x16x32_bf16 v[32:35], v[166:169], v[198:201], v[32:35]
	v_mfma_f32_16x16x32_bf16 v[20:23], v[146:149], v[206:209], v[20:23]
	v_mfma_f32_16x16x32_bf16 v[16:19], v[166:169], v[206:209], v[16:19]
	v_mfma_f32_16x16x32_bf16 v[4:7], v[146:149], v[214:217], v[4:7]
	v_mfma_f32_16x16x32_bf16 v[0:3], v[166:169], v[214:217], v[0:3]
	v_mfma_f32_16x16x32_bf16 v[52:55], v[162:165], v[194:197], v[52:55]
	v_mfma_f32_16x16x32_bf16 v[48:51], v[170:173], v[194:197], v[48:51]
	v_mfma_f32_16x16x32_bf16 v[36:39], v[162:165], v[202:205], v[36:39]
	v_mfma_f32_16x16x32_bf16 v[32:35], v[170:173], v[202:205], v[32:35]
	v_mfma_f32_16x16x32_bf16 v[20:23], v[162:165], v[210:213], v[20:23]
	v_mfma_f32_16x16x32_bf16 v[16:19], v[170:173], v[210:213], v[16:19]
	v_mfma_f32_16x16x32_bf16 v[4:7], v[162:165], v[218:221], v[4:7]
	v_mfma_f32_16x16x32_bf16 v[0:3], v[170:173], v[218:221], v[0:3]
	s_setprio 0
	s_setprio 1
	v_mfma_f32_16x16x32_bf16 v[60:63], v[174:177], v[190:193], v[60:63]
	v_mfma_f32_16x16x32_bf16 v[56:59], v[182:185], v[190:193], v[56:59]
	v_mfma_f32_16x16x32_bf16 v[44:47], v[174:177], v[198:201], v[44:47]
	v_mfma_f32_16x16x32_bf16 v[40:43], v[182:185], v[198:201], v[40:43]
	v_mfma_f32_16x16x32_bf16 v[28:31], v[174:177], v[206:209], v[28:31]
	v_mfma_f32_16x16x32_bf16 v[24:27], v[182:185], v[206:209], v[24:27]
	v_mfma_f32_16x16x32_bf16 v[12:15], v[174:177], v[214:217], v[12:15]
	v_mfma_f32_16x16x32_bf16 v[8:11], v[182:185], v[214:217], v[8:11]
	v_mfma_f32_16x16x32_bf16 v[60:63], v[178:181], v[194:197], v[60:63]
	v_mfma_f32_16x16x32_bf16 v[56:59], v[186:189], v[194:197], v[56:59]
	v_mfma_f32_16x16x32_bf16 v[44:47], v[178:181], v[202:205], v[44:47]
	v_mfma_f32_16x16x32_bf16 v[40:43], v[186:189], v[202:205], v[40:43]
	v_mfma_f32_16x16x32_bf16 v[28:31], v[178:181], v[210:213], v[28:31]
	v_mfma_f32_16x16x32_bf16 v[24:27], v[186:189], v[210:213], v[24:27]
	v_mfma_f32_16x16x32_bf16 v[12:15], v[178:181], v[218:221], v[12:15]
	v_mfma_f32_16x16x32_bf16 v[8:11], v[186:189], v[218:221], v[8:11]
	s_barrier
	s_setprio 0
	s_add_i32 s66, s66, 2
	s_add_u32 s26, s26, 0x100
	s_addc_u32 s27, s27, 0
	s_add_u32 s52, s52, 0x100
	s_addc_u32 s53, s53, 0
	s_cmp_gt_u32 s66, 13
	s_cbranch_scc0 .LBB0_874
	s_and_b64 vcc, exec, s[16:17]
	s_cbranch_vccz .LBB0_877
	s_barrier

.LBB0_1349:
	v_mov_b32_e32 v0, 0
	v_lshl_add_u64 v[128:129], s[26:27], 0, v[162:163]
	v_lshl_add_u64 v[130:131], s[26:27], 0, v[164:165]
	v_lshl_add_u64 v[132:133], s[24:25], 0, v[166:167]
	v_lshl_add_u64 v[134:135], s[24:25], 0, v[168:169]
	s_mov_b32 s21, -2
	s_mov_b64 s[28:29], 0
	v_lshl_add_u64 v[230:231], v[130:131], 0, s[28:29]
	s_mov_b32 m0, s50
	v_lshl_add_u64 v[228:229], v[230:231], 0, s[8:9]
	v_lshl_add_u64 v[232:233], v[128:129], 0, s[28:29]
	global_load_lds_dwordx4 v[228:229], off
	v_lshl_add_u64 v[228:229], v[232:233], 0, s[8:9]
	s_mov_b32 m0, s51
	s_nop 0
	global_load_lds_dwordx4 v[228:229], off
	s_waitcnt vmcnt(8)
	s_waitcnt lgkmcnt(0)
	s_setprio 1
	s_barrier
	v_mfma_f32_16x16x32_bf16 v[124:127], v[136:139], v[196:199], 0
	v_mfma_f32_16x16x32_bf16 v[120:123], v[144:147], v[196:199], 0
	v_mfma_f32_16x16x32_bf16 v[116:119], v[136:139], v[204:207], 0
	v_mfma_f32_16x16x32_bf16 v[112:115], v[144:147], v[204:207], 0
	v_mfma_f32_16x16x32_bf16 v[104:107], v[136:139], v[212:215], 0
	v_mfma_f32_16x16x32_bf16 v[96:99], v[144:147], v[212:215], 0
	v_mfma_f32_16x16x32_bf16 v[84:87], v[136:139], v[220:223], 0
	v_mfma_f32_16x16x32_bf16 v[80:83], v[144:147], v[220:223], 0
	v_mfma_f32_16x16x32_bf16 v[124:127], v[140:143], v[200:203], v[124:127]
	v_mfma_f32_16x16x32_bf16 v[120:123], v[148:151], v[200:203], v[120:123]
	v_mfma_f32_16x16x32_bf16 v[116:119], v[140:143], v[208:211], v[116:119]
	v_mfma_f32_16x16x32_bf16 v[112:115], v[148:151], v[208:211], v[112:115]
	v_mfma_f32_16x16x32_bf16 v[104:107], v[140:143], v[216:219], v[104:107]
	v_mfma_f32_16x16x32_bf16 v[96:99], v[148:151], v[216:219], v[96:99]
	v_mfma_f32_16x16x32_bf16 v[84:87], v[140:143], v[224:227], v[84:87]
	v_mfma_f32_16x16x32_bf16 v[80:83], v[148:151], v[224:227], v[80:83]
	s_setprio 0
	s_setprio 1
	v_mfma_f32_16x16x32_bf16 v[108:111], v[180:183], v[196:199], 0
	v_mfma_f32_16x16x32_bf16 v[100:103], v[188:191], v[196:199], 0
	v_mfma_f32_16x16x32_bf16 v[92:95], v[180:183], v[204:207], 0
	v_mfma_f32_16x16x32_bf16 v[88:91], v[188:191], v[204:207], 0
	v_mfma_f32_16x16x32_bf16 v[76:79], v[180:183], v[212:215], 0
	v_mfma_f32_16x16x32_bf16 v[72:75], v[188:191], v[212:215], 0
	v_mfma_f32_16x16x32_bf16 v[68:71], v[180:183], v[220:223], 0
	v_mfma_f32_16x16x32_bf16 v[64:67], v[188:191], v[220:223], 0
	v_mfma_f32_16x16x32_bf16 v[108:111], v[184:187], v[200:203], v[108:111]
	v_mfma_f32_16x16x32_bf16 v[100:103], v[192:195], v[200:203], v[100:103]
	v_mfma_f32_16x16x32_bf16 v[92:95], v[184:187], v[208:211], v[92:95]
	v_mfma_f32_16x16x32_bf16 v[88:91], v[192:195], v[208:211], v[88:91]
	v_mfma_f32_16x16x32_bf16 v[76:79], v[184:187], v[216:219], v[76:79]
	v_mfma_f32_16x16x32_bf16 v[72:75], v[192:195], v[216:219], v[72:75]
	v_mfma_f32_16x16x32_bf16 v[68:71], v[184:187], v[224:227], v[68:71]
	v_mfma_f32_16x16x32_bf16 v[64:67], v[192:195], v[224:227], v[64:67]
	s_barrier
	s_setprio 0
	v_lshl_add_u64 v[234:235], v[134:135], 0, s[28:29]
	s_add_i32 s53, s48, s38
	v_lshl_add_u64 v[228:229], v[234:235], 0, s[12:13]
	s_mov_b32 m0, s53
	v_lshl_add_u64 v[236:237], v[132:133], 0, s[28:29]
	s_add_i32 s56, s53, 0x2000
	ds_read_b128 v[196:199], v179 offset:16384
	ds_read_b128 v[200:203], v179 offset:17408
	global_load_lds_dwordx4 v[228:229], off
	v_lshl_add_u64 v[228:229], v[236:237], 0, s[12:13]
	s_mov_b32 m0, s56
	s_add_i32 s57, s49, s38
	ds_read_b128 v[204:207], v179 offset:18432
	ds_read_b128 v[208:211], v179 offset:19456
	global_load_lds_dwordx4 v[228:229], off
	v_lshl_add_u64 v[228:229], v[234:235], 0, s[14:15]
	s_mov_b32 m0, s57
	s_add_i32 s58, s57, 0x2000
	ds_read_b128 v[212:215], v179 offset:20480
	global_load_lds_dwordx4 v[228:229], off
	v_lshl_add_u64 v[228:229], v[236:237], 0, s[14:15]
	s_mov_b32 m0, s58
	ds_read_b128 v[216:219], v179 offset:21504
	global_load_lds_dwordx4 v[228:229], off
	v_lshl_add_u64 v[228:229], v[230:231], 0, s[12:13]
	s_mov_b32 m0, s39
	ds_read_b128 v[220:223], v179 offset:22528
	global_load_lds_dwordx4 v[228:229], off
	v_lshl_add_u64 v[228:229], v[232:233], 0, s[12:13]
	s_mov_b32 m0, s40
	ds_read_b128 v[224:227], v179 offset:23552
	global_load_lds_dwordx4 v[228:229], off
	s_waitcnt vmcnt(8)
	s_waitcnt lgkmcnt(0)
	s_setprio 1
	s_barrier
	v_mfma_f32_16x16x32_bf16 v[60:63], v[136:139], v[196:199], 0
	v_mfma_f32_16x16x32_bf16 v[56:59], v[144:147], v[196:199], 0
	v_mfma_f32_16x16x32_bf16 v[48:51], v[136:139], v[204:207], 0
	v_mfma_f32_16x16x32_bf16 v[40:43], v[144:147], v[204:207], 0
	v_mfma_f32_16x16x32_bf16 v[32:35], v[136:139], v[212:215], 0
	v_mfma_f32_16x16x32_bf16 v[24:27], v[144:147], v[212:215], 0
	v_mfma_f32_16x16x32_bf16 v[16:19], v[136:139], v[220:223], 0
	v_mfma_f32_16x16x32_bf16 v[8:11], v[144:147], v[220:223], 0
	v_mfma_f32_16x16x32_bf16 v[60:63], v[140:143], v[200:203], v[60:63]
	v_mfma_f32_16x16x32_bf16 v[56:59], v[148:151], v[200:203], v[56:59]
	v_mfma_f32_16x16x32_bf16 v[48:51], v[140:143], v[208:211], v[48:51]
	v_mfma_f32_16x16x32_bf16 v[40:43], v[148:151], v[208:211], v[40:43]
	v_mfma_f32_16x16x32_bf16 v[32:35], v[140:143], v[216:219], v[32:35]
	v_mfma_f32_16x16x32_bf16 v[24:27], v[148:151], v[216:219], v[24:27]
	v_mfma_f32_16x16x32_bf16 v[16:19], v[140:143], v[224:227], v[16:19]
	v_mfma_f32_16x16x32_bf16 v[8:11], v[148:151], v[224:227], v[8:11]
	s_setprio 0
	s_setprio 1
	v_mfma_f32_16x16x32_bf16 v[52:55], v[180:183], v[196:199], 0
	v_mfma_f32_16x16x32_bf16 v[44:47], v[188:191], v[196:199], 0
	v_mfma_f32_16x16x32_bf16 v[36:39], v[180:183], v[204:207], 0
	v_mfma_f32_16x16x32_bf16 v[28:31], v[188:191], v[204:207], 0
	v_mfma_f32_16x16x32_bf16 v[20:23], v[180:183], v[212:215], 0
	v_mfma_f32_16x16x32_bf16 v[12:15], v[188:191], v[212:215], 0
	v_mfma_f32_16x16x32_bf16 v[4:7], v[180:183], v[220:223], 0
	v_mfma_f32_16x16x32_bf16 v[0:3], v[188:191], v[220:223], 0
	v_mfma_f32_16x16x32_bf16 v[52:55], v[184:187], v[200:203], v[52:55]
	v_mfma_f32_16x16x32_bf16 v[44:47], v[192:195], v[200:203], v[44:47]
	v_mfma_f32_16x16x32_bf16 v[36:39], v[184:187], v[208:211], v[36:39]
	v_mfma_f32_16x16x32_bf16 v[28:31], v[192:195], v[208:211], v[28:31]
	v_mfma_f32_16x16x32_bf16 v[20:23], v[184:187], v[216:219], v[20:23]
	v_mfma_f32_16x16x32_bf16 v[12:15], v[192:195], v[216:219], v[12:15]
	v_mfma_f32_16x16x32_bf16 v[4:7], v[184:187], v[224:227], v[4:7]
	v_mfma_f32_16x16x32_bf16 v[0:3], v[192:195], v[224:227], v[0:3]
	s_barrier
	s_setprio 0
	s_branch .Lpk1350_seg3
.LBB0_1350:
	ds_read_b128 v[136:139], v177
	ds_read_b128 v[140:143], v177 offset:1024
	ds_read_b128 v[144:147], v177 offset:2048
	ds_read_b128 v[148:151], v177 offset:3072
	ds_read_b128 v[180:183], v178
	ds_read_b128 v[184:187], v178 offset:1024
	ds_read_b128 v[188:191], v178 offset:2048
	ds_read_b128 v[192:195], v178 offset:3072
	v_lshl_add_u64 v[230:231], v[130:131], 0, s[28:29]
	s_mov_b32 m0, s50
	v_lshl_add_u64 v[228:229], v[230:231], 0, s[8:9]
	v_lshl_add_u64 v[232:233], v[128:129], 0, s[28:29]
	ds_read_b128 v[196:199], v179
	ds_read_b128 v[200:203], v179 offset:1024
	ds_read_b128 v[204:207], v179 offset:2048
	ds_read_b128 v[208:211], v179 offset:3072
	ds_read_b128 v[212:215], v179 offset:4096
	ds_read_b128 v[216:219], v179 offset:5120
	ds_read_b128 v[220:223], v179 offset:6144
	ds_read_b128 v[224:227], v179 offset:7168
	global_load_lds_dwordx4 v[228:229], off
	v_lshl_add_u64 v[228:229], v[232:233], 0, s[8:9]
	s_mov_b32 m0, s51
	s_nop 0
	global_load_lds_dwordx4 v[228:229], off
	s_waitcnt vmcnt(8)
	s_waitcnt lgkmcnt(0)
	s_setprio 1
	s_barrier
	v_mfma_f32_16x16x32_bf16 v[124:127], v[136:139], v[196:199], v[124:127]
	v_mfma_f32_16x16x32_bf16 v[120:123], v[144:147], v[196:199], v[120:123]
	v_mfma_f32_16x16x32_bf16 v[116:119], v[136:139], v[204:207], v[116:119]
	v_mfma_f32_16x16x32_bf16 v[112:115], v[144:147], v[204:207], v[112:115]
	v_mfma_f32_16x16x32_bf16 v[104:107], v[136:139], v[212:215], v[104:107]
	v_mfma_f32_16x16x32_bf16 v[96:99], v[144:147], v[212:215], v[96:99]
	v_mfma_f32_16x16x32_bf16 v[84:87], v[136:139], v[220:223], v[84:87]
	v_mfma_f32_16x16x32_bf16 v[80:83], v[144:147], v[220:223], v[80:83]
	v_mfma_f32_16x16x32_bf16 v[124:127], v[140:143], v[200:203], v[124:127]
	v_mfma_f32_16x16x32_bf16 v[120:123], v[148:151], v[200:203], v[120:123]
	v_mfma_f32_16x16x32_bf16 v[116:119], v[140:143], v[208:211], v[116:119]
	v_mfma_f32_16x16x32_bf16 v[112:115], v[148:151], v[208:211], v[112:115]
	v_mfma_f32_16x16x32_bf16 v[104:107], v[140:143], v[216:219], v[104:107]
	v_mfma_f32_16x16x32_bf16 v[96:99], v[148:151], v[216:219], v[96:99]
	v_mfma_f32_16x16x32_bf16 v[84:87], v[140:143], v[224:227], v[84:87]
	v_mfma_f32_16x16x32_bf16 v[80:83], v[148:151], v[224:227], v[80:83]
	s_setprio 0
	s_setprio 1
	v_mfma_f32_16x16x32_bf16 v[108:111], v[180:183], v[196:199], v[108:111]
	v_mfma_f32_16x16x32_bf16 v[100:103], v[188:191], v[196:199], v[100:103]
	v_mfma_f32_16x16x32_bf16 v[92:95], v[180:183], v[204:207], v[92:95]
	v_mfma_f32_16x16x32_bf16 v[88:91], v[188:191], v[204:207], v[88:91]
	v_mfma_f32_16x16x32_bf16 v[76:79], v[180:183], v[212:215], v[76:79]
	v_mfma_f32_16x16x32_bf16 v[72:75], v[188:191], v[212:215], v[72:75]
	v_mfma_f32_16x16x32_bf16 v[68:71], v[180:183], v[220:223], v[68:71]
	v_mfma_f32_16x16x32_bf16 v[64:67], v[188:191], v[220:223], v[64:67]
	v_mfma_f32_16x16x32_bf16 v[108:111], v[184:187], v[200:203], v[108:111]
	v_mfma_f32_16x16x32_bf16 v[100:103], v[192:195], v[200:203], v[100:103]
	v_mfma_f32_16x16x32_bf16 v[92:95], v[184:187], v[208:211], v[92:95]
	v_mfma_f32_16x16x32_bf16 v[88:91], v[192:195], v[208:211], v[88:91]
	v_mfma_f32_16x16x32_bf16 v[76:79], v[184:187], v[216:219], v[76:79]
	v_mfma_f32_16x16x32_bf16 v[72:75], v[192:195], v[216:219], v[72:75]
	v_mfma_f32_16x16x32_bf16 v[68:71], v[184:187], v[224:227], v[68:71]
	v_mfma_f32_16x16x32_bf16 v[64:67], v[192:195], v[224:227], v[64:67]
	s_barrier
	s_setprio 0
	v_lshl_add_u64 v[234:235], v[134:135], 0, s[28:29]
	s_add_i32 s53, s48, s38
	v_lshl_add_u64 v[228:229], v[234:235], 0, s[12:13]
	s_mov_b32 m0, s53
	v_lshl_add_u64 v[236:237], v[132:133], 0, s[28:29]
	s_add_i32 s56, s53, 0x2000
	ds_read_b128 v[196:199], v179 offset:16384
	ds_read_b128 v[200:203], v179 offset:17408
	global_load_lds_dwordx4 v[228:229], off
	v_lshl_add_u64 v[228:229], v[236:237], 0, s[12:13]
	s_mov_b32 m0, s56
	s_add_i32 s57, s49, s38
	ds_read_b128 v[204:207], v179 offset:18432
	ds_read_b128 v[208:211], v179 offset:19456
	global_load_lds_dwordx4 v[228:229], off
	v_lshl_add_u64 v[228:229], v[234:235], 0, s[14:15]
	s_mov_b32 m0, s57
	s_add_i32 s58, s57, 0x2000
	ds_read_b128 v[212:215], v179 offset:20480
	global_load_lds_dwordx4 v[228:229], off
	v_lshl_add_u64 v[228:229], v[236:237], 0, s[14:15]
	s_mov_b32 m0, s58
	ds_read_b128 v[216:219], v179 offset:21504
	global_load_lds_dwordx4 v[228:229], off
	v_lshl_add_u64 v[228:229], v[230:231], 0, s[12:13]
	s_mov_b32 m0, s39
	ds_read_b128 v[220:223], v179 offset:22528
	global_load_lds_dwordx4 v[228:229], off
	v_lshl_add_u64 v[228:229], v[232:233], 0, s[12:13]
	s_mov_b32 m0, s40
	ds_read_b128 v[224:227], v179 offset:23552
	global_load_lds_dwordx4 v[228:229], off
	s_waitcnt vmcnt(8)
	s_waitcnt lgkmcnt(0)
	s_setprio 1
	s_barrier
	v_mfma_f32_16x16x32_bf16 v[60:63], v[136:139], v[196:199], v[60:63]
	v_mfma_f32_16x16x32_bf16 v[56:59], v[144:147], v[196:199], v[56:59]
	v_mfma_f32_16x16x32_bf16 v[48:51], v[136:139], v[204:207], v[48:51]
	v_mfma_f32_16x16x32_bf16 v[40:43], v[144:147], v[204:207], v[40:43]
	v_mfma_f32_16x16x32_bf16 v[32:35], v[136:139], v[212:215], v[32:35]
	v_mfma_f32_16x16x32_bf16 v[24:27], v[144:147], v[212:215], v[24:27]
	v_mfma_f32_16x16x32_bf16 v[16:19], v[136:139], v[220:223], v[16:19]
	v_mfma_f32_16x16x32_bf16 v[8:11], v[144:147], v[220:223], v[8:11]
	v_mfma_f32_16x16x32_bf16 v[60:63], v[140:143], v[200:203], v[60:63]
	v_mfma_f32_16x16x32_bf16 v[56:59], v[148:151], v[200:203], v[56:59]
	v_mfma_f32_16x16x32_bf16 v[48:51], v[140:143], v[208:211], v[48:51]
	v_mfma_f32_16x16x32_bf16 v[40:43], v[148:151], v[208:211], v[40:43]
	v_mfma_f32_16x16x32_bf16 v[32:35], v[140:143], v[216:219], v[32:35]
	v_mfma_f32_16x16x32_bf16 v[24:27], v[148:151], v[216:219], v[24:27]
	v_mfma_f32_16x16x32_bf16 v[16:19], v[140:143], v[224:227], v[16:19]
	v_mfma_f32_16x16x32_bf16 v[8:11], v[148:151], v[224:227], v[8:11]
	s_setprio 0
	s_setprio 1
	v_mfma_f32_16x16x32_bf16 v[52:55], v[180:183], v[196:199], v[52:55]
	v_mfma_f32_16x16x32_bf16 v[44:47], v[188:191], v[196:199], v[44:47]
	v_mfma_f32_16x16x32_bf16 v[36:39], v[180:183], v[204:207], v[36:39]
	v_mfma_f32_16x16x32_bf16 v[28:31], v[188:191], v[204:207], v[28:31]
	v_mfma_f32_16x16x32_bf16 v[20:23], v[180:183], v[212:215], v[20:23]
	v_mfma_f32_16x16x32_bf16 v[12:15], v[188:191], v[212:215], v[12:15]
	v_mfma_f32_16x16x32_bf16 v[4:7], v[180:183], v[220:223], v[4:7]
	v_mfma_f32_16x16x32_bf16 v[0:3], v[188:191], v[220:223], v[0:3]
	v_mfma_f32_16x16x32_bf16 v[52:55], v[184:187], v[200:203], v[52:55]
	v_mfma_f32_16x16x32_bf16 v[44:47], v[192:195], v[200:203], v[44:47]
	v_mfma_f32_16x16x32_bf16 v[36:39], v[184:187], v[208:211], v[36:39]
	v_mfma_f32_16x16x32_bf16 v[28:31], v[192:195], v[208:211], v[28:31]
	v_mfma_f32_16x16x32_bf16 v[20:23], v[184:187], v[216:219], v[20:23]
	v_mfma_f32_16x16x32_bf16 v[12:15], v[192:195], v[216:219], v[12:15]
	v_mfma_f32_16x16x32_bf16 v[4:7], v[184:187], v[224:227], v[4:7]
	v_mfma_f32_16x16x32_bf16 v[0:3], v[192:195], v[224:227], v[0:3]
	s_barrier
	s_setprio 0
.Lpk1350_seg3:
	s_add_i32 s59, 0, 0x18000
	s_add_i32 s61, 0, 0x1c000
	v_add_u32_e32 v180, s59, v175
	v_add_u32_e32 v181, s61, v175
	ds_read_b128 v[136:139], v180
	ds_read_b128 v[140:143], v180 offset:1024
	ds_read_b128 v[144:147], v180 offset:2048
	ds_read_b128 v[148:151], v180 offset:3072
	ds_read_b128 v[182:185], v181
	ds_read_b128 v[186:189], v181 offset:1024
	ds_read_b128 v[190:193], v181 offset:2048
	ds_read_b128 v[194:197], v181 offset:3072
	s_mov_b32 m0, s41
	v_lshl_add_u64 v[238:239], v[230:231], 0, s[14:15]
	ds_read_b128 v[198:201], v179 offset:32768
	ds_read_b128 v[202:205], v179 offset:33792
	ds_read_b128 v[206:209], v179 offset:34816
	ds_read_b128 v[210:213], v179 offset:35840
	ds_read_b128 v[214:217], v179 offset:36864
	ds_read_b128 v[218:221], v179 offset:37888
	ds_read_b128 v[222:225], v179 offset:38912
	ds_read_b128 v[226:229], v179 offset:39936
	global_load_lds_dwordx4 v[238:239], off
	v_lshl_add_u64 v[238:239], v[232:233], 0, s[14:15]
	s_mov_b32 m0, s42
	s_nop 0
	global_load_lds_dwordx4 v[238:239], off
	s_waitcnt vmcnt(8)
	s_waitcnt lgkmcnt(0)
	s_setprio 1
	s_barrier
	v_mfma_f32_16x16x32_bf16 v[124:127], v[136:139], v[198:201], v[124:127]
	v_mfma_f32_16x16x32_bf16 v[120:123], v[144:147], v[198:201], v[120:123]
	v_mfma_f32_16x16x32_bf16 v[116:119], v[136:139], v[206:209], v[116:119]
	v_mfma_f32_16x16x32_bf16 v[112:115], v[144:147], v[206:209], v[112:115]
	v_mfma_f32_16x16x32_bf16 v[104:107], v[136:139], v[214:217], v[104:107]
	v_mfma_f32_16x16x32_bf16 v[96:99], v[144:147], v[214:217], v[96:99]
	v_mfma_f32_16x16x32_bf16 v[84:87], v[136:139], v[222:225], v[84:87]
	v_mfma_f32_16x16x32_bf16 v[80:83], v[144:147], v[222:225], v[80:83]
	v_mfma_f32_16x16x32_bf16 v[124:127], v[140:143], v[202:205], v[124:127]
	v_mfma_f32_16x16x32_bf16 v[120:123], v[148:151], v[202:205], v[120:123]
	v_mfma_f32_16x16x32_bf16 v[116:119], v[140:143], v[210:213], v[116:119]
	v_mfma_f32_16x16x32_bf16 v[112:115], v[148:151], v[210:213], v[112:115]
	v_mfma_f32_16x16x32_bf16 v[104:107], v[140:143], v[218:221], v[104:107]
	v_mfma_f32_16x16x32_bf16 v[96:99], v[148:151], v[218:221], v[96:99]
	v_mfma_f32_16x16x32_bf16 v[84:87], v[140:143], v[226:229], v[84:87]
	v_mfma_f32_16x16x32_bf16 v[80:83], v[148:151], v[226:229], v[80:83]
	s_setprio 0
	s_setprio 1
	v_mfma_f32_16x16x32_bf16 v[108:111], v[182:185], v[198:201], v[108:111]
	v_mfma_f32_16x16x32_bf16 v[100:103], v[190:193], v[198:201], v[100:103]
	v_mfma_f32_16x16x32_bf16 v[92:95], v[182:185], v[206:209], v[92:95]
	v_mfma_f32_16x16x32_bf16 v[88:91], v[190:193], v[206:209], v[88:91]
	v_mfma_f32_16x16x32_bf16 v[76:79], v[182:185], v[214:217], v[76:79]
	v_mfma_f32_16x16x32_bf16 v[72:75], v[190:193], v[214:217], v[72:75]
	v_mfma_f32_16x16x32_bf16 v[68:71], v[182:185], v[222:225], v[68:71]
	v_mfma_f32_16x16x32_bf16 v[64:67], v[190:193], v[222:225], v[64:67]
	v_mfma_f32_16x16x32_bf16 v[108:111], v[186:189], v[202:205], v[108:111]
	v_mfma_f32_16x16x32_bf16 v[100:103], v[194:197], v[202:205], v[100:103]
	v_mfma_f32_16x16x32_bf16 v[92:95], v[186:189], v[210:213], v[92:95]
	v_mfma_f32_16x16x32_bf16 v[88:91], v[194:197], v[210:213], v[88:91]
	v_mfma_f32_16x16x32_bf16 v[76:79], v[186:189], v[218:221], v[76:79]
	v_mfma_f32_16x16x32_bf16 v[72:75], v[194:197], v[218:221], v[72:75]
	v_mfma_f32_16x16x32_bf16 v[68:71], v[186:189], v[226:229], v[68:71]
	v_mfma_f32_16x16x32_bf16 v[64:67], v[194:197], v[226:229], v[64:67]
	s_barrier
	s_setprio 0
	s_add_i32 s59, s59, s38
	v_lshl_add_u64 v[238:239], v[234:235], 0, s[16:17]
	s_mov_b32 m0, s59
	s_add_i32 s60, s59, 0x2000
	ds_read_b128 v[198:201], v179 offset:49152
	ds_read_b128 v[202:205], v179 offset:50176
	global_load_lds_dwordx4 v[238:239], off
	v_lshl_add_u64 v[238:239], v[236:237], 0, s[16:17]
	s_mov_b32 m0, s60
	s_add_i32 s61, s61, s38
	ds_read_b128 v[206:209], v179 offset:51200
	ds_read_b128 v[210:213], v179 offset:52224
	global_load_lds_dwordx4 v[238:239], off
	v_lshl_add_u64 v[234:235], v[234:235], 0, s[18:19]
	s_mov_b32 m0, s61
	s_add_i32 s62, s61, 0x2000
	ds_read_b128 v[214:217], v179 offset:53248
	global_load_lds_dwordx4 v[234:235], off
	v_lshl_add_u64 v[234:235], v[236:237], 0, s[18:19]
	s_mov_b32 m0, s62
	v_lshl_add_u64 v[230:231], v[230:231], 0, s[16:17]
	ds_read_b128 v[218:221], v179 offset:54272
	global_load_lds_dwordx4 v[234:235], off
	s_mov_b32 m0, s44
	ds_read_b128 v[222:225], v179 offset:55296
	global_load_lds_dwordx4 v[230:231], off
	v_lshl_add_u64 v[230:231], v[232:233], 0, s[16:17]
	s_mov_b32 m0, s45
	ds_read_b128 v[226:229], v179 offset:56320
	global_load_lds_dwordx4 v[230:231], off
	s_waitcnt vmcnt(8)
	s_waitcnt lgkmcnt(0)
	s_setprio 1
	s_barrier
; __device__ __forceinline__ unsigned cvt_pk_bf16(float lo, float hi) { unsigned r; asm volatile("v_cvt_pk_bf16_f32 %0, %1, %2" : "=v"(r) : "v"(lo), "v"(hi)); return r; }
; __device__ __forceinline__ float bflo(unsigned w) { return __uint_as_float(w << 16); }
; __device__ __forceinline__ float bfhi(unsigned w) { return __uint_as_float(w & 0xffff0000u); }
;     __device__ __forceinline__ void scale(Acc& acc, const Unit& u, int wr, int wc, int fr, int fq, int pc, bool store) const {
;     ...
;         for (int ai = 0; ai < 2; ++ai) {
;             u32x4 g[4][2];
; #pragma unroll
;             for (int m = 0; m < 4; ++m) {
;                 const unsigned rowoff = (unsigned)(row0 + ai * HALF + m * 16) * (unsigned)(NIN * 2) + (unsigned)col0 * 2u;
; #pragma unroll
;                 for (int bj = 0; bj < 2; ++bj) g[m][bj] = *(const u32x4*)(Pb + (rowoff + (unsigned)((pc + bj * HALF) * 2)));
;             }
; #pragma unroll
;             for (int m = 0; m < 4; ++m) {
;                 const unsigned ooff = (unsigned)(row0 + ai * HALF + m * 16) * (unsigned)(ldo * 2) + (unsigned)col0 * 2u;
; #pragma unroll
;                 for (int bj = 0; bj < 2; ++bj) {
;                     const u32x4 gg = g[m][bj];
;                     const f32x4 s0 = (f32x4){bflo(gg.x), bfhi(gg.x), bflo(gg.y), bfhi(gg.y)}, s1 = (f32x4){bflo(gg.z), bfhi(gg.z), bflo(gg.w), bfhi(gg.w)};
;                     const f32x4 v0 = acc[ai][bj][m][0] * s0, v1 = acc[ai][bj][m][1] * s1;
;                     if (store) { u32x4 w; w.x = cvt_pk_bf16(v0[0], v0[1]); w.y = cvt_pk_bf16(v0[2], v0[3]); w.z = cvt_pk_bf16(v1[0], v1[1]); w.w = cvt_pk_bf16(v1[2], v1[3]); *(u32x4*)(Ob + (ooff + (unsigned)(bj * HALF * 2))) = w; }
;                     else { acc[ai][bj][m][0] = v0; acc[ai][bj][m][1] = v1; }
	v_mfma_f32_16x16x32_bf16 v[60:63], v[136:139], v[198:201], v[60:63]
	v_mfma_f32_16x16x32_bf16 v[56:59], v[144:147], v[198:201], v[56:59]
	v_mfma_f32_16x16x32_bf16 v[48:51], v[136:139], v[206:209], v[48:51]
	v_mfma_f32_16x16x32_bf16 v[40:43], v[144:147], v[206:209], v[40:43]
	v_mfma_f32_16x16x32_bf16 v[32:35], v[136:139], v[214:217], v[32:35]
	v_mfma_f32_16x16x32_bf16 v[24:27], v[144:147], v[214:217], v[24:27]
	v_mfma_f32_16x16x32_bf16 v[16:19], v[136:139], v[222:225], v[16:19]
	v_mfma_f32_16x16x32_bf16 v[8:11], v[144:147], v[222:225], v[8:11]
	v_mfma_f32_16x16x32_bf16 v[60:63], v[140:143], v[202:205], v[60:63]
	v_mfma_f32_16x16x32_bf16 v[56:59], v[148:151], v[202:205], v[56:59]
	v_mfma_f32_16x16x32_bf16 v[48:51], v[140:143], v[210:213], v[48:51]
	v_mfma_f32_16x16x32_bf16 v[40:43], v[148:151], v[210:213], v[40:43]
	v_mfma_f32_16x16x32_bf16 v[32:35], v[140:143], v[218:221], v[32:35]
	v_mfma_f32_16x16x32_bf16 v[24:27], v[148:151], v[218:221], v[24:27]
	v_mfma_f32_16x16x32_bf16 v[16:19], v[140:143], v[226:229], v[16:19]
	v_mfma_f32_16x16x32_bf16 v[8:11], v[148:151], v[226:229], v[8:11]
	s_setprio 0
	s_setprio 1
	v_mfma_f32_16x16x32_bf16 v[52:55], v[182:185], v[198:201], v[52:55]
	v_mfma_f32_16x16x32_bf16 v[44:47], v[190:193], v[198:201], v[44:47]
	v_mfma_f32_16x16x32_bf16 v[36:39], v[182:185], v[206:209], v[36:39]
	v_mfma_f32_16x16x32_bf16 v[28:31], v[190:193], v[206:209], v[28:31]
	v_mfma_f32_16x16x32_bf16 v[20:23], v[182:185], v[214:217], v[20:23]
	v_mfma_f32_16x16x32_bf16 v[12:15], v[190:193], v[214:217], v[12:15]
	v_mfma_f32_16x16x32_bf16 v[4:7], v[182:185], v[222:225], v[4:7]
	v_mfma_f32_16x16x32_bf16 v[0:3], v[190:193], v[222:225], v[0:3]
	v_mfma_f32_16x16x32_bf16 v[52:55], v[186:189], v[202:205], v[52:55]
	v_mfma_f32_16x16x32_bf16 v[44:47], v[194:197], v[202:205], v[44:47]
	v_mfma_f32_16x16x32_bf16 v[36:39], v[186:189], v[210:213], v[36:39]
	v_mfma_f32_16x16x32_bf16 v[28:31], v[194:197], v[210:213], v[28:31]
	v_mfma_f32_16x16x32_bf16 v[20:23], v[186:189], v[218:221], v[20:23]
	v_mfma_f32_16x16x32_bf16 v[12:15], v[194:197], v[218:221], v[12:15]
	v_mfma_f32_16x16x32_bf16 v[4:7], v[186:189], v[226:229], v[4:7]
	v_mfma_f32_16x16x32_bf16 v[0:3], v[194:197], v[226:229], v[0:3]
	s_barrier
	s_setprio 0
	s_add_i32 s21, s21, 2
	s_add_u32 s28, s28, 0x100
	s_addc_u32 s29, s29, 0
	s_cmp_gt_u32 s21, 5
	s_cbranch_scc0 .LBB0_1350
	v_lshl_add_u32 v182, s34, 8, v174
	v_lshl_or_b32 v183, s23, 8, v176
	v_mov_b32_e32 v128, v182
	v_mov_b32_e32 v129, v183
	s_ashr_i32 s23, s22, 31
	v_mul_lo_u32 v128, v128, s52
	v_lshl_add_u32 v228, v129, 1, v128
	v_add_u32_e32 v128, 0x1200, v228
	v_add_u32_e32 v140, 0x49200, v228
	global_load_dwordx4 v[148:151], v128, s[68:69]
	global_load_dwordx4 v[144:147], v140, s[68:69]
	v_add_u32_e32 v128, 0x1300, v228
	v_add_u32_e32 v140, 0x49300, v228
	global_load_dwordx4 v[136:139], v128, s[68:69]
	v_add_u32_e32 v184, 0x6d200, v228
	global_load_dwordx4 v[140:143], v140, s[68:69]
	v_add_u32_e32 v128, 0x25200, v228
	global_load_dwordx4 v[132:135], v128, s[68:69]
	v_add_u32_e32 v128, 0x25300, v228
	global_load_dwordx4 v[128:131], v128, s[68:69]
	v_add_u32_e32 v188, 0x6d300, v228
	global_load_dwordx4 v[184:187], v184, s[68:69]
	s_nop 0
	global_load_dwordx4 v[188:191], v188, s[68:69]
	v_add_u32_e32 v192, 0x121200, v228
	v_add_u32_e32 v196, 0x121300, v228
	global_load_dwordx4 v[192:195], v192, s[68:69]
	s_nop 0
	global_load_dwordx4 v[196:199], v196, s[68:69]
	s_ashr_i32 s21, s20, 31
	s_lshl_b64 s[28:29], s[22:23], 19
	s_lshl_b64 s[30:31], s[20:21], 19
	s_add_u32 s28, s1, s28
	s_addc_u32 s29, s33, s29
	s_add_u32 s30, s36, s30
	s_addc_u32 s31, s37, s31
	s_and_b64 s[34:35], s[2:3], exec
	s_cselect_b32 s21, s29, s27
	s_cselect_b32 s23, s28, s26
	s_cselect_b32 s63, s31, s25
	s_cselect_b32 s66, s30, s24
	s_add_u32 s26, s26, 0x40480
	s_addc_u32 s27, s27, 0
	s_add_u32 s67, s24, 0x500
	s_addc_u32 s70, s25, 0
	s_mov_b32 s71, 6
	s_waitcnt vmcnt(0)
	v_lshlrev_b32_e32 v200, 16, v148
	v_and_b32_e32 v201, 0xffff0000, v148
	v_lshlrev_b32_e32 v148, 16, v149
	v_and_b32_e32 v149, 0xffff0000, v149
	v_lshlrev_b32_e32 v204, 16, v136
	v_and_b32_e32 v205, 0xffff0000, v136
	v_lshlrev_b32_e32 v206, 16, v137
	v_and_b32_e32 v207, 0xffff0000, v137
	v_lshlrev_b32_e32 v202, 16, v150
	v_and_b32_e32 v203, 0xffff0000, v150
	v_lshlrev_b32_e32 v224, 16, v130
	v_and_b32_e32 v225, 0xffff0000, v130
	v_lshlrev_b32_e32 v226, 16, v131
	v_and_b32_e32 v227, 0xffff0000, v131
	v_lshlrev_b32_e32 v150, 16, v151
	v_and_b32_e32 v151, 0xffff0000, v151
	v_lshlrev_b32_e32 v208, 16, v138
	v_and_b32_e32 v209, 0xffff0000, v138
	v_lshlrev_b32_e32 v210, 16, v139
	v_and_b32_e32 v211, 0xffff0000, v139
	v_pk_mul_f32 v[138:139], v[126:127], v[148:149]
	v_pk_mul_f32 v[136:137], v[124:125], v[200:201]
	v_pk_mul_f32 v[126:127], v[110:111], v[206:207]
	v_pk_mul_f32 v[124:125], v[108:109], v[204:205]
	v_pk_mul_f32 v[110:111], v[90:91], v[226:227]
	v_pk_mul_f32 v[108:109], v[88:89], v[224:225]
	v_lshlrev_b32_e32 v88, 16, v144
	v_and_b32_e32 v89, 0xffff0000, v144
	v_add_u32_e32 v91, 0x145200, v228
	v_lshlrev_b32_e32 v212, 16, v132
	v_and_b32_e32 v213, 0xffff0000, v132
	v_lshlrev_b32_e32 v214, 16, v133
	v_and_b32_e32 v215, 0xffff0000, v133
	v_lshlrev_b32_e32 v216, 16, v134
	v_and_b32_e32 v217, 0xffff0000, v134
	v_lshlrev_b32_e32 v218, 16, v135
	v_and_b32_e32 v219, 0xffff0000, v135
	v_lshlrev_b32_e32 v222, 16, v129
	v_and_b32_e32 v223, 0xffff0000, v129
	v_pk_mul_f32 v[134:135], v[122:123], v[150:151]
	v_pk_mul_f32 v[132:133], v[120:121], v[202:203]
	v_pk_mul_f32 v[120:121], v[100:101], v[208:209]
	v_lshlrev_b32_e32 v90, 16, v145
	global_load_dwordx4 v[148:151], v91, s[68:69]
	v_and_b32_e32 v91, 0xffff0000, v145
; __device__ __forceinline__ unsigned cvt_pk_bf16(float lo, float hi) { unsigned r; asm volatile("v_cvt_pk_bf16_f32 %0, %1, %2" : "=v"(r) : "v"(lo), "v"(hi)); return r; }
; __device__ __forceinline__ float bflo(unsigned w) { return __uint_as_float(w << 16); }
; __device__ __forceinline__ float bfhi(unsigned w) { return __uint_as_float(w & 0xffff0000u); }
;     __device__ __forceinline__ void scale(Acc& acc, const Unit& u, int wr, int wc, int fr, int fq, int pc, bool store) const {
;     ...
;             for (int m = 0; m < 4; ++m) {
;                 const unsigned ooff = (unsigned)(row0 + ai * HALF + m * 16) * (unsigned)(ldo * 2) + (unsigned)col0 * 2u;
; #pragma unroll
;                 for (int bj = 0; bj < 2; ++bj) {
;                     const u32x4 gg = g[m][bj];
;                     const f32x4 s0 = (f32x4){bflo(gg.x), bfhi(gg.x), bflo(gg.y), bfhi(gg.y)}, s1 = (f32x4){bflo(gg.z), bfhi(gg.z), bflo(gg.w), bfhi(gg.w)};
;                     const f32x4 v0 = acc[ai][bj][m][0] * s0, v1 = acc[ai][bj][m][1] * s1;
;                     if (store) { u32x4 w; w.x = cvt_pk_bf16(v0[0], v0[1]); w.y = cvt_pk_bf16(v0[2], v0[3]); w.z = cvt_pk_bf16(v1[0], v1[1]); w.w = cvt_pk_bf16(v1[2], v1[3]); *(u32x4*)(Ob + (ooff + (unsigned)(bj * HALF * 2))) = w; }
;                     else { acc[ai][bj][m][0] = v0; acc[ai][bj][m][1] = v1; }
	v_pk_mul_f32 v[100:101], v[104:105], v[88:89]
	v_add_u32_e32 v89, 0x145300, v228
	v_pk_mul_f32 v[122:123], v[102:103], v[210:211]
	v_pk_mul_f32 v[130:131], v[118:119], v[214:215]
	v_pk_mul_f32 v[118:119], v[114:115], v[218:219]
	v_pk_mul_f32 v[114:115], v[94:95], v[222:223]
	v_lshlrev_b32_e32 v94, 16, v147
	v_and_b32_e32 v95, 0xffff0000, v147
	v_pk_mul_f32 v[102:103], v[106:107], v[90:91]
	v_lshlrev_b32_e32 v88, 16, v140
	global_load_dwordx4 v[104:107], v89, s[68:69]
	v_and_b32_e32 v89, 0xffff0000, v140
	v_lshlrev_b32_e32 v90, 16, v141
	v_and_b32_e32 v91, 0xffff0000, v141
	v_lshlrev_b32_e32 v140, 16, v143
	v_and_b32_e32 v141, 0xffff0000, v143
	v_lshlrev_b32_e32 v220, 16, v128
	v_and_b32_e32 v221, 0xffff0000, v128
	v_pk_mul_f32 v[98:99], v[98:99], v[94:95]
	v_pk_mul_f32 v[94:95], v[78:79], v[90:91]
	v_pk_mul_f32 v[90:91], v[74:75], v[140:141]
	v_add_u32_e32 v74, 0x169200, v228
	v_pk_mul_f32 v[128:129], v[116:117], v[212:213]
	v_pk_mul_f32 v[116:117], v[112:113], v[216:217]
	v_pk_mul_f32 v[112:113], v[92:93], v[220:221]
	v_lshlrev_b32_e32 v92, 16, v146
	v_and_b32_e32 v93, 0xffff0000, v146
	v_lshlrev_b32_e32 v144, 16, v142
	v_and_b32_e32 v145, 0xffff0000, v142
	global_load_dwordx4 v[140:143], v74, s[68:69]
	v_lshlrev_b32_e32 v74, 16, v185
	v_and_b32_e32 v75, 0xffff0000, v185
	v_pk_mul_f32 v[96:97], v[96:97], v[92:93]
	v_pk_mul_f32 v[92:93], v[76:77], v[88:89]
	v_pk_mul_f32 v[88:89], v[72:73], v[144:145]
	v_lshlrev_b32_e32 v72, 16, v184
	v_and_b32_e32 v73, 0xffff0000, v184
	v_lshlrev_b32_e32 v76, 16, v186
	v_and_b32_e32 v77, 0xffff0000, v186
	v_pk_mul_f32 v[86:87], v[86:87], v[74:75]
	v_add_u32_e32 v74, 0x169300, v228
	v_lshlrev_b32_e32 v78, 16, v187
	v_and_b32_e32 v79, 0xffff0000, v187
	global_load_dwordx4 v[144:147], v74, s[68:69]
	v_pk_mul_f32 v[84:85], v[84:85], v[72:73]
	v_pk_mul_f32 v[76:77], v[80:81], v[76:77]
	v_lshlrev_b32_e32 v72, 16, v188
	v_and_b32_e32 v73, 0xffff0000, v188
	v_lshlrev_b32_e32 v184, 16, v190
	v_and_b32_e32 v185, 0xffff0000, v190
	v_add_u32_e32 v80, 0x18d200, v228
	v_pk_mul_f32 v[78:79], v[82:83], v[78:79]
	v_lshlrev_b32_e32 v74, 16, v189
	v_and_b32_e32 v75, 0xffff0000, v189
	v_lshlrev_b32_e32 v186, 16, v191
	global_load_dwordx4 v[80:83], v80, s[68:69]
	v_and_b32_e32 v187, 0xffff0000, v191
	v_pk_mul_f32 v[72:73], v[68:69], v[72:73]
	v_pk_mul_f32 v[68:69], v[64:65], v[184:185]
	v_add_u32_e32 v64, 0x18d300, v228
	v_pk_mul_f32 v[74:75], v[70:71], v[74:75]
	v_pk_mul_f32 v[70:71], v[66:67], v[186:187]
	global_load_dwordx4 v[184:187], v64, s[68:69]
	v_lshlrev_b32_e32 v64, 16, v192
	v_and_b32_e32 v65, 0xffff0000, v192
	v_lshlrev_b32_e32 v66, 16, v193
	v_and_b32_e32 v67, 0xffff0000, v193
	v_lshlrev_b32_e32 v188, 16, v194
	v_and_b32_e32 v189, 0xffff0000, v194
	v_lshlrev_b32_e32 v190, 16, v195
	v_and_b32_e32 v191, 0xffff0000, v195
	v_pk_mul_f32 v[62:63], v[62:63], v[66:67]
	v_pk_mul_f32 v[60:61], v[60:61], v[64:65]
	v_pk_mul_f32 v[66:67], v[58:59], v[190:191]
	v_pk_mul_f32 v[64:65], v[56:57], v[188:189]
	v_lshlrev_b32_e32 v56, 16, v196
	v_and_b32_e32 v57, 0xffff0000, v196
	v_lshlrev_b32_e32 v58, 16, v197
	v_and_b32_e32 v59, 0xffff0000, v197
	v_lshlrev_b32_e32 v188, 16, v198
	v_and_b32_e32 v189, 0xffff0000, v198
	v_lshlrev_b32_e32 v190, 16, v199
	v_and_b32_e32 v191, 0xffff0000, v199
	v_pk_mul_f32 v[54:55], v[54:55], v[58:59]
	v_pk_mul_f32 v[52:53], v[52:53], v[56:57]
	v_pk_mul_f32 v[58:59], v[46:47], v[190:191]
	v_pk_mul_f32 v[56:57], v[44:45], v[188:189]
	s_waitcnt vmcnt(5)
	v_lshlrev_b32_e32 v44, 16, v148
	v_and_b32_e32 v45, 0xffff0000, v148
	v_lshlrev_b32_e32 v46, 16, v149
	v_and_b32_e32 v47, 0xffff0000, v149
	v_lshlrev_b32_e32 v148, 16, v150
	v_and_b32_e32 v149, 0xffff0000, v150
	v_lshlrev_b32_e32 v150, 16, v151
	v_and_b32_e32 v151, 0xffff0000, v151
	v_pk_mul_f32 v[46:47], v[50:51], v[46:47]
	v_pk_mul_f32 v[44:45], v[48:49], v[44:45]
	v_pk_mul_f32 v[50:51], v[42:43], v[150:151]
	v_pk_mul_f32 v[48:49], v[40:41], v[148:149]
	s_waitcnt vmcnt(4)
	v_lshlrev_b32_e32 v40, 16, v104
	v_and_b32_e32 v41, 0xffff0000, v104
	v_lshlrev_b32_e32 v42, 16, v105
	v_and_b32_e32 v43, 0xffff0000, v105
	v_lshlrev_b32_e32 v104, 16, v106
	v_and_b32_e32 v105, 0xffff0000, v106
	v_lshlrev_b32_e32 v106, 16, v107
	v_and_b32_e32 v107, 0xffff0000, v107
	v_pk_mul_f32 v[38:39], v[38:39], v[42:43]
	v_pk_mul_f32 v[36:37], v[36:37], v[40:41]
	v_pk_mul_f32 v[42:43], v[30:31], v[106:107]
	v_pk_mul_f32 v[40:41], v[28:29], v[104:105]
	s_waitcnt vmcnt(3)
	v_lshlrev_b32_e32 v28, 16, v140
	v_and_b32_e32 v29, 0xffff0000, v140
	v_lshlrev_b32_e32 v30, 16, v141
	v_and_b32_e32 v31, 0xffff0000, v141
	v_lshlrev_b32_e32 v104, 16, v142
	v_and_b32_e32 v105, 0xffff0000, v142
	v_lshlrev_b32_e32 v106, 16, v143
	v_and_b32_e32 v107, 0xffff0000, v143
	v_pk_mul_f32 v[30:31], v[34:35], v[30:31]
	v_pk_mul_f32 v[28:29], v[32:33], v[28:29]
	v_pk_mul_f32 v[34:35], v[26:27], v[106:107]
	v_pk_mul_f32 v[32:33], v[24:25], v[104:105]
	s_waitcnt vmcnt(2)
	v_lshlrev_b32_e32 v24, 16, v144
	v_and_b32_e32 v25, 0xffff0000, v144
	v_lshlrev_b32_e32 v26, 16, v145
	v_and_b32_e32 v27, 0xffff0000, v145
	v_lshlrev_b32_e32 v104, 16, v146
	v_and_b32_e32 v105, 0xffff0000, v146
	v_lshlrev_b32_e32 v106, 16, v147
	v_and_b32_e32 v107, 0xffff0000, v147
	v_pk_mul_f32 v[22:23], v[22:23], v[26:27]
	v_pk_mul_f32 v[20:21], v[20:21], v[24:25]
	v_pk_mul_f32 v[26:27], v[14:15], v[106:107]
	v_pk_mul_f32 v[24:25], v[12:13], v[104:105]
	s_waitcnt vmcnt(1)
	v_lshlrev_b32_e32 v12, 16, v80
	v_and_b32_e32 v13, 0xffff0000, v80
	v_lshlrev_b32_e32 v14, 16, v81
	v_and_b32_e32 v15, 0xffff0000, v81
	v_lshlrev_b32_e32 v80, 16, v82
	v_and_b32_e32 v81, 0xffff0000, v82
	v_lshlrev_b32_e32 v82, 16, v83
	v_and_b32_e32 v83, 0xffff0000, v83
	v_pk_mul_f32 v[14:15], v[18:19], v[14:15]
	v_pk_mul_f32 v[12:13], v[16:17], v[12:13]
	v_pk_mul_f32 v[10:11], v[10:11], v[82:83]
	v_pk_mul_f32 v[8:9], v[8:9], v[80:81]
	s_waitcnt vmcnt(0)
	v_lshlrev_b32_e32 v16, 16, v184
	v_and_b32_e32 v17, 0xffff0000, v184
	v_lshlrev_b32_e32 v18, 16, v185
	v_and_b32_e32 v19, 0xffff0000, v185
	v_lshlrev_b32_e32 v80, 16, v186
	v_and_b32_e32 v81, 0xffff0000, v186
	v_lshlrev_b32_e32 v82, 16, v187
	v_and_b32_e32 v83, 0xffff0000, v187
	v_pk_mul_f32 v[6:7], v[6:7], v[18:19]
	v_pk_mul_f32 v[4:5], v[4:5], v[16:17]
	v_pk_mul_f32 v[2:3], v[2:3], v[82:83]
	v_pk_mul_f32 v[0:1], v[0:1], v[80:81]
.LBB0_1352:
	ds_read_b128 v[16:19], v177
	ds_read_b128 v[80:83], v177 offset:1024
	ds_read_b128 v[104:107], v177 offset:2048
	ds_read_b128 v[140:143], v177 offset:3072
	ds_read_b128 v[144:147], v178
	ds_read_b128 v[148:151], v178 offset:1024
	ds_read_b128 v[184:187], v178 offset:2048
	ds_read_b128 v[188:191], v178 offset:3072
	s_add_u32 s24, s26, 0xfffc0080
	s_addc_u32 s25, s27, -1
	s_cmp_eq_u32 s71, 12
	s_cselect_b32 s35, s21, s25
	s_cselect_b32 s34, s23, s24
	s_cselect_b32 s25, s63, s70
	s_cselect_b32 s24, s66, s67
	s_mov_b32 m0, s50
	v_lshl_add_u64 v[224:225], s[26:27], 0, v[164:165]
	ds_read_b128 v[192:195], v179
	ds_read_b128 v[196:199], v179 offset:1024
	ds_read_b128 v[200:203], v179 offset:2048
	ds_read_b128 v[204:207], v179 offset:3072
	ds_read_b128 v[208:211], v179 offset:4096
	ds_read_b128 v[212:215], v179 offset:5120
	ds_read_b128 v[216:219], v179 offset:6144
	ds_read_b128 v[220:223], v179 offset:7168
	global_load_lds_dwordx4 v[224:225], off
	v_lshl_add_u64 v[224:225], s[26:27], 0, v[162:163]
	s_mov_b32 m0, s51
	s_nop 0
	global_load_lds_dwordx4 v[224:225], off
	s_waitcnt vmcnt(8)
	s_waitcnt lgkmcnt(0)
	s_setprio 1
	s_barrier
	v_mfma_f32_16x16x32_bf16 v[136:139], v[16:19], v[192:195], v[136:139]
	v_mfma_f32_16x16x32_bf16 v[132:135], v[104:107], v[192:195], v[132:135]
	v_mfma_f32_16x16x32_bf16 v[128:131], v[16:19], v[200:203], v[128:131]
	v_mfma_f32_16x16x32_bf16 v[116:119], v[104:107], v[200:203], v[116:119]
	v_mfma_f32_16x16x32_bf16 v[100:103], v[16:19], v[208:211], v[100:103]
	v_mfma_f32_16x16x32_bf16 v[96:99], v[104:107], v[208:211], v[96:99]
	v_mfma_f32_16x16x32_bf16 v[84:87], v[16:19], v[216:219], v[84:87]
	v_mfma_f32_16x16x32_bf16 v[76:79], v[104:107], v[216:219], v[76:79]
	v_mfma_f32_16x16x32_bf16 v[136:139], v[80:83], v[196:199], v[136:139]
	v_mfma_f32_16x16x32_bf16 v[132:135], v[140:143], v[196:199], v[132:135]
	v_mfma_f32_16x16x32_bf16 v[128:131], v[80:83], v[204:207], v[128:131]
	v_mfma_f32_16x16x32_bf16 v[116:119], v[140:143], v[204:207], v[116:119]
	v_mfma_f32_16x16x32_bf16 v[100:103], v[80:83], v[212:215], v[100:103]
	v_mfma_f32_16x16x32_bf16 v[96:99], v[140:143], v[212:215], v[96:99]
	v_mfma_f32_16x16x32_bf16 v[84:87], v[80:83], v[220:223], v[84:87]
	v_mfma_f32_16x16x32_bf16 v[76:79], v[140:143], v[220:223], v[76:79]
	s_setprio 0
	s_setprio 1
	v_mfma_f32_16x16x32_bf16 v[124:127], v[144:147], v[192:195], v[124:127]
	v_mfma_f32_16x16x32_bf16 v[120:123], v[184:187], v[192:195], v[120:123]
	v_mfma_f32_16x16x32_bf16 v[112:115], v[144:147], v[200:203], v[112:115]
	v_mfma_f32_16x16x32_bf16 v[108:111], v[184:187], v[200:203], v[108:111]
	v_mfma_f32_16x16x32_bf16 v[92:95], v[144:147], v[208:211], v[92:95]
	v_mfma_f32_16x16x32_bf16 v[88:91], v[184:187], v[208:211], v[88:91]
	v_mfma_f32_16x16x32_bf16 v[72:75], v[144:147], v[216:219], v[72:75]
	v_mfma_f32_16x16x32_bf16 v[68:71], v[184:187], v[216:219], v[68:71]
	v_mfma_f32_16x16x32_bf16 v[124:127], v[148:151], v[196:199], v[124:127]
	v_mfma_f32_16x16x32_bf16 v[120:123], v[188:191], v[196:199], v[120:123]
	v_mfma_f32_16x16x32_bf16 v[112:115], v[148:151], v[204:207], v[112:115]
	v_mfma_f32_16x16x32_bf16 v[108:111], v[188:191], v[204:207], v[108:111]
	v_mfma_f32_16x16x32_bf16 v[92:95], v[148:151], v[212:215], v[92:95]
	v_mfma_f32_16x16x32_bf16 v[88:91], v[188:191], v[212:215], v[88:91]
	v_mfma_f32_16x16x32_bf16 v[72:75], v[148:151], v[220:223], v[72:75]
	v_mfma_f32_16x16x32_bf16 v[68:71], v[188:191], v[220:223], v[68:71]
	s_barrier
	s_setprio 0
	s_mov_b32 m0, s53
	v_lshl_add_u64 v[224:225], s[24:25], 0, v[156:157]
	s_add_u32 s54, s24, 0x40000
	ds_read_b128 v[192:195], v179 offset:16384
	ds_read_b128 v[196:199], v179 offset:17408
	global_load_lds_dwordx4 v[224:225], off
	v_lshl_add_u64 v[226:227], s[24:25], 0, v[160:161]
	s_mov_b32 m0, s56
	s_addc_u32 s55, s25, 0
	ds_read_b128 v[200:203], v179 offset:18432
	ds_read_b128 v[204:207], v179 offset:19456
	global_load_lds_dwordx4 v[226:227], off
	v_lshl_add_u64 v[228:229], s[54:55], 0, v[156:157]
	s_mov_b32 m0, s57
	v_lshl_add_u64 v[230:231], s[34:35], 0, v[158:159]
	ds_read_b128 v[208:211], v179 offset:20480
	global_load_lds_dwordx4 v[228:229], off
	v_lshl_add_u64 v[228:229], s[54:55], 0, v[160:161]
	s_mov_b32 m0, s58
	ds_read_b128 v[212:215], v179 offset:21504
	global_load_lds_dwordx4 v[228:229], off
	v_lshl_add_u64 v[228:229], s[34:35], 0, v[154:155]
	s_mov_b32 m0, s39
	ds_read_b128 v[216:219], v179 offset:22528
	global_load_lds_dwordx4 v[228:229], off
	s_mov_b32 m0, s40
	ds_read_b128 v[220:223], v179 offset:23552
	global_load_lds_dwordx4 v[230:231], off
	s_waitcnt vmcnt(8)
	s_waitcnt lgkmcnt(0)
	s_setprio 1
	s_barrier
	v_mfma_f32_16x16x32_bf16 v[60:63], v[16:19], v[192:195], v[60:63]
	v_mfma_f32_16x16x32_bf16 v[64:67], v[104:107], v[192:195], v[64:67]
	v_mfma_f32_16x16x32_bf16 v[44:47], v[16:19], v[200:203], v[44:47]
	v_mfma_f32_16x16x32_bf16 v[48:51], v[104:107], v[200:203], v[48:51]
	v_mfma_f32_16x16x32_bf16 v[28:31], v[16:19], v[208:211], v[28:31]
	v_mfma_f32_16x16x32_bf16 v[32:35], v[104:107], v[208:211], v[32:35]
	v_mfma_f32_16x16x32_bf16 v[12:15], v[16:19], v[216:219], v[12:15]
	v_mfma_f32_16x16x32_bf16 v[8:11], v[104:107], v[216:219], v[8:11]
	v_mfma_f32_16x16x32_bf16 v[60:63], v[80:83], v[196:199], v[60:63]
	v_mfma_f32_16x16x32_bf16 v[64:67], v[140:143], v[196:199], v[64:67]
	v_mfma_f32_16x16x32_bf16 v[44:47], v[80:83], v[204:207], v[44:47]
	v_mfma_f32_16x16x32_bf16 v[48:51], v[140:143], v[204:207], v[48:51]
	v_mfma_f32_16x16x32_bf16 v[28:31], v[80:83], v[212:215], v[28:31]
	v_mfma_f32_16x16x32_bf16 v[32:35], v[140:143], v[212:215], v[32:35]
	v_mfma_f32_16x16x32_bf16 v[12:15], v[80:83], v[220:223], v[12:15]
	v_mfma_f32_16x16x32_bf16 v[8:11], v[140:143], v[220:223], v[8:11]
	s_setprio 0
	s_setprio 1
	v_mfma_f32_16x16x32_bf16 v[16:19], v[144:147], v[192:195], v[52:55]
	v_mfma_f32_16x16x32_bf16 v[52:55], v[184:187], v[192:195], v[56:59]
	v_mfma_f32_16x16x32_bf16 v[36:39], v[144:147], v[200:203], v[36:39]
	v_mfma_f32_16x16x32_bf16 v[40:43], v[184:187], v[200:203], v[40:43]
	v_mfma_f32_16x16x32_bf16 v[20:23], v[144:147], v[208:211], v[20:23]
	v_mfma_f32_16x16x32_bf16 v[24:27], v[184:187], v[208:211], v[24:27]
	v_mfma_f32_16x16x32_bf16 v[4:7], v[144:147], v[216:219], v[4:7]
	v_mfma_f32_16x16x32_bf16 v[0:3], v[184:187], v[216:219], v[0:3]
	v_mfma_f32_16x16x32_bf16 v[56:59], v[188:191], v[196:199], v[52:55]
	v_mfma_f32_16x16x32_bf16 v[36:39], v[148:151], v[204:207], v[36:39]
	v_mfma_f32_16x16x32_bf16 v[40:43], v[188:191], v[204:207], v[40:43]
	v_mfma_f32_16x16x32_bf16 v[20:23], v[148:151], v[212:215], v[20:23]
	v_mfma_f32_16x16x32_bf16 v[24:27], v[188:191], v[212:215], v[24:27]
	v_mfma_f32_16x16x32_bf16 v[4:7], v[148:151], v[220:223], v[4:7]
	v_mfma_f32_16x16x32_bf16 v[0:3], v[188:191], v[220:223], v[0:3]
	v_mfma_f32_16x16x32_bf16 v[16:19], v[148:151], v[196:199], v[16:19]
	s_barrier
	s_setprio 0
	ds_read_b128 v[52:55], v180
	ds_read_b128 v[80:83], v180 offset:1024
	ds_read_b128 v[104:107], v180 offset:2048
	ds_read_b128 v[140:143], v180 offset:3072
	ds_read_b128 v[144:147], v181
	ds_read_b128 v[148:151], v181 offset:1024
	ds_read_b128 v[184:187], v181 offset:2048
	ds_read_b128 v[188:191], v181 offset:3072
	s_add_u32 s34, s34, 0x40000
	s_addc_u32 s35, s35, 0
	s_mov_b32 m0, s41
	v_lshl_add_u64 v[232:233], s[34:35], 0, v[154:155]
	ds_read_b128 v[192:195], v179 offset:32768
	ds_read_b128 v[196:199], v179 offset:33792
	ds_read_b128 v[200:203], v179 offset:34816
	ds_read_b128 v[204:207], v179 offset:35840
	ds_read_b128 v[208:211], v179 offset:36864
	ds_read_b128 v[212:215], v179 offset:37888
	ds_read_b128 v[216:219], v179 offset:38912
	ds_read_b128 v[220:223], v179 offset:39936
	global_load_lds_dwordx4 v[232:233], off
	v_lshl_add_u64 v[232:233], s[34:35], 0, v[158:159]
	s_mov_b32 m0, s42
	s_nop 0
	global_load_lds_dwordx4 v[232:233], off
	s_waitcnt vmcnt(8)
	s_waitcnt lgkmcnt(0)
	s_setprio 1
	s_barrier
	v_mfma_f32_16x16x32_bf16 v[136:139], v[52:55], v[192:195], v[136:139]
	v_mfma_f32_16x16x32_bf16 v[132:135], v[104:107], v[192:195], v[132:135]
	v_mfma_f32_16x16x32_bf16 v[128:131], v[52:55], v[200:203], v[128:131]
	v_mfma_f32_16x16x32_bf16 v[116:119], v[104:107], v[200:203], v[116:119]
	v_mfma_f32_16x16x32_bf16 v[100:103], v[52:55], v[208:211], v[100:103]
	v_mfma_f32_16x16x32_bf16 v[96:99], v[104:107], v[208:211], v[96:99]
	v_mfma_f32_16x16x32_bf16 v[84:87], v[52:55], v[216:219], v[84:87]
	v_mfma_f32_16x16x32_bf16 v[76:79], v[104:107], v[216:219], v[76:79]
	v_mfma_f32_16x16x32_bf16 v[136:139], v[80:83], v[196:199], v[136:139]
	v_mfma_f32_16x16x32_bf16 v[132:135], v[140:143], v[196:199], v[132:135]
	v_mfma_f32_16x16x32_bf16 v[128:131], v[80:83], v[204:207], v[128:131]
	v_mfma_f32_16x16x32_bf16 v[116:119], v[140:143], v[204:207], v[116:119]
	v_mfma_f32_16x16x32_bf16 v[100:103], v[80:83], v[212:215], v[100:103]
	v_mfma_f32_16x16x32_bf16 v[96:99], v[140:143], v[212:215], v[96:99]
	v_mfma_f32_16x16x32_bf16 v[84:87], v[80:83], v[220:223], v[84:87]
	v_mfma_f32_16x16x32_bf16 v[76:79], v[140:143], v[220:223], v[76:79]
	s_setprio 0
	s_setprio 1
	v_mfma_f32_16x16x32_bf16 v[124:127], v[144:147], v[192:195], v[124:127]
	v_mfma_f32_16x16x32_bf16 v[120:123], v[184:187], v[192:195], v[120:123]
	v_mfma_f32_16x16x32_bf16 v[112:115], v[144:147], v[200:203], v[112:115]
	v_mfma_f32_16x16x32_bf16 v[108:111], v[184:187], v[200:203], v[108:111]
	v_mfma_f32_16x16x32_bf16 v[92:95], v[144:147], v[208:211], v[92:95]
	v_mfma_f32_16x16x32_bf16 v[88:91], v[184:187], v[208:211], v[88:91]
	v_mfma_f32_16x16x32_bf16 v[72:75], v[144:147], v[216:219], v[72:75]
	v_mfma_f32_16x16x32_bf16 v[68:71], v[184:187], v[216:219], v[68:71]
	v_mfma_f32_16x16x32_bf16 v[124:127], v[148:151], v[196:199], v[124:127]
	v_mfma_f32_16x16x32_bf16 v[120:123], v[188:191], v[196:199], v[120:123]
	v_mfma_f32_16x16x32_bf16 v[112:115], v[148:151], v[204:207], v[112:115]
	v_mfma_f32_16x16x32_bf16 v[108:111], v[188:191], v[204:207], v[108:111]
	v_mfma_f32_16x16x32_bf16 v[92:95], v[148:151], v[212:215], v[92:95]
	v_mfma_f32_16x16x32_bf16 v[88:91], v[188:191], v[212:215], v[88:91]
	v_mfma_f32_16x16x32_bf16 v[72:75], v[148:151], v[220:223], v[72:75]
	v_mfma_f32_16x16x32_bf16 v[68:71], v[188:191], v[220:223], v[68:71]
	s_barrier
	s_setprio 0
	s_mov_b32 m0, s59
	v_lshl_add_u64 v[224:225], v[224:225], 0, s[6:7]
	s_add_u32 s24, s24, 0x40080
	ds_read_b128 v[192:195], v179 offset:49152
	ds_read_b128 v[196:199], v179 offset:50176
	global_load_lds_dwordx4 v[224:225], off
	v_lshl_add_u64 v[224:225], v[226:227], 0, s[6:7]
	s_mov_b32 m0, s60
	s_addc_u32 s25, s25, 0
	ds_read_b128 v[200:203], v179 offset:51200
	ds_read_b128 v[204:207], v179 offset:52224
	global_load_lds_dwordx4 v[224:225], off
	v_lshl_add_u64 v[224:225], s[24:25], 0, v[156:157]
	s_mov_b32 m0, s61
	ds_read_b128 v[208:211], v179 offset:53248
	global_load_lds_dwordx4 v[224:225], off
	v_lshl_add_u64 v[224:225], s[24:25], 0, v[160:161]
	s_mov_b32 m0, s62
	ds_read_b128 v[212:215], v179 offset:54272
	global_load_lds_dwordx4 v[224:225], off
	v_lshl_add_u64 v[224:225], v[228:229], 0, s[6:7]
	s_mov_b32 m0, s44
	ds_read_b128 v[216:219], v179 offset:55296
	global_load_lds_dwordx4 v[224:225], off
	v_lshl_add_u64 v[224:225], v[230:231], 0, s[6:7]
	s_mov_b32 m0, s45
	ds_read_b128 v[220:223], v179 offset:56320
	global_load_lds_dwordx4 v[224:225], off
	s_waitcnt vmcnt(8)
	s_waitcnt lgkmcnt(0)
	s_setprio 1
	s_barrier
	v_mfma_f32_16x16x32_bf16 v[60:63], v[52:55], v[192:195], v[60:63]
	v_mfma_f32_16x16x32_bf16 v[64:67], v[104:107], v[192:195], v[64:67]
	v_mfma_f32_16x16x32_bf16 v[44:47], v[52:55], v[200:203], v[44:47]
	v_mfma_f32_16x16x32_bf16 v[48:51], v[104:107], v[200:203], v[48:51]
	v_mfma_f32_16x16x32_bf16 v[28:31], v[52:55], v[208:211], v[28:31]
	v_mfma_f32_16x16x32_bf16 v[32:35], v[104:107], v[208:211], v[32:35]
	v_mfma_f32_16x16x32_bf16 v[12:15], v[52:55], v[216:219], v[12:15]
	v_mfma_f32_16x16x32_bf16 v[8:11], v[104:107], v[216:219], v[8:11]
	v_mfma_f32_16x16x32_bf16 v[60:63], v[80:83], v[196:199], v[60:63]
	v_mfma_f32_16x16x32_bf16 v[64:67], v[140:143], v[196:199], v[64:67]
	v_mfma_f32_16x16x32_bf16 v[44:47], v[80:83], v[204:207], v[44:47]
	v_mfma_f32_16x16x32_bf16 v[48:51], v[140:143], v[204:207], v[48:51]
	v_mfma_f32_16x16x32_bf16 v[28:31], v[80:83], v[212:215], v[28:31]
	v_mfma_f32_16x16x32_bf16 v[32:35], v[140:143], v[212:215], v[32:35]
	v_mfma_f32_16x16x32_bf16 v[12:15], v[80:83], v[220:223], v[12:15]
	v_mfma_f32_16x16x32_bf16 v[8:11], v[140:143], v[220:223], v[8:11]
	s_setprio 0
	s_setprio 1
	v_mfma_f32_16x16x32_bf16 v[16:19], v[144:147], v[192:195], v[16:19]
	v_mfma_f32_16x16x32_bf16 v[52:55], v[148:151], v[196:199], v[16:19]
	v_mfma_f32_16x16x32_bf16 v[16:19], v[184:187], v[192:195], v[56:59]
	v_mfma_f32_16x16x32_bf16 v[56:59], v[188:191], v[196:199], v[16:19]
	v_mfma_f32_16x16x32_bf16 v[16:19], v[144:147], v[200:203], v[36:39]
	v_mfma_f32_16x16x32_bf16 v[36:39], v[148:151], v[204:207], v[16:19]
	v_mfma_f32_16x16x32_bf16 v[16:19], v[184:187], v[200:203], v[40:43]
	v_mfma_f32_16x16x32_bf16 v[40:43], v[188:191], v[204:207], v[16:19]
	v_mfma_f32_16x16x32_bf16 v[16:19], v[144:147], v[208:211], v[20:23]
	v_mfma_f32_16x16x32_bf16 v[20:23], v[148:151], v[212:215], v[16:19]
	v_mfma_f32_16x16x32_bf16 v[16:19], v[184:187], v[208:211], v[24:27]
	v_mfma_f32_16x16x32_bf16 v[4:7], v[144:147], v[216:219], v[4:7]
	v_mfma_f32_16x16x32_bf16 v[0:3], v[184:187], v[216:219], v[0:3]
	v_mfma_f32_16x16x32_bf16 v[24:27], v[188:191], v[212:215], v[16:19]
	v_mfma_f32_16x16x32_bf16 v[4:7], v[148:151], v[220:223], v[4:7]
	v_mfma_f32_16x16x32_bf16 v[0:3], v[188:191], v[220:223], v[0:3]
	s_barrier
	s_setprio 0
	s_add_i32 s71, s71, 2
	s_add_u32 s26, s26, 0x100
	s_addc_u32 s27, s27, 0
	s_add_u32 s67, s67, 0x100
	s_addc_u32 s70, s70, 0
	s_cmp_gt_u32 s71, 13
	s_cbranch_scc0 .LBB0_1352
	s_and_b64 vcc, exec, s[10:11]
	s_cbranch_vccz .LBB0_1355
	s_barrier

.Lpk1457_j1:
	s_waitcnt lgkmcnt(0)
	s_setprio 1
	s_barrier
	v_mfma_f32_16x16x32_bf16 v[124:127], v[128:131], v[178:181], 0
	v_mfma_f32_16x16x32_bf16 v[120:123], v[136:139], v[178:181], 0
	v_mfma_f32_16x16x32_bf16 v[108:111], v[128:131], v[196:199], 0
	v_mfma_f32_16x16x32_bf16 v[104:107], v[136:139], v[196:199], 0
	v_mfma_f32_16x16x32_bf16 v[92:95], v[128:131], v[204:207], 0
	v_mfma_f32_16x16x32_bf16 v[88:91], v[136:139], v[204:207], 0
	v_mfma_f32_16x16x32_bf16 v[76:79], v[128:131], v[212:215], 0
	v_mfma_f32_16x16x32_bf16 v[72:75], v[136:139], v[212:215], 0
	v_mfma_f32_16x16x32_bf16 v[124:127], v[132:135], v[182:185], v[124:127]
	v_mfma_f32_16x16x32_bf16 v[120:123], v[140:143], v[182:185], v[120:123]
	v_mfma_f32_16x16x32_bf16 v[108:111], v[132:135], v[200:203], v[108:111]
	v_mfma_f32_16x16x32_bf16 v[104:107], v[140:143], v[200:203], v[104:107]
	v_mfma_f32_16x16x32_bf16 v[92:95], v[132:135], v[208:211], v[92:95]
	v_mfma_f32_16x16x32_bf16 v[88:91], v[140:143], v[208:211], v[88:91]
	v_mfma_f32_16x16x32_bf16 v[76:79], v[132:135], v[216:219], v[76:79]
	v_mfma_f32_16x16x32_bf16 v[72:75], v[140:143], v[216:219], v[72:75]
	s_setprio 0
	s_setprio 1
	v_mfma_f32_16x16x32_bf16 v[116:119], v[144:147], v[178:181], 0
	v_mfma_f32_16x16x32_bf16 v[112:115], v[170:173], v[178:181], 0
	v_mfma_f32_16x16x32_bf16 v[100:103], v[144:147], v[196:199], 0
	v_mfma_f32_16x16x32_bf16 v[96:99], v[170:173], v[196:199], 0
	v_mfma_f32_16x16x32_bf16 v[84:87], v[144:147], v[204:207], 0
	v_mfma_f32_16x16x32_bf16 v[80:83], v[170:173], v[204:207], 0
	v_mfma_f32_16x16x32_bf16 v[68:71], v[144:147], v[212:215], 0
	v_mfma_f32_16x16x32_bf16 v[64:67], v[170:173], v[212:215], 0
	v_mfma_f32_16x16x32_bf16 v[116:119], v[148:151], v[182:185], v[116:119]
	v_mfma_f32_16x16x32_bf16 v[112:115], v[174:177], v[182:185], v[112:115]
	v_mfma_f32_16x16x32_bf16 v[100:103], v[148:151], v[200:203], v[100:103]
	v_mfma_f32_16x16x32_bf16 v[96:99], v[174:177], v[200:203], v[96:99]
	v_mfma_f32_16x16x32_bf16 v[84:87], v[148:151], v[208:211], v[84:87]
	v_mfma_f32_16x16x32_bf16 v[80:83], v[174:177], v[208:211], v[80:83]
	v_mfma_f32_16x16x32_bf16 v[68:71], v[148:151], v[216:219], v[68:71]
	v_mfma_f32_16x16x32_bf16 v[64:67], v[174:177], v[216:219], v[64:67]
	s_barrier
	s_setprio 0
	s_add_i32 s53, s47, s33
	v_lshl_add_u64 v[186:187], s[34:35], 0, v[156:157]
	s_mov_b32 m0, s53
	ds_read_b128 v[178:181], v193 offset:16384
	ds_read_b128 v[182:185], v193 offset:17408
	global_load_lds_dwordx4 v[186:187], off
	s_add_i32 m0, s53, 0x2000
	s_add_u32 s54, s34, 0x40000
	v_lshl_add_u64 v[220:221], s[34:35], 0, v[160:161]
	s_addc_u32 s55, s35, 0
	s_add_i32 s53, s48, s33
	ds_read_b128 v[196:199], v193 offset:18432
	ds_read_b128 v[200:203], v193 offset:19456
	global_load_lds_dwordx4 v[220:221], off
	v_lshl_add_u64 v[222:223], s[54:55], 0, v[156:157]
	s_mov_b32 m0, s53
	v_lshl_add_u64 v[224:225], s[36:37], 0, v[158:159]
	ds_read_b128 v[204:207], v193 offset:20480
	global_load_lds_dwordx4 v[222:223], off
	v_lshl_add_u64 v[222:223], s[54:55], 0, v[160:161]
	s_add_i32 m0, s53, 0x2000
	ds_read_b128 v[208:211], v193 offset:21504
	global_load_lds_dwordx4 v[222:223], off
	v_lshl_add_u64 v[222:223], s[36:37], 0, v[154:155]
	s_mov_b32 m0, s29
	ds_read_b128 v[212:215], v193 offset:22528
	global_load_lds_dwordx4 v[222:223], off
	s_mov_b32 m0, s38
	ds_read_b128 v[216:219], v193 offset:23552
	global_load_lds_dwordx4 v[224:225], off
	s_cmp_eq_u32 s101, 1
	s_cbranch_scc1 .Lpk1457_r2
	s_waitcnt vmcnt(8)
	s_branch .Lpk1457_j2

.LBB0_1457:
	ds_read_b128 v[128:131], v191
	ds_read_b128 v[132:135], v191 offset:1024
	ds_read_b128 v[136:139], v191 offset:2048
	ds_read_b128 v[140:143], v191 offset:3072
	ds_read_b128 v[144:147], v192
	ds_read_b128 v[148:151], v192 offset:1024
	ds_read_b128 v[170:173], v192 offset:2048
	ds_read_b128 v[174:177], v192 offset:3072
	s_add_u32 s34, s30, 0xfff80080
	s_addc_u32 s35, s31, -1
	s_cmp_eq_u32 s52, 12
	s_cselect_b32 s37, s21, s35
	s_cselect_b32 s36, s27, s34
	s_cselect_b32 s35, s19, s51
	s_cselect_b32 s34, s49, s50
	v_lshl_add_u64 v[186:187], s[30:31], 0, v[162:163]
	s_add_i32 m0, s29, 0xc000
	ds_read_b128 v[178:181], v193
	ds_read_b128 v[182:185], v193 offset:1024
	ds_read_b128 v[196:199], v193 offset:2048
	ds_read_b128 v[200:203], v193 offset:3072
	ds_read_b128 v[204:207], v193 offset:4096
	ds_read_b128 v[208:211], v193 offset:5120
	ds_read_b128 v[212:215], v193 offset:6144
	ds_read_b128 v[216:219], v193 offset:7168
	global_load_lds_dwordx4 v[186:187], off
	v_lshl_add_u64 v[186:187], s[30:31], 0, v[164:165]
	s_add_i32 m0, s29, 0xe000
	s_nop 0
	global_load_lds_dwordx4 v[186:187], off
	s_waitcnt vmcnt(8)
	s_waitcnt lgkmcnt(0)
	s_setprio 1
	s_barrier
	v_mfma_f32_16x16x32_bf16 v[124:127], v[128:131], v[178:181], v[124:127]
	v_mfma_f32_16x16x32_bf16 v[120:123], v[136:139], v[178:181], v[120:123]
	v_mfma_f32_16x16x32_bf16 v[108:111], v[128:131], v[196:199], v[108:111]
	v_mfma_f32_16x16x32_bf16 v[104:107], v[136:139], v[196:199], v[104:107]
	v_mfma_f32_16x16x32_bf16 v[92:95], v[128:131], v[204:207], v[92:95]
	v_mfma_f32_16x16x32_bf16 v[88:91], v[136:139], v[204:207], v[88:91]
	v_mfma_f32_16x16x32_bf16 v[76:79], v[128:131], v[212:215], v[76:79]
	v_mfma_f32_16x16x32_bf16 v[72:75], v[136:139], v[212:215], v[72:75]
	v_mfma_f32_16x16x32_bf16 v[124:127], v[132:135], v[182:185], v[124:127]
	v_mfma_f32_16x16x32_bf16 v[120:123], v[140:143], v[182:185], v[120:123]
	v_mfma_f32_16x16x32_bf16 v[108:111], v[132:135], v[200:203], v[108:111]
	v_mfma_f32_16x16x32_bf16 v[104:107], v[140:143], v[200:203], v[104:107]
	v_mfma_f32_16x16x32_bf16 v[92:95], v[132:135], v[208:211], v[92:95]
	v_mfma_f32_16x16x32_bf16 v[88:91], v[140:143], v[208:211], v[88:91]
	v_mfma_f32_16x16x32_bf16 v[76:79], v[132:135], v[216:219], v[76:79]
	v_mfma_f32_16x16x32_bf16 v[72:75], v[140:143], v[216:219], v[72:75]
	s_setprio 0
	s_setprio 1
	v_mfma_f32_16x16x32_bf16 v[116:119], v[144:147], v[178:181], v[116:119]
	v_mfma_f32_16x16x32_bf16 v[112:115], v[170:173], v[178:181], v[112:115]
	v_mfma_f32_16x16x32_bf16 v[100:103], v[144:147], v[196:199], v[100:103]
	v_mfma_f32_16x16x32_bf16 v[96:99], v[170:173], v[196:199], v[96:99]
	v_mfma_f32_16x16x32_bf16 v[84:87], v[144:147], v[204:207], v[84:87]
	v_mfma_f32_16x16x32_bf16 v[80:83], v[170:173], v[204:207], v[80:83]
	v_mfma_f32_16x16x32_bf16 v[68:71], v[144:147], v[212:215], v[68:71]
	v_mfma_f32_16x16x32_bf16 v[64:67], v[170:173], v[212:215], v[64:67]
	v_mfma_f32_16x16x32_bf16 v[116:119], v[148:151], v[182:185], v[116:119]
	v_mfma_f32_16x16x32_bf16 v[112:115], v[174:177], v[182:185], v[112:115]
	v_mfma_f32_16x16x32_bf16 v[100:103], v[148:151], v[200:203], v[100:103]
	v_mfma_f32_16x16x32_bf16 v[96:99], v[174:177], v[200:203], v[96:99]
	v_mfma_f32_16x16x32_bf16 v[84:87], v[148:151], v[208:211], v[84:87]
	v_mfma_f32_16x16x32_bf16 v[80:83], v[174:177], v[208:211], v[80:83]
	v_mfma_f32_16x16x32_bf16 v[68:71], v[148:151], v[216:219], v[68:71]
	v_mfma_f32_16x16x32_bf16 v[64:67], v[174:177], v[216:219], v[64:67]
	s_barrier
	s_setprio 0
	s_add_i32 s53, s47, s33
	v_lshl_add_u64 v[186:187], s[34:35], 0, v[156:157]
	s_mov_b32 m0, s53
	ds_read_b128 v[178:181], v193 offset:16384
	ds_read_b128 v[182:185], v193 offset:17408
	global_load_lds_dwordx4 v[186:187], off
	s_add_i32 m0, s53, 0x2000
	s_add_u32 s54, s34, 0x40000
	v_lshl_add_u64 v[220:221], s[34:35], 0, v[160:161]
	s_addc_u32 s55, s35, 0
	s_add_i32 s53, s48, s33
	ds_read_b128 v[196:199], v193 offset:18432
	ds_read_b128 v[200:203], v193 offset:19456
	global_load_lds_dwordx4 v[220:221], off
	v_lshl_add_u64 v[222:223], s[54:55], 0, v[156:157]
	s_mov_b32 m0, s53
	v_lshl_add_u64 v[224:225], s[36:37], 0, v[158:159]
	ds_read_b128 v[204:207], v193 offset:20480
	global_load_lds_dwordx4 v[222:223], off
	v_lshl_add_u64 v[222:223], s[54:55], 0, v[160:161]
	s_add_i32 m0, s53, 0x2000
	ds_read_b128 v[208:211], v193 offset:21504
	global_load_lds_dwordx4 v[222:223], off
	v_lshl_add_u64 v[222:223], s[36:37], 0, v[154:155]
	s_mov_b32 m0, s29
	ds_read_b128 v[212:215], v193 offset:22528
	global_load_lds_dwordx4 v[222:223], off
	s_mov_b32 m0, s38
	ds_read_b128 v[216:219], v193 offset:23552
	global_load_lds_dwordx4 v[224:225], off
	s_waitcnt vmcnt(8)
	s_waitcnt lgkmcnt(0)
	s_setprio 1
	s_barrier
	v_mfma_f32_16x16x32_bf16 v[60:63], v[128:131], v[178:181], v[60:63]
	v_mfma_f32_16x16x32_bf16 v[56:59], v[136:139], v[178:181], v[56:59]
	v_mfma_f32_16x16x32_bf16 v[44:47], v[128:131], v[196:199], v[44:47]
	v_mfma_f32_16x16x32_bf16 v[40:43], v[136:139], v[196:199], v[40:43]
	v_mfma_f32_16x16x32_bf16 v[28:31], v[128:131], v[204:207], v[28:31]
	v_mfma_f32_16x16x32_bf16 v[24:27], v[136:139], v[204:207], v[24:27]
	v_mfma_f32_16x16x32_bf16 v[12:15], v[128:131], v[212:215], v[12:15]
	v_mfma_f32_16x16x32_bf16 v[8:11], v[136:139], v[212:215], v[8:11]
	v_mfma_f32_16x16x32_bf16 v[60:63], v[132:135], v[182:185], v[60:63]
	v_mfma_f32_16x16x32_bf16 v[56:59], v[140:143], v[182:185], v[56:59]
	v_mfma_f32_16x16x32_bf16 v[44:47], v[132:135], v[200:203], v[44:47]
	v_mfma_f32_16x16x32_bf16 v[40:43], v[140:143], v[200:203], v[40:43]
	v_mfma_f32_16x16x32_bf16 v[28:31], v[132:135], v[208:211], v[28:31]
	v_mfma_f32_16x16x32_bf16 v[24:27], v[140:143], v[208:211], v[24:27]
	v_mfma_f32_16x16x32_bf16 v[12:15], v[132:135], v[216:219], v[12:15]
	v_mfma_f32_16x16x32_bf16 v[8:11], v[140:143], v[216:219], v[8:11]
	s_setprio 0
	s_setprio 1
	v_mfma_f32_16x16x32_bf16 v[52:55], v[144:147], v[178:181], v[52:55]
	v_mfma_f32_16x16x32_bf16 v[48:51], v[170:173], v[178:181], v[48:51]
	v_mfma_f32_16x16x32_bf16 v[36:39], v[144:147], v[196:199], v[36:39]
	v_mfma_f32_16x16x32_bf16 v[32:35], v[170:173], v[196:199], v[32:35]
	v_mfma_f32_16x16x32_bf16 v[20:23], v[144:147], v[204:207], v[20:23]
	v_mfma_f32_16x16x32_bf16 v[16:19], v[170:173], v[204:207], v[16:19]
	v_mfma_f32_16x16x32_bf16 v[4:7], v[144:147], v[212:215], v[4:7]
	v_mfma_f32_16x16x32_bf16 v[0:3], v[170:173], v[212:215], v[0:3]
	v_mfma_f32_16x16x32_bf16 v[52:55], v[148:151], v[182:185], v[52:55]
	v_mfma_f32_16x16x32_bf16 v[48:51], v[174:177], v[182:185], v[48:51]
	v_mfma_f32_16x16x32_bf16 v[36:39], v[148:151], v[200:203], v[36:39]
	v_mfma_f32_16x16x32_bf16 v[32:35], v[174:177], v[200:203], v[32:35]
	v_mfma_f32_16x16x32_bf16 v[20:23], v[148:151], v[208:211], v[20:23]
	v_mfma_f32_16x16x32_bf16 v[16:19], v[174:177], v[208:211], v[16:19]
	v_mfma_f32_16x16x32_bf16 v[4:7], v[148:151], v[216:219], v[4:7]
	v_mfma_f32_16x16x32_bf16 v[0:3], v[174:177], v[216:219], v[0:3]
	s_barrier
	s_setprio 0
.Lpk1457_seg3:
	s_add_i32 s53, 0, 0x18000
	s_add_i32 s54, 0, 0x1c000
	v_add_u32_e32 v140, s53, v189
	v_add_u32_e32 v174, s54, v189
	ds_read_b128 v[128:131], v140
	ds_read_b128 v[132:135], v140 offset:1024
	ds_read_b128 v[136:139], v140 offset:2048
	ds_read_b128 v[140:143], v140 offset:3072
	ds_read_b128 v[144:147], v174
	ds_read_b128 v[148:151], v174 offset:1024
	ds_read_b128 v[170:173], v174 offset:2048
	ds_read_b128 v[174:177], v174 offset:3072
	s_add_u32 s36, s36, 0x80000
	s_addc_u32 s37, s37, 0
	s_mov_b32 m0, s39
	v_lshl_add_u64 v[226:227], s[36:37], 0, v[154:155]
	ds_read_b128 v[178:181], v193 offset:32768
	ds_read_b128 v[182:185], v193 offset:33792
	ds_read_b128 v[196:199], v193 offset:34816
	ds_read_b128 v[200:203], v193 offset:35840
	ds_read_b128 v[204:207], v193 offset:36864
	ds_read_b128 v[208:211], v193 offset:37888
	ds_read_b128 v[212:215], v193 offset:38912
	ds_read_b128 v[216:219], v193 offset:39936
	global_load_lds_dwordx4 v[226:227], off
	v_lshl_add_u64 v[226:227], s[36:37], 0, v[158:159]
	s_mov_b32 m0, s40
	s_nop 0
	global_load_lds_dwordx4 v[226:227], off
	s_waitcnt vmcnt(8)
	s_waitcnt lgkmcnt(0)
	s_setprio 1
	s_barrier
	v_mfma_f32_16x16x32_bf16 v[124:127], v[128:131], v[178:181], v[124:127]
	v_mfma_f32_16x16x32_bf16 v[120:123], v[136:139], v[178:181], v[120:123]
	v_mfma_f32_16x16x32_bf16 v[108:111], v[128:131], v[196:199], v[108:111]
	v_mfma_f32_16x16x32_bf16 v[104:107], v[136:139], v[196:199], v[104:107]
	v_mfma_f32_16x16x32_bf16 v[92:95], v[128:131], v[204:207], v[92:95]
	v_mfma_f32_16x16x32_bf16 v[88:91], v[136:139], v[204:207], v[88:91]
	v_mfma_f32_16x16x32_bf16 v[76:79], v[128:131], v[212:215], v[76:79]
	v_mfma_f32_16x16x32_bf16 v[72:75], v[136:139], v[212:215], v[72:75]
	v_mfma_f32_16x16x32_bf16 v[124:127], v[132:135], v[182:185], v[124:127]
	v_mfma_f32_16x16x32_bf16 v[120:123], v[140:143], v[182:185], v[120:123]
	v_mfma_f32_16x16x32_bf16 v[108:111], v[132:135], v[200:203], v[108:111]
	v_mfma_f32_16x16x32_bf16 v[104:107], v[140:143], v[200:203], v[104:107]
	v_mfma_f32_16x16x32_bf16 v[92:95], v[132:135], v[208:211], v[92:95]
	v_mfma_f32_16x16x32_bf16 v[88:91], v[140:143], v[208:211], v[88:91]
	v_mfma_f32_16x16x32_bf16 v[76:79], v[132:135], v[216:219], v[76:79]
	v_mfma_f32_16x16x32_bf16 v[72:75], v[140:143], v[216:219], v[72:75]
	s_setprio 0
	s_setprio 1
	v_mfma_f32_16x16x32_bf16 v[116:119], v[144:147], v[178:181], v[116:119]
	v_mfma_f32_16x16x32_bf16 v[112:115], v[170:173], v[178:181], v[112:115]
	v_mfma_f32_16x16x32_bf16 v[100:103], v[144:147], v[196:199], v[100:103]
	v_mfma_f32_16x16x32_bf16 v[96:99], v[170:173], v[196:199], v[96:99]
	v_mfma_f32_16x16x32_bf16 v[84:87], v[144:147], v[204:207], v[84:87]
	v_mfma_f32_16x16x32_bf16 v[80:83], v[170:173], v[204:207], v[80:83]
	v_mfma_f32_16x16x32_bf16 v[68:71], v[144:147], v[212:215], v[68:71]
	v_mfma_f32_16x16x32_bf16 v[64:67], v[170:173], v[212:215], v[64:67]
	v_mfma_f32_16x16x32_bf16 v[116:119], v[148:151], v[182:185], v[116:119]
	v_mfma_f32_16x16x32_bf16 v[112:115], v[174:177], v[182:185], v[112:115]
	v_mfma_f32_16x16x32_bf16 v[100:103], v[148:151], v[200:203], v[100:103]
	v_mfma_f32_16x16x32_bf16 v[96:99], v[174:177], v[200:203], v[96:99]
	v_mfma_f32_16x16x32_bf16 v[84:87], v[148:151], v[208:211], v[84:87]
	v_mfma_f32_16x16x32_bf16 v[80:83], v[174:177], v[208:211], v[80:83]
	v_mfma_f32_16x16x32_bf16 v[68:71], v[148:151], v[216:219], v[68:71]
	v_mfma_f32_16x16x32_bf16 v[64:67], v[174:177], v[216:219], v[64:67]
	s_barrier
	s_setprio 0
	s_add_i32 s36, s53, s33
	v_lshl_add_u64 v[186:187], v[186:187], 0, s[14:15]
	s_mov_b32 m0, s36
	ds_read_b128 v[178:181], v193 offset:49152
	ds_read_b128 v[182:185], v193 offset:50176
	global_load_lds_dwordx4 v[186:187], off
	s_add_i32 m0, s36, 0x2000
	s_add_u32 s34, s34, 0x40080
	v_lshl_add_u64 v[186:187], v[220:221], 0, s[14:15]
	s_addc_u32 s35, s35, 0
	s_add_i32 s36, s54, s33
	ds_read_b128 v[196:199], v193 offset:51200
	ds_read_b128 v[200:203], v193 offset:52224
	global_load_lds_dwordx4 v[186:187], off
	v_lshl_add_u64 v[186:187], s[34:35], 0, v[156:157]
	s_mov_b32 m0, s36
	ds_read_b128 v[204:207], v193 offset:53248
	global_load_lds_dwordx4 v[186:187], off
	v_lshl_add_u64 v[186:187], s[34:35], 0, v[160:161]
	s_add_i32 m0, s36, 0x2000
	ds_read_b128 v[208:211], v193 offset:54272
	global_load_lds_dwordx4 v[186:187], off
	v_lshl_add_u64 v[186:187], v[222:223], 0, s[14:15]
	s_mov_b32 m0, s42
	ds_read_b128 v[212:215], v193 offset:55296
	global_load_lds_dwordx4 v[186:187], off
	v_lshl_add_u64 v[186:187], v[224:225], 0, s[14:15]
	s_mov_b32 m0, s43
	ds_read_b128 v[216:219], v193 offset:56320
	global_load_lds_dwordx4 v[186:187], off
	s_waitcnt vmcnt(8)
	s_waitcnt lgkmcnt(0)
	s_setprio 1
	s_barrier
	v_mfma_f32_16x16x32_bf16 v[60:63], v[128:131], v[178:181], v[60:63]
	v_mfma_f32_16x16x32_bf16 v[56:59], v[136:139], v[178:181], v[56:59]
	v_mfma_f32_16x16x32_bf16 v[44:47], v[128:131], v[196:199], v[44:47]
	v_mfma_f32_16x16x32_bf16 v[40:43], v[136:139], v[196:199], v[40:43]
	v_mfma_f32_16x16x32_bf16 v[28:31], v[128:131], v[204:207], v[28:31]
	v_mfma_f32_16x16x32_bf16 v[24:27], v[136:139], v[204:207], v[24:27]
	v_mfma_f32_16x16x32_bf16 v[12:15], v[128:131], v[212:215], v[12:15]
	v_mfma_f32_16x16x32_bf16 v[8:11], v[136:139], v[212:215], v[8:11]
	v_mfma_f32_16x16x32_bf16 v[60:63], v[132:135], v[182:185], v[60:63]
	v_mfma_f32_16x16x32_bf16 v[56:59], v[140:143], v[182:185], v[56:59]
	v_mfma_f32_16x16x32_bf16 v[44:47], v[132:135], v[200:203], v[44:47]
	v_mfma_f32_16x16x32_bf16 v[40:43], v[140:143], v[200:203], v[40:43]
	v_mfma_f32_16x16x32_bf16 v[28:31], v[132:135], v[208:211], v[28:31]
	v_mfma_f32_16x16x32_bf16 v[24:27], v[140:143], v[208:211], v[24:27]
	v_mfma_f32_16x16x32_bf16 v[12:15], v[132:135], v[216:219], v[12:15]
	v_mfma_f32_16x16x32_bf16 v[8:11], v[140:143], v[216:219], v[8:11]
	s_setprio 0
	s_setprio 1
	v_mfma_f32_16x16x32_bf16 v[52:55], v[144:147], v[178:181], v[52:55]
	v_mfma_f32_16x16x32_bf16 v[48:51], v[170:173], v[178:181], v[48:51]
	v_mfma_f32_16x16x32_bf16 v[36:39], v[144:147], v[196:199], v[36:39]
	v_mfma_f32_16x16x32_bf16 v[32:35], v[170:173], v[196:199], v[32:35]
	v_mfma_f32_16x16x32_bf16 v[20:23], v[144:147], v[204:207], v[20:23]
	v_mfma_f32_16x16x32_bf16 v[16:19], v[170:173], v[204:207], v[16:19]
	v_mfma_f32_16x16x32_bf16 v[4:7], v[144:147], v[212:215], v[4:7]
	v_mfma_f32_16x16x32_bf16 v[0:3], v[170:173], v[212:215], v[0:3]
	v_mfma_f32_16x16x32_bf16 v[52:55], v[148:151], v[182:185], v[52:55]
	v_mfma_f32_16x16x32_bf16 v[48:51], v[174:177], v[182:185], v[48:51]
	v_mfma_f32_16x16x32_bf16 v[36:39], v[148:151], v[200:203], v[36:39]
	v_mfma_f32_16x16x32_bf16 v[32:35], v[174:177], v[200:203], v[32:35]
	v_mfma_f32_16x16x32_bf16 v[20:23], v[148:151], v[208:211], v[20:23]
	v_mfma_f32_16x16x32_bf16 v[16:19], v[174:177], v[208:211], v[16:19]
	v_mfma_f32_16x16x32_bf16 v[4:7], v[148:151], v[216:219], v[4:7]
	v_mfma_f32_16x16x32_bf16 v[0:3], v[174:177], v[216:219], v[0:3]
	s_barrier
	s_setprio 0
	s_add_i32 s52, s52, 2
	s_add_u32 s30, s30, 0x100
	s_addc_u32 s31, s31, 0
	s_add_u32 s50, s50, 0x100
	s_addc_u32 s51, s51, 0
	s_cmp_gt_u32 s52, 13
	s_cbranch_scc0 .LBB0_1457
	s_and_b64 vcc, exec, s[16:17]
	s_cbranch_vccz .LBB0_1460
	s_barrier

.Lpk1613_j1:
	s_waitcnt lgkmcnt(0)
	s_setprio 1
	s_barrier
	v_mfma_f32_16x16x32_bf16 v[124:127], v[154:157], v[186:189], 0
	v_mfma_f32_16x16x32_bf16 v[116:119], v[162:165], v[186:189], 0
	v_mfma_f32_16x16x32_bf16 v[108:111], v[154:157], v[194:197], 0
	v_mfma_f32_16x16x32_bf16 v[100:103], v[162:165], v[194:197], 0
	v_mfma_f32_16x16x32_bf16 v[92:95], v[154:157], v[202:205], 0
	v_mfma_f32_16x16x32_bf16 v[84:87], v[162:165], v[202:205], 0
	v_mfma_f32_16x16x32_bf16 v[76:79], v[154:157], v[210:213], 0
	v_mfma_f32_16x16x32_bf16 v[68:71], v[162:165], v[210:213], 0
	v_mfma_f32_16x16x32_bf16 v[124:127], v[158:161], v[190:193], v[124:127]
	v_mfma_f32_16x16x32_bf16 v[116:119], v[166:169], v[190:193], v[116:119]
	v_mfma_f32_16x16x32_bf16 v[108:111], v[158:161], v[198:201], v[108:111]
	v_mfma_f32_16x16x32_bf16 v[100:103], v[166:169], v[198:201], v[100:103]
	v_mfma_f32_16x16x32_bf16 v[92:95], v[158:161], v[206:209], v[92:95]
	v_mfma_f32_16x16x32_bf16 v[84:87], v[166:169], v[206:209], v[84:87]
	v_mfma_f32_16x16x32_bf16 v[76:79], v[158:161], v[214:217], v[76:79]
	v_mfma_f32_16x16x32_bf16 v[68:71], v[166:169], v[214:217], v[68:71]
	s_setprio 0
	s_setprio 1
	v_mfma_f32_16x16x32_bf16 v[120:123], v[170:173], v[186:189], 0
	v_mfma_f32_16x16x32_bf16 v[112:115], v[178:181], v[186:189], 0
	v_mfma_f32_16x16x32_bf16 v[104:107], v[170:173], v[194:197], 0
	v_mfma_f32_16x16x32_bf16 v[96:99], v[178:181], v[194:197], 0
	v_mfma_f32_16x16x32_bf16 v[88:91], v[170:173], v[202:205], 0
	v_mfma_f32_16x16x32_bf16 v[80:83], v[178:181], v[202:205], 0
	v_mfma_f32_16x16x32_bf16 v[72:75], v[170:173], v[210:213], 0
	v_mfma_f32_16x16x32_bf16 v[64:67], v[178:181], v[210:213], 0
	v_mfma_f32_16x16x32_bf16 v[120:123], v[174:177], v[190:193], v[120:123]
	v_mfma_f32_16x16x32_bf16 v[112:115], v[182:185], v[190:193], v[112:115]
	v_mfma_f32_16x16x32_bf16 v[104:107], v[174:177], v[198:201], v[104:107]
	v_mfma_f32_16x16x32_bf16 v[96:99], v[182:185], v[198:201], v[96:99]
	v_mfma_f32_16x16x32_bf16 v[88:91], v[174:177], v[206:209], v[88:91]
	v_mfma_f32_16x16x32_bf16 v[80:83], v[182:185], v[206:209], v[80:83]
	v_mfma_f32_16x16x32_bf16 v[72:75], v[174:177], v[214:217], v[72:75]
	v_mfma_f32_16x16x32_bf16 v[64:67], v[182:185], v[214:217], v[64:67]
	s_barrier
	s_setprio 0
	s_add_i32 s50, s38, s26
	v_lshl_add_u64 v[218:219], s[22:23], 0, v[132:133]
	s_mov_b32 m0, s50
	ds_read_b128 v[186:189], v150 offset:16384
	ds_read_b128 v[190:193], v150 offset:17408
	global_load_lds_dwordx4 v[218:219], off
	s_add_i32 m0, s50, 0x2000
	s_add_u32 s50, s22, 0x40000
	v_lshl_add_u64 v[220:221], s[22:23], 0, v[128:129]
	s_addc_u32 s51, s23, 0
	s_add_i32 s52, s39, s26
	ds_read_b128 v[194:197], v150 offset:18432
	ds_read_b128 v[198:201], v150 offset:19456
	global_load_lds_dwordx4 v[220:221], off
	v_lshl_add_u64 v[222:223], s[50:51], 0, v[132:133]
	s_mov_b32 m0, s52
	v_lshl_add_u64 v[224:225], s[24:25], 0, v[130:131]
	ds_read_b128 v[202:205], v150 offset:20480
	global_load_lds_dwordx4 v[222:223], off
	v_lshl_add_u64 v[222:223], s[50:51], 0, v[128:129]
	s_add_i32 m0, s52, 0x2000
	ds_read_b128 v[206:209], v150 offset:21504
	global_load_lds_dwordx4 v[222:223], off
	v_lshl_add_u64 v[222:223], s[24:25], 0, v[134:135]
	s_mov_b32 m0, s19
	ds_read_b128 v[210:213], v150 offset:22528
	global_load_lds_dwordx4 v[222:223], off
	s_mov_b32 m0, s33
	ds_read_b128 v[214:217], v150 offset:23552
	global_load_lds_dwordx4 v[224:225], off
	s_cmp_eq_u32 s101, 1
	s_cbranch_scc1 .Lpk1613_r2
	s_waitcnt vmcnt(8)
	s_branch .Lpk1613_j2

.LBB0_1613:
	ds_read_b128 v[154:157], v148
	ds_read_b128 v[158:161], v148 offset:1024
	ds_read_b128 v[162:165], v148 offset:2048
	ds_read_b128 v[166:169], v148 offset:3072
	ds_read_b128 v[170:173], v149
	ds_read_b128 v[174:177], v149 offset:1024
	ds_read_b128 v[178:181], v149 offset:2048
	ds_read_b128 v[182:185], v149 offset:3072
	s_add_u32 s22, s20, 0xfffc0080
	s_addc_u32 s23, s21, -1
	s_cmp_eq_u32 s49, 12
	s_cselect_b32 s25, s13, s23
	s_cselect_b32 s24, s45, s22
	s_cselect_b32 s23, s11, s48
	s_cselect_b32 s22, s46, s47
	v_lshl_add_u64 v[218:219], s[20:21], 0, v[136:137]
	s_add_i32 m0, s19, 0xc000
	ds_read_b128 v[186:189], v150
	ds_read_b128 v[190:193], v150 offset:1024
	ds_read_b128 v[194:197], v150 offset:2048
	ds_read_b128 v[198:201], v150 offset:3072
	ds_read_b128 v[202:205], v150 offset:4096
	ds_read_b128 v[206:209], v150 offset:5120
	ds_read_b128 v[210:213], v150 offset:6144
	ds_read_b128 v[214:217], v150 offset:7168
	global_load_lds_dwordx4 v[218:219], off
	v_lshl_add_u64 v[218:219], s[20:21], 0, v[138:139]
	s_add_i32 m0, s19, 0xe000
	s_nop 0
	global_load_lds_dwordx4 v[218:219], off
	s_waitcnt vmcnt(8)
	s_waitcnt lgkmcnt(0)
	s_setprio 1
	s_barrier
	v_mfma_f32_16x16x32_bf16 v[124:127], v[154:157], v[186:189], v[124:127]
	v_mfma_f32_16x16x32_bf16 v[116:119], v[162:165], v[186:189], v[116:119]
	v_mfma_f32_16x16x32_bf16 v[108:111], v[154:157], v[194:197], v[108:111]
	v_mfma_f32_16x16x32_bf16 v[100:103], v[162:165], v[194:197], v[100:103]
	v_mfma_f32_16x16x32_bf16 v[92:95], v[154:157], v[202:205], v[92:95]
	v_mfma_f32_16x16x32_bf16 v[84:87], v[162:165], v[202:205], v[84:87]
	v_mfma_f32_16x16x32_bf16 v[76:79], v[154:157], v[210:213], v[76:79]
	v_mfma_f32_16x16x32_bf16 v[68:71], v[162:165], v[210:213], v[68:71]
	v_mfma_f32_16x16x32_bf16 v[124:127], v[158:161], v[190:193], v[124:127]
	v_mfma_f32_16x16x32_bf16 v[116:119], v[166:169], v[190:193], v[116:119]
	v_mfma_f32_16x16x32_bf16 v[108:111], v[158:161], v[198:201], v[108:111]
	v_mfma_f32_16x16x32_bf16 v[100:103], v[166:169], v[198:201], v[100:103]
	v_mfma_f32_16x16x32_bf16 v[92:95], v[158:161], v[206:209], v[92:95]
	v_mfma_f32_16x16x32_bf16 v[84:87], v[166:169], v[206:209], v[84:87]
	v_mfma_f32_16x16x32_bf16 v[76:79], v[158:161], v[214:217], v[76:79]
	v_mfma_f32_16x16x32_bf16 v[68:71], v[166:169], v[214:217], v[68:71]
	s_setprio 0
	s_setprio 1
	v_mfma_f32_16x16x32_bf16 v[120:123], v[170:173], v[186:189], v[120:123]
	v_mfma_f32_16x16x32_bf16 v[112:115], v[178:181], v[186:189], v[112:115]
	v_mfma_f32_16x16x32_bf16 v[104:107], v[170:173], v[194:197], v[104:107]
	v_mfma_f32_16x16x32_bf16 v[96:99], v[178:181], v[194:197], v[96:99]
	v_mfma_f32_16x16x32_bf16 v[88:91], v[170:173], v[202:205], v[88:91]
	v_mfma_f32_16x16x32_bf16 v[80:83], v[178:181], v[202:205], v[80:83]
	v_mfma_f32_16x16x32_bf16 v[72:75], v[170:173], v[210:213], v[72:75]
	v_mfma_f32_16x16x32_bf16 v[64:67], v[178:181], v[210:213], v[64:67]
	v_mfma_f32_16x16x32_bf16 v[120:123], v[174:177], v[190:193], v[120:123]
	v_mfma_f32_16x16x32_bf16 v[112:115], v[182:185], v[190:193], v[112:115]
	v_mfma_f32_16x16x32_bf16 v[104:107], v[174:177], v[198:201], v[104:107]
	v_mfma_f32_16x16x32_bf16 v[96:99], v[182:185], v[198:201], v[96:99]
	v_mfma_f32_16x16x32_bf16 v[88:91], v[174:177], v[206:209], v[88:91]
	v_mfma_f32_16x16x32_bf16 v[80:83], v[182:185], v[206:209], v[80:83]
	v_mfma_f32_16x16x32_bf16 v[72:75], v[174:177], v[214:217], v[72:75]
	v_mfma_f32_16x16x32_bf16 v[64:67], v[182:185], v[214:217], v[64:67]
	s_barrier
	s_setprio 0
	s_add_i32 s50, s38, s26
	v_lshl_add_u64 v[218:219], s[22:23], 0, v[132:133]
	s_mov_b32 m0, s50
	ds_read_b128 v[186:189], v150 offset:16384
	ds_read_b128 v[190:193], v150 offset:17408
	global_load_lds_dwordx4 v[218:219], off
	s_add_i32 m0, s50, 0x2000
	s_add_u32 s50, s22, 0x40000
	v_lshl_add_u64 v[220:221], s[22:23], 0, v[128:129]
	s_addc_u32 s51, s23, 0
	s_add_i32 s52, s39, s26
	ds_read_b128 v[194:197], v150 offset:18432
	ds_read_b128 v[198:201], v150 offset:19456
	global_load_lds_dwordx4 v[220:221], off
	v_lshl_add_u64 v[222:223], s[50:51], 0, v[132:133]
	s_mov_b32 m0, s52
	v_lshl_add_u64 v[224:225], s[24:25], 0, v[130:131]
	ds_read_b128 v[202:205], v150 offset:20480
	global_load_lds_dwordx4 v[222:223], off
	v_lshl_add_u64 v[222:223], s[50:51], 0, v[128:129]
	s_add_i32 m0, s52, 0x2000
	ds_read_b128 v[206:209], v150 offset:21504
	global_load_lds_dwordx4 v[222:223], off
	v_lshl_add_u64 v[222:223], s[24:25], 0, v[134:135]
	s_mov_b32 m0, s19
	ds_read_b128 v[210:213], v150 offset:22528
	global_load_lds_dwordx4 v[222:223], off
	s_mov_b32 m0, s33
	ds_read_b128 v[214:217], v150 offset:23552
	global_load_lds_dwordx4 v[224:225], off
	s_waitcnt vmcnt(8)
	s_waitcnt lgkmcnt(0)
	s_setprio 1
	s_barrier
	v_mfma_f32_16x16x32_bf16 v[60:63], v[154:157], v[186:189], v[60:63]
	v_mfma_f32_16x16x32_bf16 v[52:55], v[162:165], v[186:189], v[52:55]
	v_mfma_f32_16x16x32_bf16 v[44:47], v[154:157], v[194:197], v[44:47]
	v_mfma_f32_16x16x32_bf16 v[36:39], v[162:165], v[194:197], v[36:39]
	v_mfma_f32_16x16x32_bf16 v[28:31], v[154:157], v[202:205], v[28:31]
	v_mfma_f32_16x16x32_bf16 v[20:23], v[162:165], v[202:205], v[20:23]
	v_mfma_f32_16x16x32_bf16 v[12:15], v[154:157], v[210:213], v[12:15]
	v_mfma_f32_16x16x32_bf16 v[4:7], v[162:165], v[210:213], v[4:7]
	v_mfma_f32_16x16x32_bf16 v[60:63], v[158:161], v[190:193], v[60:63]
	v_mfma_f32_16x16x32_bf16 v[52:55], v[166:169], v[190:193], v[52:55]
	v_mfma_f32_16x16x32_bf16 v[44:47], v[158:161], v[198:201], v[44:47]
	v_mfma_f32_16x16x32_bf16 v[36:39], v[166:169], v[198:201], v[36:39]
	v_mfma_f32_16x16x32_bf16 v[28:31], v[158:161], v[206:209], v[28:31]
	v_mfma_f32_16x16x32_bf16 v[20:23], v[166:169], v[206:209], v[20:23]
	v_mfma_f32_16x16x32_bf16 v[12:15], v[158:161], v[214:217], v[12:15]
	v_mfma_f32_16x16x32_bf16 v[4:7], v[166:169], v[214:217], v[4:7]
	s_setprio 0
	s_setprio 1
	v_mfma_f32_16x16x32_bf16 v[56:59], v[170:173], v[186:189], v[56:59]
	v_mfma_f32_16x16x32_bf16 v[48:51], v[178:181], v[186:189], v[48:51]
	v_mfma_f32_16x16x32_bf16 v[40:43], v[170:173], v[194:197], v[40:43]
	v_mfma_f32_16x16x32_bf16 v[32:35], v[178:181], v[194:197], v[32:35]
	v_mfma_f32_16x16x32_bf16 v[24:27], v[170:173], v[202:205], v[24:27]
	v_mfma_f32_16x16x32_bf16 v[16:19], v[178:181], v[202:205], v[16:19]
	v_mfma_f32_16x16x32_bf16 v[8:11], v[170:173], v[210:213], v[8:11]
	v_mfma_f32_16x16x32_bf16 v[0:3], v[178:181], v[210:213], v[0:3]
	v_mfma_f32_16x16x32_bf16 v[56:59], v[174:177], v[190:193], v[56:59]
	v_mfma_f32_16x16x32_bf16 v[48:51], v[182:185], v[190:193], v[48:51]
	v_mfma_f32_16x16x32_bf16 v[40:43], v[174:177], v[198:201], v[40:43]
	v_mfma_f32_16x16x32_bf16 v[32:35], v[182:185], v[198:201], v[32:35]
	v_mfma_f32_16x16x32_bf16 v[24:27], v[174:177], v[206:209], v[24:27]
	v_mfma_f32_16x16x32_bf16 v[16:19], v[182:185], v[206:209], v[16:19]
	v_mfma_f32_16x16x32_bf16 v[8:11], v[174:177], v[214:217], v[8:11]
	v_mfma_f32_16x16x32_bf16 v[0:3], v[182:185], v[214:217], v[0:3]
	s_barrier
	s_setprio 0
.Lpk1613_seg3:
	s_add_i32 s50, 0, 0x18000
	v_add_u32_e32 v151, s50, v145
	s_add_i32 s51, 0, 0x1c000
	ds_read_b128 v[154:157], v151
	ds_read_b128 v[158:161], v151 offset:1024
	ds_read_b128 v[162:165], v151 offset:2048
	ds_read_b128 v[166:169], v151 offset:3072
	v_add_u32_e32 v151, s51, v145
	ds_read_b128 v[170:173], v151
	ds_read_b128 v[174:177], v151 offset:1024
	ds_read_b128 v[178:181], v151 offset:2048
	ds_read_b128 v[182:185], v151 offset:3072
	s_add_u32 s24, s24, 0x40000
	s_addc_u32 s25, s25, 0
	s_mov_b32 m0, s34
	v_lshl_add_u64 v[226:227], s[24:25], 0, v[134:135]
	ds_read_b128 v[186:189], v150 offset:32768
	ds_read_b128 v[190:193], v150 offset:33792
	ds_read_b128 v[194:197], v150 offset:34816
	ds_read_b128 v[198:201], v150 offset:35840
	ds_read_b128 v[202:205], v150 offset:36864
	ds_read_b128 v[206:209], v150 offset:37888
	ds_read_b128 v[210:213], v150 offset:38912
	ds_read_b128 v[214:217], v150 offset:39936
	global_load_lds_dwordx4 v[226:227], off
	v_lshl_add_u64 v[226:227], s[24:25], 0, v[130:131]
	s_mov_b32 m0, s35
	s_nop 0
	global_load_lds_dwordx4 v[226:227], off
	s_waitcnt vmcnt(8)
	s_waitcnt lgkmcnt(0)
	s_setprio 1
	s_barrier
	v_mfma_f32_16x16x32_bf16 v[124:127], v[154:157], v[186:189], v[124:127]
	v_mfma_f32_16x16x32_bf16 v[116:119], v[162:165], v[186:189], v[116:119]
	v_mfma_f32_16x16x32_bf16 v[108:111], v[154:157], v[194:197], v[108:111]
	v_mfma_f32_16x16x32_bf16 v[100:103], v[162:165], v[194:197], v[100:103]
	v_mfma_f32_16x16x32_bf16 v[92:95], v[154:157], v[202:205], v[92:95]
	v_mfma_f32_16x16x32_bf16 v[84:87], v[162:165], v[202:205], v[84:87]
	v_mfma_f32_16x16x32_bf16 v[76:79], v[154:157], v[210:213], v[76:79]
	v_mfma_f32_16x16x32_bf16 v[68:71], v[162:165], v[210:213], v[68:71]
	v_mfma_f32_16x16x32_bf16 v[124:127], v[158:161], v[190:193], v[124:127]
	v_mfma_f32_16x16x32_bf16 v[116:119], v[166:169], v[190:193], v[116:119]
	v_mfma_f32_16x16x32_bf16 v[108:111], v[158:161], v[198:201], v[108:111]
	v_mfma_f32_16x16x32_bf16 v[100:103], v[166:169], v[198:201], v[100:103]
	v_mfma_f32_16x16x32_bf16 v[92:95], v[158:161], v[206:209], v[92:95]
	v_mfma_f32_16x16x32_bf16 v[84:87], v[166:169], v[206:209], v[84:87]
	v_mfma_f32_16x16x32_bf16 v[76:79], v[158:161], v[214:217], v[76:79]
	v_mfma_f32_16x16x32_bf16 v[68:71], v[166:169], v[214:217], v[68:71]
	s_setprio 0
	s_setprio 1
	v_mfma_f32_16x16x32_bf16 v[120:123], v[170:173], v[186:189], v[120:123]
	v_mfma_f32_16x16x32_bf16 v[112:115], v[178:181], v[186:189], v[112:115]
	v_mfma_f32_16x16x32_bf16 v[104:107], v[170:173], v[194:197], v[104:107]
	v_mfma_f32_16x16x32_bf16 v[96:99], v[178:181], v[194:197], v[96:99]
	v_mfma_f32_16x16x32_bf16 v[88:91], v[170:173], v[202:205], v[88:91]
	v_mfma_f32_16x16x32_bf16 v[80:83], v[178:181], v[202:205], v[80:83]
	v_mfma_f32_16x16x32_bf16 v[72:75], v[170:173], v[210:213], v[72:75]
	v_mfma_f32_16x16x32_bf16 v[64:67], v[178:181], v[210:213], v[64:67]
	v_mfma_f32_16x16x32_bf16 v[120:123], v[174:177], v[190:193], v[120:123]
	v_mfma_f32_16x16x32_bf16 v[112:115], v[182:185], v[190:193], v[112:115]
	v_mfma_f32_16x16x32_bf16 v[104:107], v[174:177], v[198:201], v[104:107]
	v_mfma_f32_16x16x32_bf16 v[96:99], v[182:185], v[198:201], v[96:99]
	v_mfma_f32_16x16x32_bf16 v[88:91], v[174:177], v[206:209], v[88:91]
	v_mfma_f32_16x16x32_bf16 v[80:83], v[182:185], v[206:209], v[80:83]
	v_mfma_f32_16x16x32_bf16 v[72:75], v[174:177], v[214:217], v[72:75]
	v_mfma_f32_16x16x32_bf16 v[64:67], v[182:185], v[214:217], v[64:67]
	s_barrier
	s_setprio 0
	s_add_i32 s24, s50, s26
	v_lshl_add_u64 v[218:219], v[218:219], 0, s[6:7]
	s_mov_b32 m0, s24
	ds_read_b128 v[186:189], v150 offset:49152
	ds_read_b128 v[190:193], v150 offset:50176
	global_load_lds_dwordx4 v[218:219], off
	s_add_i32 m0, s24, 0x2000
	s_add_u32 s22, s22, 0x40080
	v_lshl_add_u64 v[218:219], v[220:221], 0, s[6:7]
	s_addc_u32 s23, s23, 0
	s_add_i32 s24, s51, s26
	ds_read_b128 v[194:197], v150 offset:51200
	ds_read_b128 v[198:201], v150 offset:52224
	global_load_lds_dwordx4 v[218:219], off
	v_lshl_add_u64 v[218:219], s[22:23], 0, v[132:133]
	s_mov_b32 m0, s24
	ds_read_b128 v[202:205], v150 offset:53248
	global_load_lds_dwordx4 v[218:219], off
	v_lshl_add_u64 v[218:219], s[22:23], 0, v[128:129]
	s_add_i32 m0, s24, 0x2000
	ds_read_b128 v[206:209], v150 offset:54272
	global_load_lds_dwordx4 v[218:219], off
	v_lshl_add_u64 v[218:219], v[222:223], 0, s[6:7]
	s_mov_b32 m0, s36
	ds_read_b128 v[210:213], v150 offset:55296
	global_load_lds_dwordx4 v[218:219], off
	v_lshl_add_u64 v[218:219], v[224:225], 0, s[6:7]
	s_mov_b32 m0, s37
	ds_read_b128 v[214:217], v150 offset:56320
	global_load_lds_dwordx4 v[218:219], off
	s_waitcnt vmcnt(8)
	s_waitcnt lgkmcnt(0)
	s_setprio 1
	s_barrier
	v_mfma_f32_16x16x32_bf16 v[60:63], v[154:157], v[186:189], v[60:63]
	v_mfma_f32_16x16x32_bf16 v[52:55], v[162:165], v[186:189], v[52:55]
	v_mfma_f32_16x16x32_bf16 v[44:47], v[154:157], v[194:197], v[44:47]
	v_mfma_f32_16x16x32_bf16 v[36:39], v[162:165], v[194:197], v[36:39]
	v_mfma_f32_16x16x32_bf16 v[28:31], v[154:157], v[202:205], v[28:31]
	v_mfma_f32_16x16x32_bf16 v[20:23], v[162:165], v[202:205], v[20:23]
	v_mfma_f32_16x16x32_bf16 v[12:15], v[154:157], v[210:213], v[12:15]
	v_mfma_f32_16x16x32_bf16 v[4:7], v[162:165], v[210:213], v[4:7]
	v_mfma_f32_16x16x32_bf16 v[60:63], v[158:161], v[190:193], v[60:63]
	v_mfma_f32_16x16x32_bf16 v[52:55], v[166:169], v[190:193], v[52:55]
	v_mfma_f32_16x16x32_bf16 v[44:47], v[158:161], v[198:201], v[44:47]
	v_mfma_f32_16x16x32_bf16 v[36:39], v[166:169], v[198:201], v[36:39]
	v_mfma_f32_16x16x32_bf16 v[28:31], v[158:161], v[206:209], v[28:31]
	v_mfma_f32_16x16x32_bf16 v[20:23], v[166:169], v[206:209], v[20:23]
	v_mfma_f32_16x16x32_bf16 v[12:15], v[158:161], v[214:217], v[12:15]
	v_mfma_f32_16x16x32_bf16 v[4:7], v[166:169], v[214:217], v[4:7]
	s_setprio 0
	s_setprio 1
	v_mfma_f32_16x16x32_bf16 v[56:59], v[170:173], v[186:189], v[56:59]
	v_mfma_f32_16x16x32_bf16 v[48:51], v[178:181], v[186:189], v[48:51]
	v_mfma_f32_16x16x32_bf16 v[40:43], v[170:173], v[194:197], v[40:43]
	v_mfma_f32_16x16x32_bf16 v[32:35], v[178:181], v[194:197], v[32:35]
	v_mfma_f32_16x16x32_bf16 v[24:27], v[170:173], v[202:205], v[24:27]
	v_mfma_f32_16x16x32_bf16 v[16:19], v[178:181], v[202:205], v[16:19]
	v_mfma_f32_16x16x32_bf16 v[8:11], v[170:173], v[210:213], v[8:11]
	v_mfma_f32_16x16x32_bf16 v[0:3], v[178:181], v[210:213], v[0:3]
	v_mfma_f32_16x16x32_bf16 v[56:59], v[174:177], v[190:193], v[56:59]
	v_mfma_f32_16x16x32_bf16 v[48:51], v[182:185], v[190:193], v[48:51]
	v_mfma_f32_16x16x32_bf16 v[40:43], v[174:177], v[198:201], v[40:43]
	v_mfma_f32_16x16x32_bf16 v[32:35], v[182:185], v[198:201], v[32:35]
	v_mfma_f32_16x16x32_bf16 v[24:27], v[174:177], v[206:209], v[24:27]
	v_mfma_f32_16x16x32_bf16 v[16:19], v[182:185], v[206:209], v[16:19]
	v_mfma_f32_16x16x32_bf16 v[8:11], v[174:177], v[214:217], v[8:11]
	v_mfma_f32_16x16x32_bf16 v[0:3], v[182:185], v[214:217], v[0:3]
	s_barrier
	s_setprio 0
	s_add_i32 s49, s49, 2
	s_add_u32 s20, s20, 0x100
	s_addc_u32 s21, s21, 0
	s_add_u32 s47, s47, 0x100
	s_addc_u32 s48, s48, 0
	s_cmp_gt_u32 s49, 13
	s_cbranch_scc0 .LBB0_1613
	s_and_b64 vcc, exec, s[8:9]
	s_cbranch_vccz .LBB0_1616
	s_barrier

.Lpk1722_j1:
	s_waitcnt lgkmcnt(0)
	s_setprio 1
	s_barrier
	v_mfma_f32_16x16x32_bf16 v[124:127], v[128:131], v[176:179], 0
	v_mfma_f32_16x16x32_bf16 v[120:123], v[136:139], v[176:179], 0
	v_mfma_f32_16x16x32_bf16 v[108:111], v[128:131], v[184:187], 0
	v_mfma_f32_16x16x32_bf16 v[104:107], v[136:139], v[184:187], 0
	v_mfma_f32_16x16x32_bf16 v[92:95], v[128:131], v[192:195], 0
	v_mfma_f32_16x16x32_bf16 v[88:91], v[136:139], v[192:195], 0
	v_mfma_f32_16x16x32_bf16 v[76:79], v[128:131], v[208:211], 0
	v_mfma_f32_16x16x32_bf16 v[72:75], v[136:139], v[208:211], 0
	v_mfma_f32_16x16x32_bf16 v[124:127], v[132:135], v[180:183], v[124:127]
	v_mfma_f32_16x16x32_bf16 v[120:123], v[140:143], v[180:183], v[120:123]
	v_mfma_f32_16x16x32_bf16 v[108:111], v[132:135], v[188:191], v[108:111]
	v_mfma_f32_16x16x32_bf16 v[104:107], v[140:143], v[188:191], v[104:107]
	v_mfma_f32_16x16x32_bf16 v[92:95], v[132:135], v[204:207], v[92:95]
	v_mfma_f32_16x16x32_bf16 v[88:91], v[140:143], v[204:207], v[88:91]
	v_mfma_f32_16x16x32_bf16 v[76:79], v[132:135], v[212:215], v[76:79]
	v_mfma_f32_16x16x32_bf16 v[72:75], v[140:143], v[212:215], v[72:75]
	s_setprio 0
	s_setprio 1
	v_mfma_f32_16x16x32_bf16 v[116:119], v[144:147], v[176:179], 0
	v_mfma_f32_16x16x32_bf16 v[112:115], v[168:171], v[176:179], 0
	v_mfma_f32_16x16x32_bf16 v[100:103], v[144:147], v[184:187], 0
	v_mfma_f32_16x16x32_bf16 v[96:99], v[168:171], v[184:187], 0
	v_mfma_f32_16x16x32_bf16 v[84:87], v[144:147], v[192:195], 0
	v_mfma_f32_16x16x32_bf16 v[80:83], v[168:171], v[192:195], 0
	v_mfma_f32_16x16x32_bf16 v[68:71], v[144:147], v[208:211], 0
	v_mfma_f32_16x16x32_bf16 v[64:67], v[168:171], v[208:211], 0
	v_mfma_f32_16x16x32_bf16 v[116:119], v[148:151], v[180:183], v[116:119]
	v_mfma_f32_16x16x32_bf16 v[112:115], v[172:175], v[180:183], v[112:115]
	v_mfma_f32_16x16x32_bf16 v[100:103], v[148:151], v[188:191], v[100:103]
	v_mfma_f32_16x16x32_bf16 v[96:99], v[172:175], v[188:191], v[96:99]
	v_mfma_f32_16x16x32_bf16 v[84:87], v[148:151], v[204:207], v[84:87]
	v_mfma_f32_16x16x32_bf16 v[80:83], v[172:175], v[204:207], v[80:83]
	v_mfma_f32_16x16x32_bf16 v[68:71], v[148:151], v[212:215], v[68:71]
	v_mfma_f32_16x16x32_bf16 v[64:67], v[172:175], v[212:215], v[64:67]
	s_barrier
	s_setprio 0
	s_add_i32 s51, s41, s28
	v_lshl_add_u64 v[216:217], s[22:23], 0, v[156:157]
	s_mov_b32 m0, s51
	ds_read_b128 v[176:179], v201 offset:16384
	ds_read_b128 v[180:183], v201 offset:17408
	global_load_lds_dwordx4 v[216:217], off
	s_add_i32 m0, s51, 0x2000
	s_add_u32 s52, s22, 0xb0000
	v_lshl_add_u64 v[218:219], s[22:23], 0, v[160:161]
	s_addc_u32 s53, s23, 0
	s_add_i32 s51, s42, s28
	ds_read_b128 v[184:187], v201 offset:18432
	ds_read_b128 v[188:191], v201 offset:19456
	global_load_lds_dwordx4 v[218:219], off
	v_lshl_add_u64 v[220:221], s[52:53], 0, v[156:157]
	s_mov_b32 m0, s51
	v_lshl_add_u64 v[222:223], s[24:25], 0, v[158:159]
	ds_read_b128 v[192:195], v201 offset:20480
	global_load_lds_dwordx4 v[220:221], off
	v_lshl_add_u64 v[220:221], s[52:53], 0, v[160:161]
	s_add_i32 m0, s51, 0x2000
	ds_read_b128 v[204:207], v201 offset:21504
	global_load_lds_dwordx4 v[220:221], off
	v_lshl_add_u64 v[220:221], s[24:25], 0, v[154:155]
	s_mov_b32 m0, s29
	ds_read_b128 v[208:211], v201 offset:22528
	global_load_lds_dwordx4 v[220:221], off
	s_mov_b32 m0, s30
	ds_read_b128 v[212:215], v201 offset:23552
	global_load_lds_dwordx4 v[222:223], off
	s_cmp_eq_u32 s101, 1
	s_cbranch_scc1 .Lpk1722_r2
	s_waitcnt vmcnt(8)
	s_branch .Lpk1722_j2

.Lpk1722_j2:
	s_mov_b32 s101, 0
	s_waitcnt lgkmcnt(0)
	s_setprio 1
	s_barrier
	v_mfma_f32_16x16x32_bf16 v[60:63], v[128:131], v[176:179], 0
	v_mfma_f32_16x16x32_bf16 v[56:59], v[136:139], v[176:179], 0
	v_mfma_f32_16x16x32_bf16 v[44:47], v[128:131], v[184:187], 0
	v_mfma_f32_16x16x32_bf16 v[40:43], v[136:139], v[184:187], 0
	v_mfma_f32_16x16x32_bf16 v[28:31], v[128:131], v[192:195], 0
	v_mfma_f32_16x16x32_bf16 v[24:27], v[136:139], v[192:195], 0
	v_mfma_f32_16x16x32_bf16 v[12:15], v[128:131], v[208:211], 0
	v_mfma_f32_16x16x32_bf16 v[8:11], v[136:139], v[208:211], 0
	v_mfma_f32_16x16x32_bf16 v[60:63], v[132:135], v[180:183], v[60:63]
	v_mfma_f32_16x16x32_bf16 v[56:59], v[140:143], v[180:183], v[56:59]
	v_mfma_f32_16x16x32_bf16 v[44:47], v[132:135], v[188:191], v[44:47]
	v_mfma_f32_16x16x32_bf16 v[40:43], v[140:143], v[188:191], v[40:43]
	v_mfma_f32_16x16x32_bf16 v[28:31], v[132:135], v[204:207], v[28:31]
	v_mfma_f32_16x16x32_bf16 v[24:27], v[140:143], v[204:207], v[24:27]
	v_mfma_f32_16x16x32_bf16 v[12:15], v[132:135], v[212:215], v[12:15]
	v_mfma_f32_16x16x32_bf16 v[8:11], v[140:143], v[212:215], v[8:11]
	s_setprio 0
	s_setprio 1
	v_mfma_f32_16x16x32_bf16 v[52:55], v[144:147], v[176:179], 0
	v_mfma_f32_16x16x32_bf16 v[48:51], v[168:171], v[176:179], 0
	v_mfma_f32_16x16x32_bf16 v[36:39], v[144:147], v[184:187], 0
	v_mfma_f32_16x16x32_bf16 v[32:35], v[168:171], v[184:187], 0
	v_mfma_f32_16x16x32_bf16 v[20:23], v[144:147], v[192:195], 0
	v_mfma_f32_16x16x32_bf16 v[16:19], v[168:171], v[192:195], 0
	v_mfma_f32_16x16x32_bf16 v[4:7], v[144:147], v[208:211], 0
	v_mfma_f32_16x16x32_bf16 v[0:3], v[168:171], v[208:211], 0
	v_mfma_f32_16x16x32_bf16 v[52:55], v[148:151], v[180:183], v[52:55]
	v_mfma_f32_16x16x32_bf16 v[48:51], v[172:175], v[180:183], v[48:51]
	v_mfma_f32_16x16x32_bf16 v[36:39], v[148:151], v[188:191], v[36:39]
	v_mfma_f32_16x16x32_bf16 v[32:35], v[172:175], v[188:191], v[32:35]
	v_mfma_f32_16x16x32_bf16 v[20:23], v[148:151], v[204:207], v[20:23]
	v_mfma_f32_16x16x32_bf16 v[16:19], v[172:175], v[204:207], v[16:19]
	v_mfma_f32_16x16x32_bf16 v[4:7], v[148:151], v[212:215], v[4:7]
	v_mfma_f32_16x16x32_bf16 v[0:3], v[172:175], v[212:215], v[0:3]
	s_barrier
	s_setprio 0
	s_branch .Lpk1722_seg3
.LBB0_1722:
	ds_read_b128 v[128:131], v199
	ds_read_b128 v[132:135], v199 offset:1024
	ds_read_b128 v[136:139], v199 offset:2048
	ds_read_b128 v[140:143], v199 offset:3072
	ds_read_b128 v[144:147], v200
	ds_read_b128 v[148:151], v200 offset:1024
	ds_read_b128 v[168:171], v200 offset:2048
	ds_read_b128 v[172:175], v200 offset:3072
	s_add_u32 s22, s6, 0xfff50080
	s_addc_u32 s23, s7, -1
	s_cmp_eq_u32 s50, 40
	s_cselect_b32 s25, s19, s23
	s_cselect_b32 s24, s18, s22
	s_cselect_b32 s23, s21, s49
	s_cselect_b32 s22, s20, s48
	v_lshl_add_u64 v[216:217], s[6:7], 0, v[152:153]
	s_add_i32 m0, s29, 0xc000
	ds_read_b128 v[176:179], v201
	ds_read_b128 v[180:183], v201 offset:1024
	ds_read_b128 v[184:187], v201 offset:2048
	ds_read_b128 v[188:191], v201 offset:3072
	ds_read_b128 v[192:195], v201 offset:4096
	ds_read_b128 v[204:207], v201 offset:5120
	ds_read_b128 v[208:211], v201 offset:6144
	ds_read_b128 v[212:215], v201 offset:7168
	global_load_lds_dwordx4 v[216:217], off
	v_lshl_add_u64 v[216:217], s[6:7], 0, v[162:163]
	s_add_i32 m0, s29, 0xe000
	s_nop 0
	global_load_lds_dwordx4 v[216:217], off
	s_waitcnt vmcnt(8)
	s_waitcnt lgkmcnt(0)
	s_setprio 1
	s_barrier
	v_mfma_f32_16x16x32_bf16 v[124:127], v[128:131], v[176:179], v[124:127]
	v_mfma_f32_16x16x32_bf16 v[120:123], v[136:139], v[176:179], v[120:123]
	v_mfma_f32_16x16x32_bf16 v[108:111], v[128:131], v[184:187], v[108:111]
	v_mfma_f32_16x16x32_bf16 v[104:107], v[136:139], v[184:187], v[104:107]
	v_mfma_f32_16x16x32_bf16 v[92:95], v[128:131], v[192:195], v[92:95]
	v_mfma_f32_16x16x32_bf16 v[88:91], v[136:139], v[192:195], v[88:91]
	v_mfma_f32_16x16x32_bf16 v[76:79], v[128:131], v[208:211], v[76:79]
	v_mfma_f32_16x16x32_bf16 v[72:75], v[136:139], v[208:211], v[72:75]
	v_mfma_f32_16x16x32_bf16 v[124:127], v[132:135], v[180:183], v[124:127]
	v_mfma_f32_16x16x32_bf16 v[120:123], v[140:143], v[180:183], v[120:123]
	v_mfma_f32_16x16x32_bf16 v[108:111], v[132:135], v[188:191], v[108:111]
	v_mfma_f32_16x16x32_bf16 v[104:107], v[140:143], v[188:191], v[104:107]
	v_mfma_f32_16x16x32_bf16 v[92:95], v[132:135], v[204:207], v[92:95]
	v_mfma_f32_16x16x32_bf16 v[88:91], v[140:143], v[204:207], v[88:91]
	v_mfma_f32_16x16x32_bf16 v[76:79], v[132:135], v[212:215], v[76:79]
	v_mfma_f32_16x16x32_bf16 v[72:75], v[140:143], v[212:215], v[72:75]
	s_setprio 0
	s_setprio 1
	v_mfma_f32_16x16x32_bf16 v[116:119], v[144:147], v[176:179], v[116:119]
	v_mfma_f32_16x16x32_bf16 v[112:115], v[168:171], v[176:179], v[112:115]
	v_mfma_f32_16x16x32_bf16 v[100:103], v[144:147], v[184:187], v[100:103]
	v_mfma_f32_16x16x32_bf16 v[96:99], v[168:171], v[184:187], v[96:99]
	v_mfma_f32_16x16x32_bf16 v[84:87], v[144:147], v[192:195], v[84:87]
	v_mfma_f32_16x16x32_bf16 v[80:83], v[168:171], v[192:195], v[80:83]
	v_mfma_f32_16x16x32_bf16 v[68:71], v[144:147], v[208:211], v[68:71]
	v_mfma_f32_16x16x32_bf16 v[64:67], v[168:171], v[208:211], v[64:67]
	v_mfma_f32_16x16x32_bf16 v[116:119], v[148:151], v[180:183], v[116:119]
	v_mfma_f32_16x16x32_bf16 v[112:115], v[172:175], v[180:183], v[112:115]
	v_mfma_f32_16x16x32_bf16 v[100:103], v[148:151], v[188:191], v[100:103]
	v_mfma_f32_16x16x32_bf16 v[96:99], v[172:175], v[188:191], v[96:99]
	v_mfma_f32_16x16x32_bf16 v[84:87], v[148:151], v[204:207], v[84:87]
	v_mfma_f32_16x16x32_bf16 v[80:83], v[172:175], v[204:207], v[80:83]
	v_mfma_f32_16x16x32_bf16 v[68:71], v[148:151], v[212:215], v[68:71]
	v_mfma_f32_16x16x32_bf16 v[64:67], v[172:175], v[212:215], v[64:67]
	s_barrier
	s_setprio 0
	s_add_i32 s51, s41, s28
	v_lshl_add_u64 v[216:217], s[22:23], 0, v[156:157]
	s_mov_b32 m0, s51
	ds_read_b128 v[176:179], v201 offset:16384
	ds_read_b128 v[180:183], v201 offset:17408
	global_load_lds_dwordx4 v[216:217], off
	s_add_i32 m0, s51, 0x2000
	s_add_u32 s52, s22, 0xb0000
	v_lshl_add_u64 v[218:219], s[22:23], 0, v[160:161]
	s_addc_u32 s53, s23, 0
	s_add_i32 s51, s42, s28
	ds_read_b128 v[184:187], v201 offset:18432
	ds_read_b128 v[188:191], v201 offset:19456
	global_load_lds_dwordx4 v[218:219], off
	v_lshl_add_u64 v[220:221], s[52:53], 0, v[156:157]
	s_mov_b32 m0, s51
	v_lshl_add_u64 v[222:223], s[24:25], 0, v[158:159]
	ds_read_b128 v[192:195], v201 offset:20480
	global_load_lds_dwordx4 v[220:221], off
	v_lshl_add_u64 v[220:221], s[52:53], 0, v[160:161]
	s_add_i32 m0, s51, 0x2000
	ds_read_b128 v[204:207], v201 offset:21504
	global_load_lds_dwordx4 v[220:221], off
	v_lshl_add_u64 v[220:221], s[24:25], 0, v[154:155]
	s_mov_b32 m0, s29
	ds_read_b128 v[208:211], v201 offset:22528
	global_load_lds_dwordx4 v[220:221], off
	s_mov_b32 m0, s30
	ds_read_b128 v[212:215], v201 offset:23552
	global_load_lds_dwordx4 v[222:223], off
	s_waitcnt vmcnt(8)
	s_waitcnt lgkmcnt(0)
	s_setprio 1
	s_barrier
	v_mfma_f32_16x16x32_bf16 v[60:63], v[128:131], v[176:179], v[60:63]
	v_mfma_f32_16x16x32_bf16 v[56:59], v[136:139], v[176:179], v[56:59]
	v_mfma_f32_16x16x32_bf16 v[44:47], v[128:131], v[184:187], v[44:47]
	v_mfma_f32_16x16x32_bf16 v[40:43], v[136:139], v[184:187], v[40:43]
	v_mfma_f32_16x16x32_bf16 v[28:31], v[128:131], v[192:195], v[28:31]
	v_mfma_f32_16x16x32_bf16 v[24:27], v[136:139], v[192:195], v[24:27]
	v_mfma_f32_16x16x32_bf16 v[12:15], v[128:131], v[208:211], v[12:15]
	v_mfma_f32_16x16x32_bf16 v[8:11], v[136:139], v[208:211], v[8:11]
	v_mfma_f32_16x16x32_bf16 v[60:63], v[132:135], v[180:183], v[60:63]
	v_mfma_f32_16x16x32_bf16 v[56:59], v[140:143], v[180:183], v[56:59]
	v_mfma_f32_16x16x32_bf16 v[44:47], v[132:135], v[188:191], v[44:47]
	v_mfma_f32_16x16x32_bf16 v[40:43], v[140:143], v[188:191], v[40:43]
	v_mfma_f32_16x16x32_bf16 v[28:31], v[132:135], v[204:207], v[28:31]
	v_mfma_f32_16x16x32_bf16 v[24:27], v[140:143], v[204:207], v[24:27]
	v_mfma_f32_16x16x32_bf16 v[12:15], v[132:135], v[212:215], v[12:15]
	v_mfma_f32_16x16x32_bf16 v[8:11], v[140:143], v[212:215], v[8:11]
	s_setprio 0
	s_setprio 1
	v_mfma_f32_16x16x32_bf16 v[52:55], v[144:147], v[176:179], v[52:55]
	v_mfma_f32_16x16x32_bf16 v[48:51], v[168:171], v[176:179], v[48:51]
	v_mfma_f32_16x16x32_bf16 v[36:39], v[144:147], v[184:187], v[36:39]
	v_mfma_f32_16x16x32_bf16 v[32:35], v[168:171], v[184:187], v[32:35]
	v_mfma_f32_16x16x32_bf16 v[20:23], v[144:147], v[192:195], v[20:23]
	v_mfma_f32_16x16x32_bf16 v[16:19], v[168:171], v[192:195], v[16:19]
	v_mfma_f32_16x16x32_bf16 v[4:7], v[144:147], v[208:211], v[4:7]
	v_mfma_f32_16x16x32_bf16 v[0:3], v[168:171], v[208:211], v[0:3]
	v_mfma_f32_16x16x32_bf16 v[52:55], v[148:151], v[180:183], v[52:55]
	v_mfma_f32_16x16x32_bf16 v[48:51], v[172:175], v[180:183], v[48:51]
	v_mfma_f32_16x16x32_bf16 v[36:39], v[148:151], v[188:191], v[36:39]
	v_mfma_f32_16x16x32_bf16 v[32:35], v[172:175], v[188:191], v[32:35]
	v_mfma_f32_16x16x32_bf16 v[20:23], v[148:151], v[204:207], v[20:23]
	v_mfma_f32_16x16x32_bf16 v[16:19], v[172:175], v[204:207], v[16:19]
	v_mfma_f32_16x16x32_bf16 v[4:7], v[148:151], v[212:215], v[4:7]
	v_mfma_f32_16x16x32_bf16 v[0:3], v[172:175], v[212:215], v[0:3]
	s_barrier
	s_setprio 0
.Lpk1722_seg3:
	s_add_i32 s51, 0, 0x18000
	s_add_i32 s52, 0, 0x1c000
	v_add_u32_e32 v140, s51, v197
	v_add_u32_e32 v172, s52, v197
	ds_read_b128 v[128:131], v140
	ds_read_b128 v[132:135], v140 offset:1024
	ds_read_b128 v[136:139], v140 offset:2048
	ds_read_b128 v[140:143], v140 offset:3072
	ds_read_b128 v[144:147], v172
	ds_read_b128 v[148:151], v172 offset:1024
	ds_read_b128 v[168:171], v172 offset:2048
	ds_read_b128 v[172:175], v172 offset:3072
	s_add_u32 s24, s24, 0xb0000
	s_addc_u32 s25, s25, 0
	s_mov_b32 m0, s31
	v_lshl_add_u64 v[224:225], s[24:25], 0, v[154:155]
	ds_read_b128 v[176:179], v201 offset:32768
	ds_read_b128 v[180:183], v201 offset:33792
	ds_read_b128 v[184:187], v201 offset:34816
	ds_read_b128 v[188:191], v201 offset:35840
	ds_read_b128 v[192:195], v201 offset:36864
	ds_read_b128 v[204:207], v201 offset:37888
	ds_read_b128 v[208:211], v201 offset:38912
	ds_read_b128 v[212:215], v201 offset:39936
	global_load_lds_dwordx4 v[224:225], off
	v_lshl_add_u64 v[224:225], s[24:25], 0, v[158:159]
	s_mov_b32 m0, s33
	s_nop 0
	global_load_lds_dwordx4 v[224:225], off
	s_waitcnt vmcnt(8)
	s_waitcnt lgkmcnt(0)
	s_setprio 1
	s_barrier
	v_mfma_f32_16x16x32_bf16 v[124:127], v[128:131], v[176:179], v[124:127]
	v_mfma_f32_16x16x32_bf16 v[120:123], v[136:139], v[176:179], v[120:123]
	v_mfma_f32_16x16x32_bf16 v[108:111], v[128:131], v[184:187], v[108:111]
	v_mfma_f32_16x16x32_bf16 v[104:107], v[136:139], v[184:187], v[104:107]
	v_mfma_f32_16x16x32_bf16 v[92:95], v[128:131], v[192:195], v[92:95]
	v_mfma_f32_16x16x32_bf16 v[88:91], v[136:139], v[192:195], v[88:91]
	v_mfma_f32_16x16x32_bf16 v[76:79], v[128:131], v[208:211], v[76:79]
	v_mfma_f32_16x16x32_bf16 v[72:75], v[136:139], v[208:211], v[72:75]
	v_mfma_f32_16x16x32_bf16 v[124:127], v[132:135], v[180:183], v[124:127]
	v_mfma_f32_16x16x32_bf16 v[120:123], v[140:143], v[180:183], v[120:123]
	v_mfma_f32_16x16x32_bf16 v[108:111], v[132:135], v[188:191], v[108:111]
	v_mfma_f32_16x16x32_bf16 v[104:107], v[140:143], v[188:191], v[104:107]
	v_mfma_f32_16x16x32_bf16 v[92:95], v[132:135], v[204:207], v[92:95]
	v_mfma_f32_16x16x32_bf16 v[88:91], v[140:143], v[204:207], v[88:91]
	v_mfma_f32_16x16x32_bf16 v[76:79], v[132:135], v[212:215], v[76:79]
	v_mfma_f32_16x16x32_bf16 v[72:75], v[140:143], v[212:215], v[72:75]
	s_setprio 0
	s_setprio 1
	v_mfma_f32_16x16x32_bf16 v[116:119], v[144:147], v[176:179], v[116:119]
	v_mfma_f32_16x16x32_bf16 v[112:115], v[168:171], v[176:179], v[112:115]
	v_mfma_f32_16x16x32_bf16 v[100:103], v[144:147], v[184:187], v[100:103]
	v_mfma_f32_16x16x32_bf16 v[96:99], v[168:171], v[184:187], v[96:99]
	v_mfma_f32_16x16x32_bf16 v[84:87], v[144:147], v[192:195], v[84:87]
	v_mfma_f32_16x16x32_bf16 v[80:83], v[168:171], v[192:195], v[80:83]
	v_mfma_f32_16x16x32_bf16 v[68:71], v[144:147], v[208:211], v[68:71]
	v_mfma_f32_16x16x32_bf16 v[64:67], v[168:171], v[208:211], v[64:67]
	v_mfma_f32_16x16x32_bf16 v[116:119], v[148:151], v[180:183], v[116:119]
	v_mfma_f32_16x16x32_bf16 v[112:115], v[172:175], v[180:183], v[112:115]
	v_mfma_f32_16x16x32_bf16 v[100:103], v[148:151], v[188:191], v[100:103]
	v_mfma_f32_16x16x32_bf16 v[96:99], v[172:175], v[188:191], v[96:99]
	v_mfma_f32_16x16x32_bf16 v[84:87], v[148:151], v[204:207], v[84:87]
	v_mfma_f32_16x16x32_bf16 v[80:83], v[172:175], v[204:207], v[80:83]
	v_mfma_f32_16x16x32_bf16 v[68:71], v[148:151], v[212:215], v[68:71]
	v_mfma_f32_16x16x32_bf16 v[64:67], v[172:175], v[212:215], v[64:67]
	s_barrier
	s_setprio 0
	s_add_i32 s24, s51, s28
	v_lshl_add_u64 v[216:217], v[216:217], 0, s[14:15]
	s_mov_b32 m0, s24
	ds_read_b128 v[176:179], v201 offset:49152
	ds_read_b128 v[180:183], v201 offset:50176
	global_load_lds_dwordx4 v[216:217], off
	s_add_i32 m0, s24, 0x2000
	s_add_u32 s22, s22, 0xb0080
	v_lshl_add_u64 v[216:217], v[218:219], 0, s[14:15]
	s_addc_u32 s23, s23, 0
	s_add_i32 s24, s52, s28
	ds_read_b128 v[184:187], v201 offset:51200
	ds_read_b128 v[188:191], v201 offset:52224
	global_load_lds_dwordx4 v[216:217], off
	v_lshl_add_u64 v[216:217], s[22:23], 0, v[156:157]
	s_mov_b32 m0, s24
	ds_read_b128 v[192:195], v201 offset:53248
	global_load_lds_dwordx4 v[216:217], off
	v_lshl_add_u64 v[216:217], s[22:23], 0, v[160:161]
	s_add_i32 m0, s24, 0x2000
	ds_read_b128 v[204:207], v201 offset:54272
	global_load_lds_dwordx4 v[216:217], off
	v_lshl_add_u64 v[216:217], v[220:221], 0, s[14:15]
	s_mov_b32 m0, s37
	ds_read_b128 v[208:211], v201 offset:55296
	global_load_lds_dwordx4 v[216:217], off
	v_lshl_add_u64 v[216:217], v[222:223], 0, s[14:15]
	s_mov_b32 m0, s38
	ds_read_b128 v[212:215], v201 offset:56320
	global_load_lds_dwordx4 v[216:217], off
	s_waitcnt vmcnt(8)
	s_waitcnt lgkmcnt(0)
	s_setprio 1
	s_barrier
	v_mfma_f32_16x16x32_bf16 v[60:63], v[128:131], v[176:179], v[60:63]
	v_mfma_f32_16x16x32_bf16 v[56:59], v[136:139], v[176:179], v[56:59]
	v_mfma_f32_16x16x32_bf16 v[44:47], v[128:131], v[184:187], v[44:47]
	v_mfma_f32_16x16x32_bf16 v[40:43], v[136:139], v[184:187], v[40:43]
	v_mfma_f32_16x16x32_bf16 v[28:31], v[128:131], v[192:195], v[28:31]
	v_mfma_f32_16x16x32_bf16 v[24:27], v[136:139], v[192:195], v[24:27]
	v_mfma_f32_16x16x32_bf16 v[12:15], v[128:131], v[208:211], v[12:15]
	v_mfma_f32_16x16x32_bf16 v[8:11], v[136:139], v[208:211], v[8:11]
	v_mfma_f32_16x16x32_bf16 v[60:63], v[132:135], v[180:183], v[60:63]
	v_mfma_f32_16x16x32_bf16 v[56:59], v[140:143], v[180:183], v[56:59]
	v_mfma_f32_16x16x32_bf16 v[44:47], v[132:135], v[188:191], v[44:47]
	v_mfma_f32_16x16x32_bf16 v[40:43], v[140:143], v[188:191], v[40:43]
	v_mfma_f32_16x16x32_bf16 v[28:31], v[132:135], v[204:207], v[28:31]
	v_mfma_f32_16x16x32_bf16 v[24:27], v[140:143], v[204:207], v[24:27]
	v_mfma_f32_16x16x32_bf16 v[12:15], v[132:135], v[212:215], v[12:15]
	v_mfma_f32_16x16x32_bf16 v[8:11], v[140:143], v[212:215], v[8:11]
	s_setprio 0
	s_setprio 1
	v_mfma_f32_16x16x32_bf16 v[52:55], v[144:147], v[176:179], v[52:55]
	v_mfma_f32_16x16x32_bf16 v[48:51], v[168:171], v[176:179], v[48:51]
	v_mfma_f32_16x16x32_bf16 v[36:39], v[144:147], v[184:187], v[36:39]
	v_mfma_f32_16x16x32_bf16 v[32:35], v[168:171], v[184:187], v[32:35]
	v_mfma_f32_16x16x32_bf16 v[20:23], v[144:147], v[192:195], v[20:23]
	v_mfma_f32_16x16x32_bf16 v[16:19], v[168:171], v[192:195], v[16:19]
	v_mfma_f32_16x16x32_bf16 v[4:7], v[144:147], v[208:211], v[4:7]
	v_mfma_f32_16x16x32_bf16 v[0:3], v[168:171], v[208:211], v[0:3]
	v_mfma_f32_16x16x32_bf16 v[52:55], v[148:151], v[180:183], v[52:55]
	v_mfma_f32_16x16x32_bf16 v[48:51], v[172:175], v[180:183], v[48:51]
	v_mfma_f32_16x16x32_bf16 v[36:39], v[148:151], v[188:191], v[36:39]
	v_mfma_f32_16x16x32_bf16 v[32:35], v[172:175], v[188:191], v[32:35]
	v_mfma_f32_16x16x32_bf16 v[20:23], v[148:151], v[204:207], v[20:23]
	v_mfma_f32_16x16x32_bf16 v[16:19], v[172:175], v[204:207], v[16:19]
	v_mfma_f32_16x16x32_bf16 v[4:7], v[148:151], v[212:215], v[4:7]
	v_mfma_f32_16x16x32_bf16 v[0:3], v[172:175], v[212:215], v[0:3]
	s_barrier
	s_setprio 0
	s_add_i32 s50, s50, 2
	s_add_u32 s6, s6, 0x100
	s_addc_u32 s7, s7, 0
	s_add_u32 s48, s48, 0x100
	s_addc_u32 s49, s49, 0
	s_cmp_gt_u32 s50, 41
	s_cbranch_scc0 .LBB0_1722
	s_and_b64 vcc, exec, s[16:17]
	s_cbranch_vccz .LBB0_1725
	s_barrier
